# E1: all 7 GEMM K-loops: STAGE(SA(0,0)) moved from phase 2 to phase 3 (DMA 2-4-4-6), phase-2 vmcnt 8->6
# baseline (speedup 1.0000x reference)
; #define PG8_STAGE(bufoff, gbase, voff) do { _Pragma("unroll") for (int _i = 0; _i < 2; ++_i) \
;         __builtin_amdgcn_global_load_lds((const unsigned*)((const char*)(gbase) + (voff)[_i]), (PG8_LAS unsigned*)(lds + (bufoff) + ldsw + _i * 8192), 16, 0, 0); } while (0)
; #define PG8_LDA(dst, b, h) do { _Pragma("unroll") for (int m = 0; m < 4; ++m) _Pragma("unroll") for (int k = 0; k < 2; ++k) dst[m][k] = *(const PG8_LAS bf16x8*)(lds + PG8_SA(b, h) + aoff + m * 2048 + k * 1024); } while (0)
; #define PG8_LDB(dst, b, h) do { _Pragma("unroll") for (int n = 0; n < 2; ++n) _Pragma("unroll") for (int k = 0; k < 2; ++k) dst[n][k] = *(const PG8_LAS bf16x8*)(lds + PG8_SB(b, h) + boff + n * 2048 + k * 1024); } while (0)
; #define PG8_MMA(ai, bj, At, Bt) do { __builtin_amdgcn_s_setprio(3); _Pragma("unroll") for (int m = 0; m < 4; ++m) _Pragma("unroll") for (int n = 0; n < 2; ++n) _Pragma("unroll") for (int k = 0; k < 2; ++k) \
;         acc[ai][bj][m][n] = __builtin_amdgcn_mfma_f32_16x16x32_bf16(Bt[n][k], At[m][k], acc[ai][bj][m][n], 0, 0, 0); __builtin_amdgcn_s_setprio(0); } while (0)
; #define PG8_WAIT_V(n) asm volatile("s_waitcnt vmcnt(" #n ")" ::: "memory")
; #define PG8_WAIT_L(n) asm volatile("s_waitcnt lgkmcnt(" #n ")" ::: "memory")
; template <class Epi, class Sched, bool ALIGN_EPI = false, bool SP2 = false>
; __device__ __forceinline__ void gemm_phase(PG8_LAS unsigned char* lds, const Gemm g, const Sched& S, const Epi& E) {
;     ...
;         for (int t = 0; t < nt; t += 2) {
;             const bool last = (t == nt - 2);
;             const char* a1 = cA + (size_t)(t + 1) * kstep;
;             const char* a2 = last ? nA : cA + (size_t)(t + 2) * kstep; const char* b2 = last ? nB : cB + (size_t)(t + 2) * kstep;
;             const char* a3 = a2 + kstep; const char* b3 = b2 + kstep;
;             if (last && has_next) S.a_ready(nxt);
;             if constexpr (Epi::MIDK) { if (t == E.midk_step(nt)) E.midk(acc, cur, wr, wc, fr, fq); }
;             if constexpr (SP2) {
;             PG8_LDB(B0, 0, 0); PG8_LDB(B1, 0, 1); PG8_SCHED; PG8_LDA(At, 0, 0); PG8_STAGE(PG8_SA(1, 1), a1 + hstepA, voffA);
;             PG8_WAIT_V(8); PG8_WAIT_L(0); PG8_BAR; PG8_MMA(0, 0, At, B0); PG8_MMA(0, 1, At, B1); PG8_BAR; PG8_SCHED;
;             PG8_LDA(At, 0, 1); PG8_STAGE(PG8_SB(0, 0), b2, voffB); PG8_STAGE(PG8_SB(0, 1), b2 + hstepB, voffB); PG8_STAGE(PG8_SA(0, 0), a2, voffA);
.LBB0_143:
	ds_read_b128 v[130:133], v167
	ds_read_b128 v[134:137], v167 offset:1024
	ds_read_b128 v[156:159], v167 offset:2048
	ds_read_b128 v[172:175], v167 offset:3072
	ds_read_b128 v[176:179], v168
	ds_read_b128 v[180:183], v168 offset:1024
	ds_read_b128 v[184:187], v168 offset:2048
	ds_read_b128 v[188:191], v168 offset:3072
	s_add_u32 s8, s6, 0xfff00080
	s_addc_u32 s9, s7, -1
	s_cmp_eq_u32 s45, 60
	s_cselect_b32 s37, s1, s9
	s_cselect_b32 s36, s14, s8
	s_cselect_b32 s9, s25, s44
	s_cselect_b32 s8, s27, s33
	v_lshl_add_u64 v[160:161], s[6:7], 0, v[148:149]
	s_add_i32 m0, s55, 0xc000
	ds_read_b128 v[192:195], v169
	ds_read_b128 v[196:199], v169 offset:1024
	ds_read_b128 v[200:203], v169 offset:2048
	ds_read_b128 v[204:207], v169 offset:3072
	ds_read_b128 v[208:211], v169 offset:4096
	ds_read_b128 v[212:215], v169 offset:5120
	ds_read_b128 v[216:219], v169 offset:6144
	ds_read_b128 v[220:223], v169 offset:7168
	global_load_lds_dwordx4 v[160:161], off
	v_lshl_add_u64 v[160:161], s[6:7], 0, v[150:151]
	s_add_i32 m0, s55, 0xe000
	s_nop 0
	global_load_lds_dwordx4 v[160:161], off
	s_waitcnt vmcnt(8)
	s_waitcnt lgkmcnt(0)
	s_barrier
	s_setprio 3
	s_waitcnt lgkmcnt(0)
	v_mfma_f32_16x16x32_bf16 v[126:129], v[130:133], v[192:195], v[126:129]
	v_mfma_f32_16x16x32_bf16 v[118:121], v[156:159], v[192:195], v[118:121]
	v_mfma_f32_16x16x32_bf16 v[110:113], v[130:133], v[200:203], v[110:113]
	v_mfma_f32_16x16x32_bf16 v[102:105], v[156:159], v[200:203], v[102:105]
	v_mfma_f32_16x16x32_bf16 v[94:97], v[130:133], v[208:211], v[94:97]
	v_mfma_f32_16x16x32_bf16 v[86:89], v[156:159], v[208:211], v[86:89]
	v_mfma_f32_16x16x32_bf16 v[78:81], v[130:133], v[216:219], v[78:81]
	v_mfma_f32_16x16x32_bf16 v[70:73], v[156:159], v[216:219], v[70:73]
	v_mfma_f32_16x16x32_bf16 v[126:129], v[134:137], v[196:199], v[126:129]
	v_mfma_f32_16x16x32_bf16 v[118:121], v[172:175], v[196:199], v[118:121]
	v_mfma_f32_16x16x32_bf16 v[110:113], v[134:137], v[204:207], v[110:113]
	v_mfma_f32_16x16x32_bf16 v[102:105], v[172:175], v[204:207], v[102:105]
	v_mfma_f32_16x16x32_bf16 v[94:97], v[134:137], v[212:215], v[94:97]
	v_mfma_f32_16x16x32_bf16 v[86:89], v[172:175], v[212:215], v[86:89]
	v_mfma_f32_16x16x32_bf16 v[78:81], v[134:137], v[220:223], v[78:81]
	v_mfma_f32_16x16x32_bf16 v[70:73], v[172:175], v[220:223], v[70:73]
	s_setprio 0
	s_setprio 3
	v_mfma_f32_16x16x32_bf16 v[122:125], v[176:179], v[192:195], v[122:125]
	v_mfma_f32_16x16x32_bf16 v[114:117], v[184:187], v[192:195], v[114:117]
	v_mfma_f32_16x16x32_bf16 v[106:109], v[176:179], v[200:203], v[106:109]
	v_mfma_f32_16x16x32_bf16 v[98:101], v[184:187], v[200:203], v[98:101]
	v_mfma_f32_16x16x32_bf16 v[90:93], v[176:179], v[208:211], v[90:93]
	v_mfma_f32_16x16x32_bf16 v[82:85], v[184:187], v[208:211], v[82:85]
	v_mfma_f32_16x16x32_bf16 v[74:77], v[176:179], v[216:219], v[74:77]
	v_mfma_f32_16x16x32_bf16 v[66:69], v[184:187], v[216:219], v[66:69]
	v_mfma_f32_16x16x32_bf16 v[122:125], v[180:183], v[196:199], v[122:125]
	v_mfma_f32_16x16x32_bf16 v[114:117], v[188:191], v[196:199], v[114:117]
	v_mfma_f32_16x16x32_bf16 v[106:109], v[180:183], v[204:207], v[106:109]
	v_mfma_f32_16x16x32_bf16 v[98:101], v[188:191], v[204:207], v[98:101]
	v_mfma_f32_16x16x32_bf16 v[90:93], v[180:183], v[212:215], v[90:93]
	v_mfma_f32_16x16x32_bf16 v[82:85], v[188:191], v[212:215], v[82:85]
	v_mfma_f32_16x16x32_bf16 v[74:77], v[180:183], v[220:223], v[74:77]
	v_mfma_f32_16x16x32_bf16 v[66:69], v[188:191], v[220:223], v[66:69]
	s_setprio 0
	s_barrier
	s_add_i32 s56, s83, s66
	v_lshl_add_u64 v[160:161], s[8:9], 0, v[140:141]
	s_mov_b32 m0, s56
	ds_read_b128 v[192:195], v169 offset:16384
	ds_read_b128 v[196:199], v169 offset:17408
	ds_read_b128 v[200:203], v169 offset:18432
	ds_read_b128 v[204:207], v169 offset:19456
	ds_read_b128 v[208:211], v169 offset:20480
	ds_read_b128 v[212:215], v169 offset:21504
	ds_read_b128 v[216:219], v169 offset:22528
	ds_read_b128 v[220:223], v169 offset:23552
	global_load_lds_dwordx4 v[160:161], off
	s_add_i32 m0, s56, 0x2000
	s_add_u32 s56, s8, 0x100000
	v_lshl_add_u64 v[224:225], s[8:9], 0, v[144:145]
	s_addc_u32 s57, s9, 0
	s_add_i32 s58, s89, s66
	global_load_lds_dwordx4 v[224:225], off
	v_lshl_add_u64 v[226:227], s[56:57], 0, v[140:141]
	s_mov_b32 m0, s58
	v_lshl_add_u64 v[228:229], s[36:37], 0, v[142:143]
	global_load_lds_dwordx4 v[226:227], off
	v_lshl_add_u64 v[226:227], s[56:57], 0, v[144:145]
	s_add_i32 m0, s58, 0x2000
	s_nop 0
	global_load_lds_dwordx4 v[226:227], off
	v_lshl_add_u64 v[226:227], s[36:37], 0, v[138:139]
	s_waitcnt vmcnt(6)
	s_waitcnt lgkmcnt(0)
	s_barrier
; #define PG8_STAGE(bufoff, gbase, voff) do { _Pragma("unroll") for (int _i = 0; _i < 2; ++_i) \
;         __builtin_amdgcn_global_load_lds((const unsigned*)((const char*)(gbase) + (voff)[_i]), (PG8_LAS unsigned*)(lds + (bufoff) + ldsw + _i * 8192), 16, 0, 0); } while (0)
; #define PG8_LDA(dst, b, h) do { _Pragma("unroll") for (int m = 0; m < 4; ++m) _Pragma("unroll") for (int k = 0; k < 2; ++k) dst[m][k] = *(const PG8_LAS bf16x8*)(lds + PG8_SA(b, h) + aoff + m * 2048 + k * 1024); } while (0)
; #define PG8_LDB(dst, b, h) do { _Pragma("unroll") for (int n = 0; n < 2; ++n) _Pragma("unroll") for (int k = 0; k < 2; ++k) dst[n][k] = *(const PG8_LAS bf16x8*)(lds + PG8_SB(b, h) + boff + n * 2048 + k * 1024); } while (0)
; #define PG8_MMA(ai, bj, At, Bt) do { __builtin_amdgcn_s_setprio(3); _Pragma("unroll") for (int m = 0; m < 4; ++m) _Pragma("unroll") for (int n = 0; n < 2; ++n) _Pragma("unroll") for (int k = 0; k < 2; ++k) \
;         acc[ai][bj][m][n] = __builtin_amdgcn_mfma_f32_16x16x32_bf16(Bt[n][k], At[m][k], acc[ai][bj][m][n], 0, 0, 0); __builtin_amdgcn_s_setprio(0); } while (0)
; #define PG8_WAIT_V(n) asm volatile("s_waitcnt vmcnt(" #n ")" ::: "memory")
; #define PG8_WAIT_L(n) asm volatile("s_waitcnt lgkmcnt(" #n ")" ::: "memory")
; #define PG8_BAR __builtin_amdgcn_s_barrier()
; #define PG8_SCHED __builtin_amdgcn_sched_barrier(0)
; template <class Epi, class Sched, bool ALIGN_EPI = false, bool SP2 = false>
; __device__ __forceinline__ void gemm_phase(PG8_LAS unsigned char* lds, const Gemm g, const Sched& S, const Epi& E) {
;     ...
;             PG8_WAIT_V(8); PG8_WAIT_L(0); PG8_BAR; PG8_MMA(0, 0, At, B0); PG8_MMA(0, 1, At, B1); PG8_BAR; PG8_SCHED;
;             PG8_LDA(At, 0, 1); PG8_STAGE(PG8_SB(0, 0), b2, voffB); PG8_STAGE(PG8_SB(0, 1), b2 + hstepB, voffB); PG8_STAGE(PG8_SA(0, 0), a2, voffA);
;             PG8_WAIT_V(8); PG8_WAIT_L(0); PG8_BAR; PG8_MMA(1, 0, At, B0); PG8_MMA(1, 1, At, B1); PG8_BAR; PG8_SCHED;
;             PG8_LDB(B0, 1, 0); PG8_LDB(B1, 1, 1); PG8_SCHED; PG8_LDA(At, 1, 0); PG8_STAGE(PG8_SA(0, 1), a2 + hstepA, voffA);
;             PG8_WAIT_V(8); PG8_WAIT_L(0); PG8_BAR; PG8_MMA(0, 0, At, B0); PG8_MMA(0, 1, At, B1); PG8_BAR; PG8_SCHED;
	s_setprio 3
	s_waitcnt lgkmcnt(0)
	v_mfma_f32_16x16x32_bf16 v[62:65], v[130:133], v[192:195], v[62:65]
	v_mfma_f32_16x16x32_bf16 v[54:57], v[156:159], v[192:195], v[54:57]
	v_mfma_f32_16x16x32_bf16 v[46:49], v[130:133], v[200:203], v[46:49]
	v_mfma_f32_16x16x32_bf16 v[38:41], v[156:159], v[200:203], v[38:41]
	v_mfma_f32_16x16x32_bf16 v[30:33], v[130:133], v[208:211], v[30:33]
	v_mfma_f32_16x16x32_bf16 v[22:25], v[156:159], v[208:211], v[22:25]
	v_mfma_f32_16x16x32_bf16 v[14:17], v[130:133], v[216:219], v[14:17]
	v_mfma_f32_16x16x32_bf16 v[6:9], v[156:159], v[216:219], v[6:9]
	v_mfma_f32_16x16x32_bf16 v[62:65], v[134:137], v[196:199], v[62:65]
	v_mfma_f32_16x16x32_bf16 v[54:57], v[172:175], v[196:199], v[54:57]
	v_mfma_f32_16x16x32_bf16 v[46:49], v[134:137], v[204:207], v[46:49]
	v_mfma_f32_16x16x32_bf16 v[38:41], v[172:175], v[204:207], v[38:41]
	v_mfma_f32_16x16x32_bf16 v[30:33], v[134:137], v[212:215], v[30:33]
	v_mfma_f32_16x16x32_bf16 v[22:25], v[172:175], v[212:215], v[22:25]
	v_mfma_f32_16x16x32_bf16 v[14:17], v[134:137], v[220:223], v[14:17]
	v_mfma_f32_16x16x32_bf16 v[6:9], v[172:175], v[220:223], v[6:9]
	s_setprio 0
	s_setprio 3
	v_mfma_f32_16x16x32_bf16 v[58:61], v[176:179], v[192:195], v[58:61]
	v_mfma_f32_16x16x32_bf16 v[50:53], v[184:187], v[192:195], v[50:53]
	v_mfma_f32_16x16x32_bf16 v[42:45], v[176:179], v[200:203], v[42:45]
	v_mfma_f32_16x16x32_bf16 v[34:37], v[184:187], v[200:203], v[34:37]
	v_mfma_f32_16x16x32_bf16 v[26:29], v[176:179], v[208:211], v[26:29]
	v_mfma_f32_16x16x32_bf16 v[18:21], v[184:187], v[208:211], v[18:21]
	v_mfma_f32_16x16x32_bf16 v[10:13], v[176:179], v[216:219], v[10:13]
	v_mfma_f32_16x16x32_bf16 v[2:5], v[184:187], v[216:219], v[2:5]
	v_mfma_f32_16x16x32_bf16 v[58:61], v[180:183], v[196:199], v[58:61]
	v_mfma_f32_16x16x32_bf16 v[50:53], v[188:191], v[196:199], v[50:53]
	v_mfma_f32_16x16x32_bf16 v[42:45], v[180:183], v[204:207], v[42:45]
	v_mfma_f32_16x16x32_bf16 v[34:37], v[188:191], v[204:207], v[34:37]
	v_mfma_f32_16x16x32_bf16 v[26:29], v[180:183], v[212:215], v[26:29]
	v_mfma_f32_16x16x32_bf16 v[18:21], v[188:191], v[212:215], v[18:21]
	v_mfma_f32_16x16x32_bf16 v[10:13], v[180:183], v[220:223], v[10:13]
	v_mfma_f32_16x16x32_bf16 v[2:5], v[188:191], v[220:223], v[2:5]
	s_setprio 0
	s_barrier
	s_add_i32 s56, 0, 0x18000
	v_add_u32_e32 v146, s56, v164
	s_add_i32 s57, 0, 0x1c000
	ds_read_b128 v[130:133], v146
	ds_read_b128 v[134:137], v146 offset:1024
	ds_read_b128 v[156:159], v146 offset:2048
	ds_read_b128 v[172:175], v146 offset:3072
	v_add_u32_e32 v146, s57, v164
	ds_read_b128 v[176:179], v146
	ds_read_b128 v[180:183], v146 offset:1024
	ds_read_b128 v[184:187], v146 offset:2048
	ds_read_b128 v[188:191], v146 offset:3072
	s_add_u32 s36, s36, 0x100000
	s_addc_u32 s37, s37, 0
	s_mov_b32 m0, s72
	v_lshl_add_u64 v[230:231], s[36:37], 0, v[138:139]
	ds_read_b128 v[192:195], v169 offset:32768
	ds_read_b128 v[196:199], v169 offset:33792
	ds_read_b128 v[200:203], v169 offset:34816
	ds_read_b128 v[204:207], v169 offset:35840
	ds_read_b128 v[208:211], v169 offset:36864
	ds_read_b128 v[212:215], v169 offset:37888
	ds_read_b128 v[216:219], v169 offset:38912
	ds_read_b128 v[220:223], v169 offset:39936
	s_mov_b32 m0, s55
	s_nop 0
	global_load_lds_dwordx4 v[226:227], off
	s_mov_b32 m0, s67
	s_nop 0
	global_load_lds_dwordx4 v[228:229], off
	s_mov_b32 m0, s72
	s_nop 0
	global_load_lds_dwordx4 v[230:231], off
	v_lshl_add_u64 v[230:231], s[36:37], 0, v[142:143]
	s_mov_b32 m0, s73
	s_nop 0
	global_load_lds_dwordx4 v[230:231], off
	s_waitcnt vmcnt(8)
	s_waitcnt lgkmcnt(0)
	s_barrier
	s_setprio 3
	s_waitcnt lgkmcnt(0)
	v_mfma_f32_16x16x32_bf16 v[126:129], v[130:133], v[192:195], v[126:129]
	v_mfma_f32_16x16x32_bf16 v[118:121], v[156:159], v[192:195], v[118:121]
	v_mfma_f32_16x16x32_bf16 v[110:113], v[130:133], v[200:203], v[110:113]
	v_mfma_f32_16x16x32_bf16 v[102:105], v[156:159], v[200:203], v[102:105]
	v_mfma_f32_16x16x32_bf16 v[94:97], v[130:133], v[208:211], v[94:97]
	v_mfma_f32_16x16x32_bf16 v[86:89], v[156:159], v[208:211], v[86:89]
	v_mfma_f32_16x16x32_bf16 v[78:81], v[130:133], v[216:219], v[78:81]
	v_mfma_f32_16x16x32_bf16 v[70:73], v[156:159], v[216:219], v[70:73]
	v_mfma_f32_16x16x32_bf16 v[126:129], v[134:137], v[196:199], v[126:129]
	v_mfma_f32_16x16x32_bf16 v[118:121], v[172:175], v[196:199], v[118:121]
	v_mfma_f32_16x16x32_bf16 v[110:113], v[134:137], v[204:207], v[110:113]
	v_mfma_f32_16x16x32_bf16 v[102:105], v[172:175], v[204:207], v[102:105]
	v_mfma_f32_16x16x32_bf16 v[94:97], v[134:137], v[212:215], v[94:97]
	v_mfma_f32_16x16x32_bf16 v[86:89], v[172:175], v[212:215], v[86:89]
	v_mfma_f32_16x16x32_bf16 v[78:81], v[134:137], v[220:223], v[78:81]
	v_mfma_f32_16x16x32_bf16 v[70:73], v[172:175], v[220:223], v[70:73]
	s_setprio 0
	s_setprio 3
	v_mfma_f32_16x16x32_bf16 v[122:125], v[176:179], v[192:195], v[122:125]
	v_mfma_f32_16x16x32_bf16 v[114:117], v[184:187], v[192:195], v[114:117]
	v_mfma_f32_16x16x32_bf16 v[106:109], v[176:179], v[200:203], v[106:109]
	v_mfma_f32_16x16x32_bf16 v[98:101], v[184:187], v[200:203], v[98:101]
	v_mfma_f32_16x16x32_bf16 v[90:93], v[176:179], v[208:211], v[90:93]
	v_mfma_f32_16x16x32_bf16 v[82:85], v[184:187], v[208:211], v[82:85]
	v_mfma_f32_16x16x32_bf16 v[74:77], v[176:179], v[216:219], v[74:77]
	v_mfma_f32_16x16x32_bf16 v[66:69], v[184:187], v[216:219], v[66:69]
	v_mfma_f32_16x16x32_bf16 v[122:125], v[180:183], v[196:199], v[122:125]
	v_mfma_f32_16x16x32_bf16 v[114:117], v[188:191], v[196:199], v[114:117]
	v_mfma_f32_16x16x32_bf16 v[106:109], v[180:183], v[204:207], v[106:109]
	v_mfma_f32_16x16x32_bf16 v[98:101], v[188:191], v[204:207], v[98:101]
	v_mfma_f32_16x16x32_bf16 v[90:93], v[180:183], v[212:215], v[90:93]
	v_mfma_f32_16x16x32_bf16 v[82:85], v[188:191], v[212:215], v[82:85]
	v_mfma_f32_16x16x32_bf16 v[74:77], v[180:183], v[220:223], v[74:77]
	v_mfma_f32_16x16x32_bf16 v[66:69], v[188:191], v[220:223], v[66:69]
	s_setprio 0
	s_barrier
; #define PG8_STAGE(bufoff, gbase, voff) do { _Pragma("unroll") for (int _i = 0; _i < 2; ++_i) \
;         __builtin_amdgcn_global_load_lds((const unsigned*)((const char*)(gbase) + (voff)[_i]), (PG8_LAS unsigned*)(lds + (bufoff) + ldsw + _i * 8192), 16, 0, 0); } while (0)
; #define PG8_LDA(dst, b, h) do { _Pragma("unroll") for (int m = 0; m < 4; ++m) _Pragma("unroll") for (int k = 0; k < 2; ++k) dst[m][k] = *(const PG8_LAS bf16x8*)(lds + PG8_SA(b, h) + aoff + m * 2048 + k * 1024); } while (0)
; #define PG8_MMA(ai, bj, At, Bt) do { __builtin_amdgcn_s_setprio(3); _Pragma("unroll") for (int m = 0; m < 4; ++m) _Pragma("unroll") for (int n = 0; n < 2; ++n) _Pragma("unroll") for (int k = 0; k < 2; ++k) \
;         acc[ai][bj][m][n] = __builtin_amdgcn_mfma_f32_16x16x32_bf16(Bt[n][k], At[m][k], acc[ai][bj][m][n], 0, 0, 0); __builtin_amdgcn_s_setprio(0); } while (0)
; #define PG8_WAIT_V(n) asm volatile("s_waitcnt vmcnt(" #n ")" ::: "memory")
; #define PG8_WAIT_L(n) asm volatile("s_waitcnt lgkmcnt(" #n ")" ::: "memory")
; #define PG8_BAR __builtin_amdgcn_s_barrier()
; #define PG8_SCHED __builtin_amdgcn_sched_barrier(0)
; template <class Epi, class Sched, bool ALIGN_EPI = false, bool SP2 = false>
; __device__ __forceinline__ void gemm_phase(PG8_LAS unsigned char* lds, const Gemm g, const Sched& S, const Epi& E) {
;     ...
;             PG8_LDA(At, 1, 1); PG8_STAGE(PG8_SB(1, 0), b3, voffB); PG8_STAGE(PG8_SB(1, 1), b3 + hstepB, voffB); PG8_STAGE(PG8_SA(1, 0), a3, voffA);
;             PG8_WAIT_V(8); PG8_WAIT_L(0); PG8_BAR; PG8_MMA(1, 0, At, B0); PG8_MMA(1, 1, At, B1); PG8_BAR; PG8_SCHED;
;     ...
;         if constexpr (ALIGN_EPI) { if (wr == 0) PG8_BAR; }
;         if constexpr (!Epi::AFTER_DRAIN) { E(acc, cur, wr, wc, fr, fq); S.done(cur); }
	s_add_i32 s36, s56, s66
	v_lshl_add_u64 v[160:161], v[160:161], 0, s[18:19]
	s_mov_b32 m0, s36
	ds_read_b128 v[192:195], v169 offset:49152
	ds_read_b128 v[196:199], v169 offset:50176
	ds_read_b128 v[200:203], v169 offset:51200
	ds_read_b128 v[204:207], v169 offset:52224
	ds_read_b128 v[208:211], v169 offset:53248
	ds_read_b128 v[212:215], v169 offset:54272
	ds_read_b128 v[216:219], v169 offset:55296
	ds_read_b128 v[220:223], v169 offset:56320
	global_load_lds_dwordx4 v[160:161], off
	s_add_i32 m0, s36, 0x2000
	s_add_u32 s8, s8, 0x100080
	v_lshl_add_u64 v[160:161], v[224:225], 0, s[18:19]
	s_addc_u32 s9, s9, 0
	s_add_i32 s36, s57, s66
	global_load_lds_dwordx4 v[160:161], off
	v_lshl_add_u64 v[160:161], s[8:9], 0, v[140:141]
	s_mov_b32 m0, s36
	s_nop 0
	global_load_lds_dwordx4 v[160:161], off
	v_lshl_add_u64 v[160:161], s[8:9], 0, v[144:145]
	s_add_i32 m0, s36, 0x2000
	s_nop 0
	global_load_lds_dwordx4 v[160:161], off
	v_lshl_add_u64 v[160:161], v[226:227], 0, s[18:19]
	s_mov_b32 m0, s75
	s_nop 0
	global_load_lds_dwordx4 v[160:161], off
	v_lshl_add_u64 v[160:161], v[228:229], 0, s[18:19]
	s_mov_b32 m0, s76
	s_nop 0
	global_load_lds_dwordx4 v[160:161], off
	s_waitcnt vmcnt(8)
	s_waitcnt lgkmcnt(0)
	s_barrier
	s_setprio 3
	s_waitcnt lgkmcnt(0)
	v_mfma_f32_16x16x32_bf16 v[62:65], v[130:133], v[192:195], v[62:65]
	v_mfma_f32_16x16x32_bf16 v[54:57], v[156:159], v[192:195], v[54:57]
	v_mfma_f32_16x16x32_bf16 v[46:49], v[130:133], v[200:203], v[46:49]
	v_mfma_f32_16x16x32_bf16 v[38:41], v[156:159], v[200:203], v[38:41]
	v_mfma_f32_16x16x32_bf16 v[30:33], v[130:133], v[208:211], v[30:33]
	v_mfma_f32_16x16x32_bf16 v[22:25], v[156:159], v[208:211], v[22:25]
	v_mfma_f32_16x16x32_bf16 v[14:17], v[130:133], v[216:219], v[14:17]
	v_mfma_f32_16x16x32_bf16 v[6:9], v[156:159], v[216:219], v[6:9]
	v_mfma_f32_16x16x32_bf16 v[62:65], v[134:137], v[196:199], v[62:65]
	v_mfma_f32_16x16x32_bf16 v[54:57], v[172:175], v[196:199], v[54:57]
	v_mfma_f32_16x16x32_bf16 v[46:49], v[134:137], v[204:207], v[46:49]
	v_mfma_f32_16x16x32_bf16 v[38:41], v[172:175], v[204:207], v[38:41]
	v_mfma_f32_16x16x32_bf16 v[30:33], v[134:137], v[212:215], v[30:33]
	v_mfma_f32_16x16x32_bf16 v[22:25], v[172:175], v[212:215], v[22:25]
	v_mfma_f32_16x16x32_bf16 v[14:17], v[134:137], v[220:223], v[14:17]
	v_mfma_f32_16x16x32_bf16 v[6:9], v[172:175], v[220:223], v[6:9]
	s_setprio 0
	s_setprio 3
	v_mfma_f32_16x16x32_bf16 v[58:61], v[176:179], v[192:195], v[58:61]
	v_mfma_f32_16x16x32_bf16 v[50:53], v[184:187], v[192:195], v[50:53]
	v_mfma_f32_16x16x32_bf16 v[42:45], v[176:179], v[200:203], v[42:45]
	v_mfma_f32_16x16x32_bf16 v[34:37], v[184:187], v[200:203], v[34:37]
	v_mfma_f32_16x16x32_bf16 v[26:29], v[176:179], v[208:211], v[26:29]
	v_mfma_f32_16x16x32_bf16 v[18:21], v[184:187], v[208:211], v[18:21]
	v_mfma_f32_16x16x32_bf16 v[10:13], v[176:179], v[216:219], v[10:13]
	v_mfma_f32_16x16x32_bf16 v[2:5], v[184:187], v[216:219], v[2:5]
	v_mfma_f32_16x16x32_bf16 v[58:61], v[180:183], v[196:199], v[58:61]
	v_mfma_f32_16x16x32_bf16 v[50:53], v[188:191], v[196:199], v[50:53]
	v_mfma_f32_16x16x32_bf16 v[42:45], v[180:183], v[204:207], v[42:45]
	v_mfma_f32_16x16x32_bf16 v[34:37], v[188:191], v[204:207], v[34:37]
	v_mfma_f32_16x16x32_bf16 v[26:29], v[180:183], v[212:215], v[26:29]
	v_mfma_f32_16x16x32_bf16 v[18:21], v[188:191], v[212:215], v[18:21]
	v_mfma_f32_16x16x32_bf16 v[10:13], v[180:183], v[220:223], v[10:13]
	v_mfma_f32_16x16x32_bf16 v[2:5], v[188:191], v[220:223], v[2:5]
	s_setprio 0
	s_barrier
	s_add_i32 s45, s45, 2
	s_add_u32 s6, s6, 0x100
	s_addc_u32 s7, s7, 0
	s_add_u32 s33, s33, 0x100
	s_addc_u32 s44, s44, 0
	s_cmp_gt_u32 s45, 61
	s_cbranch_scc0 .LBB0_143
	s_and_b64 vcc, exec, s[20:21]
	s_cbranch_vccz .LBB0_148
	s_barrier
	v_lshl_add_u32 v156, s0, 8, v163
	s_cmp_lt_i32 s54, 40
	s_mov_b64 s[0:1], -1
	s_cbranch_scc1 .LBB0_149

; #define PG8_STAGE(bufoff, gbase, voff) do { _Pragma("unroll") for (int _i = 0; _i < 2; ++_i) \
;         __builtin_amdgcn_global_load_lds((const unsigned*)((const char*)(gbase) + (voff)[_i]), (PG8_LAS unsigned*)(lds + (bufoff) + ldsw + _i * 8192), 16, 0, 0); } while (0)
; #define PG8_LDA(dst, b, h) do { _Pragma("unroll") for (int m = 0; m < 4; ++m) _Pragma("unroll") for (int k = 0; k < 2; ++k) dst[m][k] = *(const PG8_LAS bf16x8*)(lds + PG8_SA(b, h) + aoff + m * 2048 + k * 1024); } while (0)
; #define PG8_LDB(dst, b, h) do { _Pragma("unroll") for (int n = 0; n < 2; ++n) _Pragma("unroll") for (int k = 0; k < 2; ++k) dst[n][k] = *(const PG8_LAS bf16x8*)(lds + PG8_SB(b, h) + boff + n * 2048 + k * 1024); } while (0)
; #define PG8_MMA(ai, bj, At, Bt) do { __builtin_amdgcn_s_setprio(3); _Pragma("unroll") for (int m = 0; m < 4; ++m) _Pragma("unroll") for (int n = 0; n < 2; ++n) _Pragma("unroll") for (int k = 0; k < 2; ++k) \
;         acc[ai][bj][m][n] = __builtin_amdgcn_mfma_f32_16x16x32_bf16(Bt[n][k], At[m][k], acc[ai][bj][m][n], 0, 0, 0); __builtin_amdgcn_s_setprio(0); } while (0)
; #define PG8_WAIT_V(n) asm volatile("s_waitcnt vmcnt(" #n ")" ::: "memory")
; #define PG8_WAIT_L(n) asm volatile("s_waitcnt lgkmcnt(" #n ")" ::: "memory")
; template <class Epi, class Sched, bool ALIGN_EPI = false, bool SP2 = false>
; __device__ __forceinline__ void gemm_phase(PG8_LAS unsigned char* lds, const Gemm g, const Sched& S, const Epi& E) {
;     ...
;         for (int t = 0; t < nt; t += 2) {
;             const bool last = (t == nt - 2);
;             const char* a1 = cA + (size_t)(t + 1) * kstep;
;             const char* a2 = last ? nA : cA + (size_t)(t + 2) * kstep; const char* b2 = last ? nB : cB + (size_t)(t + 2) * kstep;
;             const char* a3 = a2 + kstep; const char* b3 = b2 + kstep;
;             if (last && has_next) S.a_ready(nxt);
;             if constexpr (Epi::MIDK) { if (t == E.midk_step(nt)) E.midk(acc, cur, wr, wc, fr, fq); }
;             if constexpr (SP2) {
;             PG8_LDB(B0, 0, 0); PG8_LDB(B1, 0, 1); PG8_SCHED; PG8_LDA(At, 0, 0); PG8_STAGE(PG8_SA(1, 1), a1 + hstepA, voffA);
;             PG8_WAIT_V(8); PG8_WAIT_L(0); PG8_BAR; PG8_MMA(0, 0, At, B0); PG8_MMA(0, 1, At, B1); PG8_BAR; PG8_SCHED;
;             PG8_LDA(At, 0, 1); PG8_STAGE(PG8_SB(0, 0), b2, voffB); PG8_STAGE(PG8_SB(0, 1), b2 + hstepB, voffB); PG8_STAGE(PG8_SA(0, 0), a2, voffA);
.LBB0_478:
	ds_read_b128 v[130:133], v170
	ds_read_b128 v[134:137], v170 offset:1024
	ds_read_b128 v[138:141], v170 offset:2048
	ds_read_b128 v[142:145], v170 offset:3072
	ds_read_b128 v[164:167], v171
	ds_read_b128 v[174:177], v171 offset:1024
	ds_read_b128 v[178:181], v171 offset:2048
	ds_read_b128 v[182:185], v171 offset:3072
	s_add_u32 s36, s6, 0xfff80080
	s_addc_u32 s37, s7, -1
	s_cmp_eq_u32 s79, 4
	s_cselect_b32 s59, s27, s37
	s_cselect_b32 s58, s26, s36
	s_cselect_b32 s37, s23, s78
	s_cselect_b32 s36, s25, s77
	v_lshl_add_u64 v[218:219], s[6:7], 0, v[154:155]
	s_add_i32 m0, s31, 0xc000
	ds_read_b128 v[186:189], v172
	ds_read_b128 v[190:193], v172 offset:1024
	ds_read_b128 v[194:197], v172 offset:2048
	ds_read_b128 v[198:201], v172 offset:3072
	ds_read_b128 v[202:205], v172 offset:4096
	ds_read_b128 v[206:209], v172 offset:5120
	ds_read_b128 v[210:213], v172 offset:6144
	ds_read_b128 v[214:217], v172 offset:7168
	global_load_lds_dwordx4 v[218:219], off
	v_lshl_add_u64 v[218:219], s[6:7], 0, v[156:157]
	s_add_i32 m0, s31, 0xe000
	s_nop 0
	global_load_lds_dwordx4 v[218:219], off
	s_waitcnt vmcnt(8)
	s_waitcnt lgkmcnt(0)
	s_barrier
	s_setprio 3
	s_waitcnt lgkmcnt(0)
	v_mfma_f32_16x16x32_bf16 v[126:129], v[130:133], v[186:189], v[126:129]
	v_mfma_f32_16x16x32_bf16 v[122:125], v[138:141], v[186:189], v[122:125]
	v_mfma_f32_16x16x32_bf16 v[118:121], v[130:133], v[194:197], v[118:121]
	v_mfma_f32_16x16x32_bf16 v[114:117], v[138:141], v[194:197], v[114:117]
	v_mfma_f32_16x16x32_bf16 v[110:113], v[130:133], v[202:205], v[110:113]
	v_mfma_f32_16x16x32_bf16 v[102:105], v[138:141], v[202:205], v[102:105]
	v_mfma_f32_16x16x32_bf16 v[78:81], v[130:133], v[210:213], v[78:81]
	v_mfma_f32_16x16x32_bf16 v[74:77], v[138:141], v[210:213], v[74:77]
	v_mfma_f32_16x16x32_bf16 v[126:129], v[134:137], v[190:193], v[126:129]
	v_mfma_f32_16x16x32_bf16 v[122:125], v[142:145], v[190:193], v[122:125]
	v_mfma_f32_16x16x32_bf16 v[118:121], v[134:137], v[198:201], v[118:121]
	v_mfma_f32_16x16x32_bf16 v[114:117], v[142:145], v[198:201], v[114:117]
	v_mfma_f32_16x16x32_bf16 v[110:113], v[134:137], v[206:209], v[110:113]
	v_mfma_f32_16x16x32_bf16 v[102:105], v[142:145], v[206:209], v[102:105]
	v_mfma_f32_16x16x32_bf16 v[78:81], v[134:137], v[214:217], v[78:81]
	v_mfma_f32_16x16x32_bf16 v[74:77], v[142:145], v[214:217], v[74:77]
	s_setprio 0
	s_setprio 3
	v_mfma_f32_16x16x32_bf16 v[106:109], v[164:167], v[186:189], v[106:109]
	v_mfma_f32_16x16x32_bf16 v[98:101], v[178:181], v[186:189], v[98:101]
	v_mfma_f32_16x16x32_bf16 v[94:97], v[164:167], v[194:197], v[94:97]
	v_mfma_f32_16x16x32_bf16 v[90:93], v[178:181], v[194:197], v[90:93]
	v_mfma_f32_16x16x32_bf16 v[86:89], v[164:167], v[202:205], v[86:89]
	v_mfma_f32_16x16x32_bf16 v[82:85], v[178:181], v[202:205], v[82:85]
	v_mfma_f32_16x16x32_bf16 v[70:73], v[164:167], v[210:213], v[70:73]
	v_mfma_f32_16x16x32_bf16 v[66:69], v[178:181], v[210:213], v[66:69]
	v_mfma_f32_16x16x32_bf16 v[106:109], v[174:177], v[190:193], v[106:109]
	v_mfma_f32_16x16x32_bf16 v[98:101], v[182:185], v[190:193], v[98:101]
	v_mfma_f32_16x16x32_bf16 v[94:97], v[174:177], v[198:201], v[94:97]
	v_mfma_f32_16x16x32_bf16 v[90:93], v[182:185], v[198:201], v[90:93]
	v_mfma_f32_16x16x32_bf16 v[86:89], v[174:177], v[206:209], v[86:89]
	v_mfma_f32_16x16x32_bf16 v[82:85], v[182:185], v[206:209], v[82:85]
	v_mfma_f32_16x16x32_bf16 v[70:73], v[174:177], v[214:217], v[70:73]
	v_mfma_f32_16x16x32_bf16 v[66:69], v[182:185], v[214:217], v[66:69]
	s_setprio 0
	s_barrier
	s_add_i32 s83, s72, s44
	v_lshl_add_u64 v[218:219], s[36:37], 0, v[148:149]
	s_mov_b32 m0, s83
	ds_read_b128 v[186:189], v172 offset:16384
	ds_read_b128 v[190:193], v172 offset:17408
	ds_read_b128 v[194:197], v172 offset:18432
	ds_read_b128 v[198:201], v172 offset:19456
	ds_read_b128 v[202:205], v172 offset:20480
	ds_read_b128 v[206:209], v172 offset:21504
	ds_read_b128 v[210:213], v172 offset:22528
	ds_read_b128 v[214:217], v172 offset:23552
	global_load_lds_dwordx4 v[218:219], off
	s_add_i32 m0, s83, 0x2000
	s_add_u32 s84, s36, 0x20000
	v_lshl_add_u64 v[220:221], s[36:37], 0, v[152:153]
	s_addc_u32 s85, s37, 0
	s_add_i32 s83, s73, s44
	global_load_lds_dwordx4 v[220:221], off
	v_lshl_add_u64 v[222:223], s[84:85], 0, v[148:149]
	s_mov_b32 m0, s83
	v_lshl_add_u64 v[224:225], s[58:59], 0, v[150:151]
	global_load_lds_dwordx4 v[222:223], off
	v_lshl_add_u64 v[222:223], s[84:85], 0, v[152:153]
	s_add_i32 m0, s83, 0x2000
	s_nop 0
	global_load_lds_dwordx4 v[222:223], off
	v_lshl_add_u64 v[222:223], s[58:59], 0, v[146:147]
	s_waitcnt vmcnt(6)
	s_waitcnt lgkmcnt(0)
	s_barrier
; #define PG8_STAGE(bufoff, gbase, voff) do { _Pragma("unroll") for (int _i = 0; _i < 2; ++_i) \
;         __builtin_amdgcn_global_load_lds((const unsigned*)((const char*)(gbase) + (voff)[_i]), (PG8_LAS unsigned*)(lds + (bufoff) + ldsw + _i * 8192), 16, 0, 0); } while (0)
; #define PG8_LDA(dst, b, h) do { _Pragma("unroll") for (int m = 0; m < 4; ++m) _Pragma("unroll") for (int k = 0; k < 2; ++k) dst[m][k] = *(const PG8_LAS bf16x8*)(lds + PG8_SA(b, h) + aoff + m * 2048 + k * 1024); } while (0)
; #define PG8_LDB(dst, b, h) do { _Pragma("unroll") for (int n = 0; n < 2; ++n) _Pragma("unroll") for (int k = 0; k < 2; ++k) dst[n][k] = *(const PG8_LAS bf16x8*)(lds + PG8_SB(b, h) + boff + n * 2048 + k * 1024); } while (0)
; #define PG8_MMA(ai, bj, At, Bt) do { __builtin_amdgcn_s_setprio(3); _Pragma("unroll") for (int m = 0; m < 4; ++m) _Pragma("unroll") for (int n = 0; n < 2; ++n) _Pragma("unroll") for (int k = 0; k < 2; ++k) \
;         acc[ai][bj][m][n] = __builtin_amdgcn_mfma_f32_16x16x32_bf16(Bt[n][k], At[m][k], acc[ai][bj][m][n], 0, 0, 0); __builtin_amdgcn_s_setprio(0); } while (0)
; #define PG8_WAIT_V(n) asm volatile("s_waitcnt vmcnt(" #n ")" ::: "memory")
; #define PG8_WAIT_L(n) asm volatile("s_waitcnt lgkmcnt(" #n ")" ::: "memory")
; #define PG8_BAR __builtin_amdgcn_s_barrier()
; #define PG8_SCHED __builtin_amdgcn_sched_barrier(0)
; template <class Epi, class Sched, bool ALIGN_EPI = false, bool SP2 = false>
; __device__ __forceinline__ void gemm_phase(PG8_LAS unsigned char* lds, const Gemm g, const Sched& S, const Epi& E) {
;     ...
;             PG8_WAIT_V(8); PG8_WAIT_L(0); PG8_BAR; PG8_MMA(0, 0, At, B0); PG8_MMA(0, 1, At, B1); PG8_BAR; PG8_SCHED;
;             PG8_LDA(At, 0, 1); PG8_STAGE(PG8_SB(0, 0), b2, voffB); PG8_STAGE(PG8_SB(0, 1), b2 + hstepB, voffB); PG8_STAGE(PG8_SA(0, 0), a2, voffA);
;             PG8_WAIT_V(8); PG8_WAIT_L(0); PG8_BAR; PG8_MMA(1, 0, At, B0); PG8_MMA(1, 1, At, B1); PG8_BAR; PG8_SCHED;
;             PG8_LDB(B0, 1, 0); PG8_LDB(B1, 1, 1); PG8_SCHED; PG8_LDA(At, 1, 0); PG8_STAGE(PG8_SA(0, 1), a2 + hstepA, voffA);
;             PG8_WAIT_V(8); PG8_WAIT_L(0); PG8_BAR; PG8_MMA(0, 0, At, B0); PG8_MMA(0, 1, At, B1); PG8_BAR; PG8_SCHED;
	s_setprio 3
	s_waitcnt lgkmcnt(0)
	v_mfma_f32_16x16x32_bf16 v[62:65], v[130:133], v[186:189], v[62:65]
	v_mfma_f32_16x16x32_bf16 v[58:61], v[138:141], v[186:189], v[58:61]
	v_mfma_f32_16x16x32_bf16 v[54:57], v[130:133], v[194:197], v[54:57]
	v_mfma_f32_16x16x32_bf16 v[46:49], v[138:141], v[194:197], v[46:49]
	v_mfma_f32_16x16x32_bf16 v[38:41], v[130:133], v[202:205], v[38:41]
	v_mfma_f32_16x16x32_bf16 v[30:33], v[138:141], v[202:205], v[30:33]
	v_mfma_f32_16x16x32_bf16 v[22:25], v[130:133], v[210:213], v[22:25]
	v_mfma_f32_16x16x32_bf16 v[14:17], v[138:141], v[210:213], v[14:17]
	v_mfma_f32_16x16x32_bf16 v[62:65], v[134:137], v[190:193], v[62:65]
	v_mfma_f32_16x16x32_bf16 v[58:61], v[142:145], v[190:193], v[58:61]
	v_mfma_f32_16x16x32_bf16 v[54:57], v[134:137], v[198:201], v[54:57]
	v_mfma_f32_16x16x32_bf16 v[46:49], v[142:145], v[198:201], v[46:49]
	v_mfma_f32_16x16x32_bf16 v[38:41], v[134:137], v[206:209], v[38:41]
	v_mfma_f32_16x16x32_bf16 v[30:33], v[142:145], v[206:209], v[30:33]
	v_mfma_f32_16x16x32_bf16 v[22:25], v[134:137], v[214:217], v[22:25]
	v_mfma_f32_16x16x32_bf16 v[14:17], v[142:145], v[214:217], v[14:17]
	s_setprio 0
	s_setprio 3
	v_mfma_f32_16x16x32_bf16 v[50:53], v[164:167], v[186:189], v[50:53]
	v_mfma_f32_16x16x32_bf16 v[42:45], v[178:181], v[186:189], v[42:45]
	v_mfma_f32_16x16x32_bf16 v[34:37], v[164:167], v[194:197], v[34:37]
	v_mfma_f32_16x16x32_bf16 v[26:29], v[178:181], v[194:197], v[26:29]
	v_mfma_f32_16x16x32_bf16 v[18:21], v[164:167], v[202:205], v[18:21]
	v_mfma_f32_16x16x32_bf16 v[10:13], v[178:181], v[202:205], v[10:13]
	v_mfma_f32_16x16x32_bf16 v[6:9], v[164:167], v[210:213], v[6:9]
	v_mfma_f32_16x16x32_bf16 v[2:5], v[178:181], v[210:213], v[2:5]
	v_mfma_f32_16x16x32_bf16 v[50:53], v[174:177], v[190:193], v[50:53]
	v_mfma_f32_16x16x32_bf16 v[42:45], v[182:185], v[190:193], v[42:45]
	v_mfma_f32_16x16x32_bf16 v[34:37], v[174:177], v[198:201], v[34:37]
	v_mfma_f32_16x16x32_bf16 v[26:29], v[182:185], v[198:201], v[26:29]
	v_mfma_f32_16x16x32_bf16 v[18:21], v[174:177], v[206:209], v[18:21]
	v_mfma_f32_16x16x32_bf16 v[10:13], v[182:185], v[206:209], v[10:13]
	v_mfma_f32_16x16x32_bf16 v[6:9], v[174:177], v[214:217], v[6:9]
	v_mfma_f32_16x16x32_bf16 v[2:5], v[182:185], v[214:217], v[2:5]
	s_setprio 0
	s_barrier
	s_add_i32 s83, 0, 0x18000
	s_add_i32 s84, 0, 0x1c000
	v_add_u32_e32 v142, s83, v168
	v_add_u32_e32 v173, s84, v168
	ds_read_b128 v[130:133], v142
	ds_read_b128 v[134:137], v142 offset:1024
	ds_read_b128 v[138:141], v142 offset:2048
	ds_read_b128 v[142:145], v142 offset:3072
	ds_read_b128 v[164:167], v173
	ds_read_b128 v[174:177], v173 offset:1024
	ds_read_b128 v[178:181], v173 offset:2048
	ds_read_b128 v[182:185], v173 offset:3072
	s_add_u32 s58, s58, 0x80000
	s_addc_u32 s59, s59, 0
	s_mov_b32 m0, s54
	v_lshl_add_u64 v[226:227], s[58:59], 0, v[146:147]
	ds_read_b128 v[186:189], v172 offset:32768
	ds_read_b128 v[190:193], v172 offset:33792
	ds_read_b128 v[194:197], v172 offset:34816
	ds_read_b128 v[198:201], v172 offset:35840
	ds_read_b128 v[202:205], v172 offset:36864
	ds_read_b128 v[206:209], v172 offset:37888
	ds_read_b128 v[210:213], v172 offset:38912
	ds_read_b128 v[214:217], v172 offset:39936
	s_mov_b32 m0, s31
	s_nop 0
	global_load_lds_dwordx4 v[222:223], off
	s_mov_b32 m0, s45
	s_nop 0
	global_load_lds_dwordx4 v[224:225], off
	s_mov_b32 m0, s54
	s_nop 0
	global_load_lds_dwordx4 v[226:227], off
	v_lshl_add_u64 v[226:227], s[58:59], 0, v[150:151]
	s_mov_b32 m0, s55
	s_nop 0
	global_load_lds_dwordx4 v[226:227], off
	s_waitcnt vmcnt(8)
	s_waitcnt lgkmcnt(0)
	s_barrier
	s_setprio 3
	s_waitcnt lgkmcnt(0)
	v_mfma_f32_16x16x32_bf16 v[126:129], v[130:133], v[186:189], v[126:129]
	v_mfma_f32_16x16x32_bf16 v[122:125], v[138:141], v[186:189], v[122:125]
	v_mfma_f32_16x16x32_bf16 v[118:121], v[130:133], v[194:197], v[118:121]
	v_mfma_f32_16x16x32_bf16 v[114:117], v[138:141], v[194:197], v[114:117]
	v_mfma_f32_16x16x32_bf16 v[110:113], v[130:133], v[202:205], v[110:113]
	v_mfma_f32_16x16x32_bf16 v[102:105], v[138:141], v[202:205], v[102:105]
	v_mfma_f32_16x16x32_bf16 v[78:81], v[130:133], v[210:213], v[78:81]
	v_mfma_f32_16x16x32_bf16 v[74:77], v[138:141], v[210:213], v[74:77]
	v_mfma_f32_16x16x32_bf16 v[126:129], v[134:137], v[190:193], v[126:129]
	v_mfma_f32_16x16x32_bf16 v[122:125], v[142:145], v[190:193], v[122:125]
	v_mfma_f32_16x16x32_bf16 v[118:121], v[134:137], v[198:201], v[118:121]
	v_mfma_f32_16x16x32_bf16 v[114:117], v[142:145], v[198:201], v[114:117]
	v_mfma_f32_16x16x32_bf16 v[110:113], v[134:137], v[206:209], v[110:113]
	v_mfma_f32_16x16x32_bf16 v[102:105], v[142:145], v[206:209], v[102:105]
	v_mfma_f32_16x16x32_bf16 v[78:81], v[134:137], v[214:217], v[78:81]
	v_mfma_f32_16x16x32_bf16 v[74:77], v[142:145], v[214:217], v[74:77]
	s_setprio 0
	s_setprio 3
	v_mfma_f32_16x16x32_bf16 v[106:109], v[164:167], v[186:189], v[106:109]
	v_mfma_f32_16x16x32_bf16 v[98:101], v[178:181], v[186:189], v[98:101]
	v_mfma_f32_16x16x32_bf16 v[94:97], v[164:167], v[194:197], v[94:97]
	v_mfma_f32_16x16x32_bf16 v[90:93], v[178:181], v[194:197], v[90:93]
	v_mfma_f32_16x16x32_bf16 v[86:89], v[164:167], v[202:205], v[86:89]
	v_mfma_f32_16x16x32_bf16 v[82:85], v[178:181], v[202:205], v[82:85]
	v_mfma_f32_16x16x32_bf16 v[70:73], v[164:167], v[210:213], v[70:73]
	v_mfma_f32_16x16x32_bf16 v[66:69], v[178:181], v[210:213], v[66:69]
	v_mfma_f32_16x16x32_bf16 v[106:109], v[174:177], v[190:193], v[106:109]
	v_mfma_f32_16x16x32_bf16 v[98:101], v[182:185], v[190:193], v[98:101]
	v_mfma_f32_16x16x32_bf16 v[94:97], v[174:177], v[198:201], v[94:97]
	v_mfma_f32_16x16x32_bf16 v[90:93], v[182:185], v[198:201], v[90:93]
	v_mfma_f32_16x16x32_bf16 v[86:89], v[174:177], v[206:209], v[86:89]
	v_mfma_f32_16x16x32_bf16 v[82:85], v[182:185], v[206:209], v[82:85]
	v_mfma_f32_16x16x32_bf16 v[70:73], v[174:177], v[214:217], v[70:73]
	v_mfma_f32_16x16x32_bf16 v[66:69], v[182:185], v[214:217], v[66:69]
	s_setprio 0
	s_barrier
; #define PG8_STAGE(bufoff, gbase, voff) do { _Pragma("unroll") for (int _i = 0; _i < 2; ++_i) \
;         __builtin_amdgcn_global_load_lds((const unsigned*)((const char*)(gbase) + (voff)[_i]), (PG8_LAS unsigned*)(lds + (bufoff) + ldsw + _i * 8192), 16, 0, 0); } while (0)
; #define PG8_LDA(dst, b, h) do { _Pragma("unroll") for (int m = 0; m < 4; ++m) _Pragma("unroll") for (int k = 0; k < 2; ++k) dst[m][k] = *(const PG8_LAS bf16x8*)(lds + PG8_SA(b, h) + aoff + m * 2048 + k * 1024); } while (0)
; #define PG8_MMA(ai, bj, At, Bt) do { __builtin_amdgcn_s_setprio(3); _Pragma("unroll") for (int m = 0; m < 4; ++m) _Pragma("unroll") for (int n = 0; n < 2; ++n) _Pragma("unroll") for (int k = 0; k < 2; ++k) \
;         acc[ai][bj][m][n] = __builtin_amdgcn_mfma_f32_16x16x32_bf16(Bt[n][k], At[m][k], acc[ai][bj][m][n], 0, 0, 0); __builtin_amdgcn_s_setprio(0); } while (0)
; #define PG8_WAIT_V(n) asm volatile("s_waitcnt vmcnt(" #n ")" ::: "memory")
; #define PG8_WAIT_L(n) asm volatile("s_waitcnt lgkmcnt(" #n ")" ::: "memory")
; #define PG8_BAR __builtin_amdgcn_s_barrier()
; #define PG8_SCHED __builtin_amdgcn_sched_barrier(0)
; template <class Epi, class Sched, bool ALIGN_EPI = false, bool SP2 = false>
; __device__ __forceinline__ void gemm_phase(PG8_LAS unsigned char* lds, const Gemm g, const Sched& S, const Epi& E) {
;     ...
;             PG8_LDA(At, 1, 1); PG8_STAGE(PG8_SB(1, 0), b3, voffB); PG8_STAGE(PG8_SB(1, 1), b3 + hstepB, voffB); PG8_STAGE(PG8_SA(1, 0), a3, voffA);
;             PG8_WAIT_V(8); PG8_WAIT_L(0); PG8_BAR; PG8_MMA(1, 0, At, B0); PG8_MMA(1, 1, At, B1); PG8_BAR; PG8_SCHED;
;     ...
;         if constexpr (ALIGN_EPI) { if (wr == 0) PG8_BAR; }
;         if constexpr (!Epi::AFTER_DRAIN) { E(acc, cur, wr, wc, fr, fq); S.done(cur); }
	s_add_i32 s58, s83, s44
	v_lshl_add_u64 v[218:219], v[218:219], 0, s[18:19]
	s_mov_b32 m0, s58
	ds_read_b128 v[186:189], v172 offset:49152
	ds_read_b128 v[190:193], v172 offset:50176
	ds_read_b128 v[194:197], v172 offset:51200
	ds_read_b128 v[198:201], v172 offset:52224
	ds_read_b128 v[202:205], v172 offset:53248
	ds_read_b128 v[206:209], v172 offset:54272
	ds_read_b128 v[210:213], v172 offset:55296
	ds_read_b128 v[214:217], v172 offset:56320
	global_load_lds_dwordx4 v[218:219], off
	s_add_i32 m0, s58, 0x2000
	s_add_u32 s36, s36, 0x20080
	v_lshl_add_u64 v[218:219], v[220:221], 0, s[18:19]
	s_addc_u32 s37, s37, 0
	s_add_i32 s58, s84, s44
	global_load_lds_dwordx4 v[218:219], off
	v_lshl_add_u64 v[218:219], s[36:37], 0, v[148:149]
	s_mov_b32 m0, s58
	s_nop 0
	global_load_lds_dwordx4 v[218:219], off
	v_lshl_add_u64 v[218:219], s[36:37], 0, v[152:153]
	s_add_i32 m0, s58, 0x2000
	s_nop 0
	global_load_lds_dwordx4 v[218:219], off
	v_lshl_add_u64 v[218:219], v[222:223], 0, s[18:19]
	s_mov_b32 m0, s63
	s_nop 0
	global_load_lds_dwordx4 v[218:219], off
	v_lshl_add_u64 v[218:219], v[224:225], 0, s[18:19]
	s_mov_b32 m0, s66
	s_nop 0
	global_load_lds_dwordx4 v[218:219], off
	s_waitcnt vmcnt(8)
	s_waitcnt lgkmcnt(0)
	s_barrier
	s_setprio 3
	s_waitcnt lgkmcnt(0)
	v_mfma_f32_16x16x32_bf16 v[62:65], v[130:133], v[186:189], v[62:65]
	v_mfma_f32_16x16x32_bf16 v[58:61], v[138:141], v[186:189], v[58:61]
	v_mfma_f32_16x16x32_bf16 v[54:57], v[130:133], v[194:197], v[54:57]
	v_mfma_f32_16x16x32_bf16 v[46:49], v[138:141], v[194:197], v[46:49]
	v_mfma_f32_16x16x32_bf16 v[38:41], v[130:133], v[202:205], v[38:41]
	v_mfma_f32_16x16x32_bf16 v[30:33], v[138:141], v[202:205], v[30:33]
	v_mfma_f32_16x16x32_bf16 v[22:25], v[130:133], v[210:213], v[22:25]
	v_mfma_f32_16x16x32_bf16 v[14:17], v[138:141], v[210:213], v[14:17]
	v_mfma_f32_16x16x32_bf16 v[62:65], v[134:137], v[190:193], v[62:65]
	v_mfma_f32_16x16x32_bf16 v[58:61], v[142:145], v[190:193], v[58:61]
	v_mfma_f32_16x16x32_bf16 v[54:57], v[134:137], v[198:201], v[54:57]
	v_mfma_f32_16x16x32_bf16 v[46:49], v[142:145], v[198:201], v[46:49]
	v_mfma_f32_16x16x32_bf16 v[38:41], v[134:137], v[206:209], v[38:41]
	v_mfma_f32_16x16x32_bf16 v[30:33], v[142:145], v[206:209], v[30:33]
	v_mfma_f32_16x16x32_bf16 v[22:25], v[134:137], v[214:217], v[22:25]
	v_mfma_f32_16x16x32_bf16 v[14:17], v[142:145], v[214:217], v[14:17]
	s_setprio 0
	s_setprio 3
	v_mfma_f32_16x16x32_bf16 v[50:53], v[164:167], v[186:189], v[50:53]
	v_mfma_f32_16x16x32_bf16 v[42:45], v[178:181], v[186:189], v[42:45]
	v_mfma_f32_16x16x32_bf16 v[34:37], v[164:167], v[194:197], v[34:37]
	v_mfma_f32_16x16x32_bf16 v[26:29], v[178:181], v[194:197], v[26:29]
	v_mfma_f32_16x16x32_bf16 v[18:21], v[164:167], v[202:205], v[18:21]
	v_mfma_f32_16x16x32_bf16 v[10:13], v[178:181], v[202:205], v[10:13]
	v_mfma_f32_16x16x32_bf16 v[6:9], v[164:167], v[210:213], v[6:9]
	v_mfma_f32_16x16x32_bf16 v[2:5], v[178:181], v[210:213], v[2:5]
	v_mfma_f32_16x16x32_bf16 v[50:53], v[174:177], v[190:193], v[50:53]
	v_mfma_f32_16x16x32_bf16 v[42:45], v[182:185], v[190:193], v[42:45]
	v_mfma_f32_16x16x32_bf16 v[34:37], v[174:177], v[198:201], v[34:37]
	v_mfma_f32_16x16x32_bf16 v[26:29], v[182:185], v[198:201], v[26:29]
	v_mfma_f32_16x16x32_bf16 v[18:21], v[174:177], v[206:209], v[18:21]
	v_mfma_f32_16x16x32_bf16 v[10:13], v[182:185], v[206:209], v[10:13]
	v_mfma_f32_16x16x32_bf16 v[6:9], v[174:177], v[214:217], v[6:9]
	v_mfma_f32_16x16x32_bf16 v[2:5], v[182:185], v[214:217], v[2:5]
	s_setprio 0
	s_barrier
	s_add_i32 s79, s79, 2
	s_add_u32 s6, s6, 0x100
	s_addc_u32 s7, s7, 0
	s_add_u32 s77, s77, 0x100
	s_addc_u32 s78, s78, 0
	s_cmp_gt_u32 s79, 5
	s_cbranch_scc0 .LBB0_478
	s_and_b64 vcc, exec, s[20:21]
	s_cbranch_vccz .LBB0_481
	s_barrier

; #define PG8_STAGE(bufoff, gbase, voff) do { _Pragma("unroll") for (int _i = 0; _i < 2; ++_i) \
;         __builtin_amdgcn_global_load_lds((const unsigned*)((const char*)(gbase) + (voff)[_i]), (PG8_LAS unsigned*)(lds + (bufoff) + ldsw + _i * 8192), 16, 0, 0); } while (0)
; #define PG8_LDA(dst, b, h) do { _Pragma("unroll") for (int m = 0; m < 4; ++m) _Pragma("unroll") for (int k = 0; k < 2; ++k) dst[m][k] = *(const PG8_LAS bf16x8*)(lds + PG8_SA(b, h) + aoff + m * 2048 + k * 1024); } while (0)
; #define PG8_LDB(dst, b, h) do { _Pragma("unroll") for (int n = 0; n < 2; ++n) _Pragma("unroll") for (int k = 0; k < 2; ++k) dst[n][k] = *(const PG8_LAS bf16x8*)(lds + PG8_SB(b, h) + boff + n * 2048 + k * 1024); } while (0)
; #define PG8_MMA(ai, bj, At, Bt) do { __builtin_amdgcn_s_setprio(3); _Pragma("unroll") for (int m = 0; m < 4; ++m) _Pragma("unroll") for (int n = 0; n < 2; ++n) _Pragma("unroll") for (int k = 0; k < 2; ++k) \
;         acc[ai][bj][m][n] = __builtin_amdgcn_mfma_f32_16x16x32_bf16(Bt[n][k], At[m][k], acc[ai][bj][m][n], 0, 0, 0); __builtin_amdgcn_s_setprio(0); } while (0)
; #define PG8_WAIT_V(n) asm volatile("s_waitcnt vmcnt(" #n ")" ::: "memory")
; #define PG8_WAIT_L(n) asm volatile("s_waitcnt lgkmcnt(" #n ")" ::: "memory")
; template <class Epi, class Sched, bool ALIGN_EPI = false, bool SP2 = false>
; __device__ __forceinline__ void gemm_phase(PG8_LAS unsigned char* lds, const Gemm g, const Sched& S, const Epi& E) {
;     ...
;         for (int t = 0; t < nt; t += 2) {
;             const bool last = (t == nt - 2);
;             const char* a1 = cA + (size_t)(t + 1) * kstep;
;             const char* a2 = last ? nA : cA + (size_t)(t + 2) * kstep; const char* b2 = last ? nB : cB + (size_t)(t + 2) * kstep;
;             const char* a3 = a2 + kstep; const char* b3 = b2 + kstep;
;             if (last && has_next) S.a_ready(nxt);
;             if constexpr (Epi::MIDK) { if (t == E.midk_step(nt)) E.midk(acc, cur, wr, wc, fr, fq); }
;             if constexpr (SP2) {
;             PG8_LDB(B0, 0, 0); PG8_LDB(B1, 0, 1); PG8_SCHED; PG8_LDA(At, 0, 0); PG8_STAGE(PG8_SA(1, 1), a1 + hstepA, voffA);
;             PG8_WAIT_V(8); PG8_WAIT_L(0); PG8_BAR; PG8_MMA(0, 0, At, B0); PG8_MMA(0, 1, At, B1); PG8_BAR; PG8_SCHED;
;             PG8_LDA(At, 0, 1); PG8_STAGE(PG8_SB(0, 0), b2, voffB); PG8_STAGE(PG8_SB(0, 1), b2 + hstepB, voffB); PG8_STAGE(PG8_SA(0, 0), a2, voffA);
.LBB0_727:
	v_add_u32_e32 v160, s66, v157
	ds_read_b128 v[130:133], v160
	ds_read_b128 v[164:167], v160 offset:1024
	ds_read_b128 v[168:171], v160 offset:2048
	ds_read_b128 v[172:175], v160 offset:3072
	v_add_u32_e32 v160, s67, v157
	s_add_u32 s0, s28, s30
	ds_read_b128 v[176:179], v160
	ds_read_b128 v[180:183], v160 offset:1024
	ds_read_b128 v[184:187], v160 offset:2048
	ds_read_b128 v[188:191], v160 offset:3072
	s_addc_u32 s1, s29, s31
	s_add_u32 s0, s0, 0x100
	s_addc_u32 s1, s1, 0
	s_add_u32 s84, s79, s30
	s_addc_u32 s85, s81, s31
	s_cmpk_eq_i32 s30, 0x1f00
	s_cselect_b32 s37, s23, s1
	s_cselect_b32 s36, s72, s0
	s_cselect_b32 s1, s75, s85
	s_cselect_b32 s0, s76, s84
	v_lshl_add_u64 v[160:161], v[150:151], 0, s[30:31]
	s_add_i32 m0, s44, 0xc000
	ds_read_b128 v[192:195], v159
	ds_read_b128 v[196:199], v159 offset:1024
	ds_read_b128 v[200:203], v159 offset:2048
	ds_read_b128 v[204:207], v159 offset:3072
	ds_read_b128 v[208:211], v159 offset:4096
	ds_read_b128 v[212:215], v159 offset:5120
	ds_read_b128 v[216:219], v159 offset:6144
	ds_read_b128 v[220:223], v159 offset:7168
	global_load_lds_dwordx4 v[160:161], off
	v_lshl_add_u64 v[160:161], v[152:153], 0, s[30:31]
	s_add_i32 m0, s44, 0xe000
	s_nop 0
	global_load_lds_dwordx4 v[160:161], off
	s_waitcnt vmcnt(8)
	s_waitcnt lgkmcnt(0)
	s_barrier
	s_setprio 3
	s_waitcnt lgkmcnt(0)
	v_mfma_f32_16x16x32_bf16 v[126:129], v[130:133], v[192:195], v[126:129]
	v_mfma_f32_16x16x32_bf16 v[122:125], v[168:171], v[192:195], v[122:125]
	v_mfma_f32_16x16x32_bf16 v[110:113], v[130:133], v[200:203], v[110:113]
	v_mfma_f32_16x16x32_bf16 v[106:109], v[168:171], v[200:203], v[106:109]
	v_mfma_f32_16x16x32_bf16 v[94:97], v[130:133], v[208:211], v[94:97]
	v_mfma_f32_16x16x32_bf16 v[90:93], v[168:171], v[208:211], v[90:93]
	v_mfma_f32_16x16x32_bf16 v[78:81], v[130:133], v[216:219], v[78:81]
	v_mfma_f32_16x16x32_bf16 v[74:77], v[168:171], v[216:219], v[74:77]
	v_mfma_f32_16x16x32_bf16 v[126:129], v[164:167], v[196:199], v[126:129]
	v_mfma_f32_16x16x32_bf16 v[122:125], v[172:175], v[196:199], v[122:125]
	v_mfma_f32_16x16x32_bf16 v[110:113], v[164:167], v[204:207], v[110:113]
	v_mfma_f32_16x16x32_bf16 v[106:109], v[172:175], v[204:207], v[106:109]
	v_mfma_f32_16x16x32_bf16 v[94:97], v[164:167], v[212:215], v[94:97]
	v_mfma_f32_16x16x32_bf16 v[90:93], v[172:175], v[212:215], v[90:93]
	v_mfma_f32_16x16x32_bf16 v[78:81], v[164:167], v[220:223], v[78:81]
	v_mfma_f32_16x16x32_bf16 v[74:77], v[172:175], v[220:223], v[74:77]
	s_setprio 0
	s_setprio 3
	v_mfma_f32_16x16x32_bf16 v[118:121], v[176:179], v[192:195], v[118:121]
	v_mfma_f32_16x16x32_bf16 v[114:117], v[184:187], v[192:195], v[114:117]
	v_mfma_f32_16x16x32_bf16 v[102:105], v[176:179], v[200:203], v[102:105]
	v_mfma_f32_16x16x32_bf16 v[98:101], v[184:187], v[200:203], v[98:101]
	v_mfma_f32_16x16x32_bf16 v[86:89], v[176:179], v[208:211], v[86:89]
	v_mfma_f32_16x16x32_bf16 v[82:85], v[184:187], v[208:211], v[82:85]
	v_mfma_f32_16x16x32_bf16 v[70:73], v[176:179], v[216:219], v[70:73]
	v_mfma_f32_16x16x32_bf16 v[66:69], v[184:187], v[216:219], v[66:69]
	v_mfma_f32_16x16x32_bf16 v[118:121], v[180:183], v[196:199], v[118:121]
	v_mfma_f32_16x16x32_bf16 v[114:117], v[188:191], v[196:199], v[114:117]
	v_mfma_f32_16x16x32_bf16 v[102:105], v[180:183], v[204:207], v[102:105]
	v_mfma_f32_16x16x32_bf16 v[98:101], v[188:191], v[204:207], v[98:101]
	v_mfma_f32_16x16x32_bf16 v[86:89], v[180:183], v[212:215], v[86:89]
	v_mfma_f32_16x16x32_bf16 v[82:85], v[188:191], v[212:215], v[82:85]
	v_mfma_f32_16x16x32_bf16 v[70:73], v[180:183], v[220:223], v[70:73]
	v_mfma_f32_16x16x32_bf16 v[66:69], v[188:191], v[220:223], v[66:69]
	s_setprio 0
	s_barrier
	s_add_i32 s84, s66, s33
	v_lshl_add_u64 v[160:161], s[0:1], 0, v[136:137]
	s_mov_b32 m0, s84
	ds_read_b128 v[192:195], v159 offset:16384
	ds_read_b128 v[196:199], v159 offset:17408
	ds_read_b128 v[200:203], v159 offset:18432
	ds_read_b128 v[204:207], v159 offset:19456
	ds_read_b128 v[208:211], v159 offset:20480
	ds_read_b128 v[212:215], v159 offset:21504
	ds_read_b128 v[216:219], v159 offset:22528
	ds_read_b128 v[220:223], v159 offset:23552
	global_load_lds_dwordx4 v[160:161], off
	s_add_i32 m0, s84, 0x2000
	s_add_u32 s84, s0, 0x100000
	v_lshl_add_u64 v[224:225], s[0:1], 0, v[140:141]
	s_addc_u32 s85, s1, 0
	s_add_i32 s86, s67, s33
	global_load_lds_dwordx4 v[224:225], off
	v_lshl_add_u64 v[226:227], s[84:85], 0, v[136:137]
	s_mov_b32 m0, s86
	v_lshl_add_u64 v[228:229], s[36:37], 0, v[138:139]
	global_load_lds_dwordx4 v[226:227], off
	v_lshl_add_u64 v[226:227], s[84:85], 0, v[140:141]
	s_add_i32 m0, s86, 0x2000
	s_nop 0
	global_load_lds_dwordx4 v[226:227], off
	v_lshl_add_u64 v[226:227], s[36:37], 0, v[134:135]
	s_waitcnt vmcnt(6)
	s_waitcnt lgkmcnt(0)
	s_barrier
; #define PG8_STAGE(bufoff, gbase, voff) do { _Pragma("unroll") for (int _i = 0; _i < 2; ++_i) \
;         __builtin_amdgcn_global_load_lds((const unsigned*)((const char*)(gbase) + (voff)[_i]), (PG8_LAS unsigned*)(lds + (bufoff) + ldsw + _i * 8192), 16, 0, 0); } while (0)
; #define PG8_LDA(dst, b, h) do { _Pragma("unroll") for (int m = 0; m < 4; ++m) _Pragma("unroll") for (int k = 0; k < 2; ++k) dst[m][k] = *(const PG8_LAS bf16x8*)(lds + PG8_SA(b, h) + aoff + m * 2048 + k * 1024); } while (0)
; #define PG8_LDB(dst, b, h) do { _Pragma("unroll") for (int n = 0; n < 2; ++n) _Pragma("unroll") for (int k = 0; k < 2; ++k) dst[n][k] = *(const PG8_LAS bf16x8*)(lds + PG8_SB(b, h) + boff + n * 2048 + k * 1024); } while (0)
; #define PG8_MMA(ai, bj, At, Bt) do { __builtin_amdgcn_s_setprio(3); _Pragma("unroll") for (int m = 0; m < 4; ++m) _Pragma("unroll") for (int n = 0; n < 2; ++n) _Pragma("unroll") for (int k = 0; k < 2; ++k) \
;         acc[ai][bj][m][n] = __builtin_amdgcn_mfma_f32_16x16x32_bf16(Bt[n][k], At[m][k], acc[ai][bj][m][n], 0, 0, 0); __builtin_amdgcn_s_setprio(0); } while (0)
; #define PG8_WAIT_V(n) asm volatile("s_waitcnt vmcnt(" #n ")" ::: "memory")
; #define PG8_WAIT_L(n) asm volatile("s_waitcnt lgkmcnt(" #n ")" ::: "memory")
; #define PG8_BAR __builtin_amdgcn_s_barrier()
; #define PG8_SCHED __builtin_amdgcn_sched_barrier(0)
; template <class Epi, class Sched, bool ALIGN_EPI = false, bool SP2 = false>
; __device__ __forceinline__ void gemm_phase(PG8_LAS unsigned char* lds, const Gemm g, const Sched& S, const Epi& E) {
;     ...
;             PG8_WAIT_V(8); PG8_WAIT_L(0); PG8_BAR; PG8_MMA(0, 0, At, B0); PG8_MMA(0, 1, At, B1); PG8_BAR; PG8_SCHED;
;             PG8_LDA(At, 0, 1); PG8_STAGE(PG8_SB(0, 0), b2, voffB); PG8_STAGE(PG8_SB(0, 1), b2 + hstepB, voffB); PG8_STAGE(PG8_SA(0, 0), a2, voffA);
;             PG8_WAIT_V(8); PG8_WAIT_L(0); PG8_BAR; PG8_MMA(1, 0, At, B0); PG8_MMA(1, 1, At, B1); PG8_BAR; PG8_SCHED;
;             PG8_LDB(B0, 1, 0); PG8_LDB(B1, 1, 1); PG8_SCHED; PG8_LDA(At, 1, 0); PG8_STAGE(PG8_SA(0, 1), a2 + hstepA, voffA);
;             PG8_WAIT_V(8); PG8_WAIT_L(0); PG8_BAR; PG8_MMA(0, 0, At, B0); PG8_MMA(0, 1, At, B1); PG8_BAR; PG8_SCHED;
	s_setprio 3
	s_waitcnt lgkmcnt(0)
	v_mfma_f32_16x16x32_bf16 v[62:65], v[130:133], v[192:195], v[62:65]
	v_mfma_f32_16x16x32_bf16 v[58:61], v[168:171], v[192:195], v[58:61]
	v_mfma_f32_16x16x32_bf16 v[46:49], v[130:133], v[200:203], v[46:49]
	v_mfma_f32_16x16x32_bf16 v[42:45], v[168:171], v[200:203], v[42:45]
	v_mfma_f32_16x16x32_bf16 v[30:33], v[130:133], v[208:211], v[30:33]
	v_mfma_f32_16x16x32_bf16 v[26:29], v[168:171], v[208:211], v[26:29]
	v_mfma_f32_16x16x32_bf16 v[14:17], v[130:133], v[216:219], v[14:17]
	v_mfma_f32_16x16x32_bf16 v[10:13], v[168:171], v[216:219], v[10:13]
	v_mfma_f32_16x16x32_bf16 v[62:65], v[164:167], v[196:199], v[62:65]
	v_mfma_f32_16x16x32_bf16 v[58:61], v[172:175], v[196:199], v[58:61]
	v_mfma_f32_16x16x32_bf16 v[46:49], v[164:167], v[204:207], v[46:49]
	v_mfma_f32_16x16x32_bf16 v[42:45], v[172:175], v[204:207], v[42:45]
	v_mfma_f32_16x16x32_bf16 v[30:33], v[164:167], v[212:215], v[30:33]
	v_mfma_f32_16x16x32_bf16 v[26:29], v[172:175], v[212:215], v[26:29]
	v_mfma_f32_16x16x32_bf16 v[14:17], v[164:167], v[220:223], v[14:17]
	v_mfma_f32_16x16x32_bf16 v[10:13], v[172:175], v[220:223], v[10:13]
	s_setprio 0
	s_setprio 3
	v_mfma_f32_16x16x32_bf16 v[54:57], v[176:179], v[192:195], v[54:57]
	v_mfma_f32_16x16x32_bf16 v[50:53], v[184:187], v[192:195], v[50:53]
	v_mfma_f32_16x16x32_bf16 v[38:41], v[176:179], v[200:203], v[38:41]
	v_mfma_f32_16x16x32_bf16 v[34:37], v[184:187], v[200:203], v[34:37]
	v_mfma_f32_16x16x32_bf16 v[22:25], v[176:179], v[208:211], v[22:25]
	v_mfma_f32_16x16x32_bf16 v[18:21], v[184:187], v[208:211], v[18:21]
	v_mfma_f32_16x16x32_bf16 v[6:9], v[176:179], v[216:219], v[6:9]
	v_mfma_f32_16x16x32_bf16 v[2:5], v[184:187], v[216:219], v[2:5]
	v_mfma_f32_16x16x32_bf16 v[54:57], v[180:183], v[196:199], v[54:57]
	v_mfma_f32_16x16x32_bf16 v[50:53], v[188:191], v[196:199], v[50:53]
	v_mfma_f32_16x16x32_bf16 v[38:41], v[180:183], v[204:207], v[38:41]
	v_mfma_f32_16x16x32_bf16 v[34:37], v[188:191], v[204:207], v[34:37]
	v_mfma_f32_16x16x32_bf16 v[22:25], v[180:183], v[212:215], v[22:25]
	v_mfma_f32_16x16x32_bf16 v[18:21], v[188:191], v[212:215], v[18:21]
	v_mfma_f32_16x16x32_bf16 v[6:9], v[180:183], v[220:223], v[6:9]
	v_mfma_f32_16x16x32_bf16 v[2:5], v[188:191], v[220:223], v[2:5]
	s_setprio 0
	s_barrier
	s_add_i32 s84, 0, 0x18000
	v_add_u32_e32 v163, s84, v157
	s_add_i32 s85, 0, 0x1c000
	ds_read_b128 v[130:133], v163
	ds_read_b128 v[164:167], v163 offset:1024
	ds_read_b128 v[168:171], v163 offset:2048
	ds_read_b128 v[172:175], v163 offset:3072
	v_add_u32_e32 v163, s85, v157
	ds_read_b128 v[176:179], v163
	ds_read_b128 v[180:183], v163 offset:1024
	ds_read_b128 v[184:187], v163 offset:2048
	ds_read_b128 v[188:191], v163 offset:3072
	s_add_u32 s36, s36, 0x100000
	s_addc_u32 s37, s37, 0
	s_mov_b32 m0, s54
	v_lshl_add_u64 v[230:231], s[36:37], 0, v[134:135]
	ds_read_b128 v[192:195], v159 offset:32768
	ds_read_b128 v[196:199], v159 offset:33792
	ds_read_b128 v[200:203], v159 offset:34816
	ds_read_b128 v[204:207], v159 offset:35840
	ds_read_b128 v[208:211], v159 offset:36864
	ds_read_b128 v[212:215], v159 offset:37888
	ds_read_b128 v[216:219], v159 offset:38912
	ds_read_b128 v[220:223], v159 offset:39936
	s_mov_b32 m0, s44
	s_nop 0
	global_load_lds_dwordx4 v[226:227], off
	s_mov_b32 m0, s45
	s_nop 0
	global_load_lds_dwordx4 v[228:229], off
	s_mov_b32 m0, s54
	s_nop 0
	global_load_lds_dwordx4 v[230:231], off
	v_lshl_add_u64 v[230:231], s[36:37], 0, v[138:139]
	s_mov_b32 m0, s55
	s_nop 0
	global_load_lds_dwordx4 v[230:231], off
	s_waitcnt vmcnt(8)
	s_waitcnt lgkmcnt(0)
	s_barrier
	s_setprio 3
	s_waitcnt lgkmcnt(0)
	v_mfma_f32_16x16x32_bf16 v[126:129], v[130:133], v[192:195], v[126:129]
	v_mfma_f32_16x16x32_bf16 v[122:125], v[168:171], v[192:195], v[122:125]
	v_mfma_f32_16x16x32_bf16 v[110:113], v[130:133], v[200:203], v[110:113]
	v_mfma_f32_16x16x32_bf16 v[106:109], v[168:171], v[200:203], v[106:109]
	v_mfma_f32_16x16x32_bf16 v[94:97], v[130:133], v[208:211], v[94:97]
	v_mfma_f32_16x16x32_bf16 v[90:93], v[168:171], v[208:211], v[90:93]
	v_mfma_f32_16x16x32_bf16 v[78:81], v[130:133], v[216:219], v[78:81]
	v_mfma_f32_16x16x32_bf16 v[74:77], v[168:171], v[216:219], v[74:77]
	v_mfma_f32_16x16x32_bf16 v[126:129], v[164:167], v[196:199], v[126:129]
	v_mfma_f32_16x16x32_bf16 v[122:125], v[172:175], v[196:199], v[122:125]
	v_mfma_f32_16x16x32_bf16 v[110:113], v[164:167], v[204:207], v[110:113]
	v_mfma_f32_16x16x32_bf16 v[106:109], v[172:175], v[204:207], v[106:109]
	v_mfma_f32_16x16x32_bf16 v[94:97], v[164:167], v[212:215], v[94:97]
	v_mfma_f32_16x16x32_bf16 v[90:93], v[172:175], v[212:215], v[90:93]
	v_mfma_f32_16x16x32_bf16 v[78:81], v[164:167], v[220:223], v[78:81]
	v_mfma_f32_16x16x32_bf16 v[74:77], v[172:175], v[220:223], v[74:77]
	s_setprio 0
	s_setprio 3
	v_mfma_f32_16x16x32_bf16 v[118:121], v[176:179], v[192:195], v[118:121]
	v_mfma_f32_16x16x32_bf16 v[114:117], v[184:187], v[192:195], v[114:117]
	v_mfma_f32_16x16x32_bf16 v[102:105], v[176:179], v[200:203], v[102:105]
	v_mfma_f32_16x16x32_bf16 v[98:101], v[184:187], v[200:203], v[98:101]
	v_mfma_f32_16x16x32_bf16 v[86:89], v[176:179], v[208:211], v[86:89]
	v_mfma_f32_16x16x32_bf16 v[82:85], v[184:187], v[208:211], v[82:85]
	v_mfma_f32_16x16x32_bf16 v[70:73], v[176:179], v[216:219], v[70:73]
	v_mfma_f32_16x16x32_bf16 v[66:69], v[184:187], v[216:219], v[66:69]
	v_mfma_f32_16x16x32_bf16 v[118:121], v[180:183], v[196:199], v[118:121]
	v_mfma_f32_16x16x32_bf16 v[114:117], v[188:191], v[196:199], v[114:117]
	v_mfma_f32_16x16x32_bf16 v[102:105], v[180:183], v[204:207], v[102:105]
	v_mfma_f32_16x16x32_bf16 v[98:101], v[188:191], v[204:207], v[98:101]
	v_mfma_f32_16x16x32_bf16 v[86:89], v[180:183], v[212:215], v[86:89]
	v_mfma_f32_16x16x32_bf16 v[82:85], v[188:191], v[212:215], v[82:85]
	v_mfma_f32_16x16x32_bf16 v[70:73], v[180:183], v[220:223], v[70:73]
	v_mfma_f32_16x16x32_bf16 v[66:69], v[188:191], v[220:223], v[66:69]
	s_setprio 0
	s_barrier
; #define PG8_STAGE(bufoff, gbase, voff) do { _Pragma("unroll") for (int _i = 0; _i < 2; ++_i) \
;         __builtin_amdgcn_global_load_lds((const unsigned*)((const char*)(gbase) + (voff)[_i]), (PG8_LAS unsigned*)(lds + (bufoff) + ldsw + _i * 8192), 16, 0, 0); } while (0)
; #define PG8_LDA(dst, b, h) do { _Pragma("unroll") for (int m = 0; m < 4; ++m) _Pragma("unroll") for (int k = 0; k < 2; ++k) dst[m][k] = *(const PG8_LAS bf16x8*)(lds + PG8_SA(b, h) + aoff + m * 2048 + k * 1024); } while (0)
; #define PG8_MMA(ai, bj, At, Bt) do { __builtin_amdgcn_s_setprio(3); _Pragma("unroll") for (int m = 0; m < 4; ++m) _Pragma("unroll") for (int n = 0; n < 2; ++n) _Pragma("unroll") for (int k = 0; k < 2; ++k) \
;         acc[ai][bj][m][n] = __builtin_amdgcn_mfma_f32_16x16x32_bf16(Bt[n][k], At[m][k], acc[ai][bj][m][n], 0, 0, 0); __builtin_amdgcn_s_setprio(0); } while (0)
; #define PG8_WAIT_V(n) asm volatile("s_waitcnt vmcnt(" #n ")" ::: "memory")
; #define PG8_WAIT_L(n) asm volatile("s_waitcnt lgkmcnt(" #n ")" ::: "memory")
; #define PG8_BAR __builtin_amdgcn_s_barrier()
; #define PG8_SCHED __builtin_amdgcn_sched_barrier(0)
; template <class Epi, class Sched, bool ALIGN_EPI = false, bool SP2 = false>
; __device__ __forceinline__ void gemm_phase(PG8_LAS unsigned char* lds, const Gemm g, const Sched& S, const Epi& E) {
;     ...
;             PG8_LDA(At, 1, 1); PG8_STAGE(PG8_SB(1, 0), b3, voffB); PG8_STAGE(PG8_SB(1, 1), b3 + hstepB, voffB); PG8_STAGE(PG8_SA(1, 0), a3, voffA);
;             PG8_WAIT_V(8); PG8_WAIT_L(0); PG8_BAR; PG8_MMA(1, 0, At, B0); PG8_MMA(1, 1, At, B1); PG8_BAR; PG8_SCHED;
	s_add_i32 s36, s84, s33
	v_lshl_add_u64 v[160:161], v[160:161], 0, s[10:11]
	s_mov_b32 m0, s36
	ds_read_b128 v[192:195], v159 offset:49152
	ds_read_b128 v[196:199], v159 offset:50176
	ds_read_b128 v[200:203], v159 offset:51200
	ds_read_b128 v[204:207], v159 offset:52224
	ds_read_b128 v[208:211], v159 offset:53248
	ds_read_b128 v[212:215], v159 offset:54272
	ds_read_b128 v[216:219], v159 offset:55296
	ds_read_b128 v[220:223], v159 offset:56320
	global_load_lds_dwordx4 v[160:161], off
	s_add_i32 m0, s36, 0x2000
	s_add_u32 s0, s0, 0x100080
	v_lshl_add_u64 v[160:161], v[224:225], 0, s[10:11]
	s_addc_u32 s1, s1, 0
	s_add_i32 s36, s85, s33
	global_load_lds_dwordx4 v[160:161], off
	v_lshl_add_u64 v[160:161], s[0:1], 0, v[136:137]
	s_mov_b32 m0, s36
	s_nop 0
	global_load_lds_dwordx4 v[160:161], off
	v_lshl_add_u64 v[160:161], s[0:1], 0, v[140:141]
	s_add_i32 m0, s36, 0x2000
	s_nop 0
	global_load_lds_dwordx4 v[160:161], off
	v_lshl_add_u64 v[160:161], v[226:227], 0, s[10:11]
	s_mov_b32 m0, s61
	s_nop 0
	global_load_lds_dwordx4 v[160:161], off
	v_lshl_add_u64 v[160:161], v[228:229], 0, s[10:11]
	s_mov_b32 m0, s62
	s_nop 0
	global_load_lds_dwordx4 v[160:161], off
	s_waitcnt vmcnt(8)
	s_waitcnt lgkmcnt(0)
	s_barrier
	s_setprio 3
	s_waitcnt lgkmcnt(0)
	v_mfma_f32_16x16x32_bf16 v[62:65], v[130:133], v[192:195], v[62:65]
	v_mfma_f32_16x16x32_bf16 v[58:61], v[168:171], v[192:195], v[58:61]
	v_mfma_f32_16x16x32_bf16 v[46:49], v[130:133], v[200:203], v[46:49]
	v_mfma_f32_16x16x32_bf16 v[42:45], v[168:171], v[200:203], v[42:45]
	v_mfma_f32_16x16x32_bf16 v[30:33], v[130:133], v[208:211], v[30:33]
	v_mfma_f32_16x16x32_bf16 v[26:29], v[168:171], v[208:211], v[26:29]
	v_mfma_f32_16x16x32_bf16 v[14:17], v[130:133], v[216:219], v[14:17]
	v_mfma_f32_16x16x32_bf16 v[10:13], v[168:171], v[216:219], v[10:13]
	v_mfma_f32_16x16x32_bf16 v[62:65], v[164:167], v[196:199], v[62:65]
	v_mfma_f32_16x16x32_bf16 v[58:61], v[172:175], v[196:199], v[58:61]
	v_mfma_f32_16x16x32_bf16 v[46:49], v[164:167], v[204:207], v[46:49]
	v_mfma_f32_16x16x32_bf16 v[42:45], v[172:175], v[204:207], v[42:45]
	v_mfma_f32_16x16x32_bf16 v[30:33], v[164:167], v[212:215], v[30:33]
	v_mfma_f32_16x16x32_bf16 v[26:29], v[172:175], v[212:215], v[26:29]
	v_mfma_f32_16x16x32_bf16 v[14:17], v[164:167], v[220:223], v[14:17]
	v_mfma_f32_16x16x32_bf16 v[10:13], v[172:175], v[220:223], v[10:13]
	s_setprio 0
	s_setprio 3
	v_mfma_f32_16x16x32_bf16 v[54:57], v[176:179], v[192:195], v[54:57]
	v_mfma_f32_16x16x32_bf16 v[50:53], v[184:187], v[192:195], v[50:53]
	v_mfma_f32_16x16x32_bf16 v[38:41], v[176:179], v[200:203], v[38:41]
	v_mfma_f32_16x16x32_bf16 v[34:37], v[184:187], v[200:203], v[34:37]
	v_mfma_f32_16x16x32_bf16 v[22:25], v[176:179], v[208:211], v[22:25]
	v_mfma_f32_16x16x32_bf16 v[18:21], v[184:187], v[208:211], v[18:21]
	v_mfma_f32_16x16x32_bf16 v[6:9], v[176:179], v[216:219], v[6:9]
	v_mfma_f32_16x16x32_bf16 v[2:5], v[184:187], v[216:219], v[2:5]
	v_mfma_f32_16x16x32_bf16 v[54:57], v[180:183], v[196:199], v[54:57]
	v_mfma_f32_16x16x32_bf16 v[50:53], v[188:191], v[196:199], v[50:53]
	v_mfma_f32_16x16x32_bf16 v[38:41], v[180:183], v[204:207], v[38:41]
	v_mfma_f32_16x16x32_bf16 v[34:37], v[188:191], v[204:207], v[34:37]
	v_mfma_f32_16x16x32_bf16 v[22:25], v[180:183], v[212:215], v[22:25]
	v_mfma_f32_16x16x32_bf16 v[18:21], v[188:191], v[212:215], v[18:21]
	v_mfma_f32_16x16x32_bf16 v[6:9], v[180:183], v[220:223], v[6:9]
	v_mfma_f32_16x16x32_bf16 v[2:5], v[188:191], v[220:223], v[2:5]
	s_setprio 0
	s_barrier
	s_add_i32 s83, s83, 2
	s_add_u32 s30, s30, 0x100
	s_addc_u32 s31, s31, 0
	s_cmp_gt_u32 s83, 61
	s_cbranch_scc1 .LBB0_730

; #define PG8_STAGE(bufoff, gbase, voff) do { _Pragma("unroll") for (int _i = 0; _i < 2; ++_i) \
;         __builtin_amdgcn_global_load_lds((const unsigned*)((const char*)(gbase) + (voff)[_i]), (PG8_LAS unsigned*)(lds + (bufoff) + ldsw + _i * 8192), 16, 0, 0); } while (0)
; #define PG8_LDA(dst, b, h) do { _Pragma("unroll") for (int m = 0; m < 4; ++m) _Pragma("unroll") for (int k = 0; k < 2; ++k) dst[m][k] = *(const PG8_LAS bf16x8*)(lds + PG8_SA(b, h) + aoff + m * 2048 + k * 1024); } while (0)
; #define PG8_LDB(dst, b, h) do { _Pragma("unroll") for (int n = 0; n < 2; ++n) _Pragma("unroll") for (int k = 0; k < 2; ++k) dst[n][k] = *(const PG8_LAS bf16x8*)(lds + PG8_SB(b, h) + boff + n * 2048 + k * 1024); } while (0)
; #define PG8_MMA(ai, bj, At, Bt) do { __builtin_amdgcn_s_setprio(3); _Pragma("unroll") for (int m = 0; m < 4; ++m) _Pragma("unroll") for (int n = 0; n < 2; ++n) _Pragma("unroll") for (int k = 0; k < 2; ++k) \
;         acc[ai][bj][m][n] = __builtin_amdgcn_mfma_f32_16x16x32_bf16(Bt[n][k], At[m][k], acc[ai][bj][m][n], 0, 0, 0); __builtin_amdgcn_s_setprio(0); } while (0)
; #define PG8_WAIT_V(n) asm volatile("s_waitcnt vmcnt(" #n ")" ::: "memory")
; #define PG8_WAIT_L(n) asm volatile("s_waitcnt lgkmcnt(" #n ")" ::: "memory")
; template <class Epi, class Sched, bool ALIGN_EPI = false, bool SP2 = false>
; __device__ __forceinline__ void gemm_phase(PG8_LAS unsigned char* lds, const Gemm g, const Sched& S, const Epi& E) {
;     ...
;         for (int t = 0; t < nt; t += 2) {
;             const bool last = (t == nt - 2);
;             const char* a1 = cA + (size_t)(t + 1) * kstep;
;             const char* a2 = last ? nA : cA + (size_t)(t + 2) * kstep; const char* b2 = last ? nB : cB + (size_t)(t + 2) * kstep;
;             const char* a3 = a2 + kstep; const char* b3 = b2 + kstep;
;             if (last && has_next) S.a_ready(nxt);
;             if constexpr (Epi::MIDK) { if (t == E.midk_step(nt)) E.midk(acc, cur, wr, wc, fr, fq); }
;             if constexpr (SP2) {
;             PG8_LDB(B0, 0, 0); PG8_LDB(B1, 0, 1); PG8_SCHED; PG8_LDA(At, 0, 0); PG8_STAGE(PG8_SA(1, 1), a1 + hstepA, voffA);
;             PG8_WAIT_V(8); PG8_WAIT_L(0); PG8_BAR; PG8_MMA(0, 0, At, B0); PG8_MMA(0, 1, At, B1); PG8_BAR; PG8_SCHED;
;             PG8_LDA(At, 0, 1); PG8_STAGE(PG8_SB(0, 0), b2, voffB); PG8_STAGE(PG8_SB(0, 1), b2 + hstepB, voffB); PG8_STAGE(PG8_SA(0, 0), a2, voffA);
.LBB0_808:
	v_add_u32_e32 v3, s65, v186
	ds_read_b128 v[134:137], v3
	ds_read_b128 v[138:141], v3 offset:1024
	ds_read_b128 v[142:145], v3 offset:2048
	ds_read_b128 v[146:149], v3 offset:3072
	v_add_u32_e32 v3, s66, v186
	s_add_u32 s36, s28, s30
	ds_read_b128 v[150:153], v3
	ds_read_b128 v[154:157], v3 offset:1024
	ds_read_b128 v[158:161], v3 offset:2048
	ds_read_b128 v[190:193], v3 offset:3072
	s_addc_u32 s37, s29, s31
	s_add_u32 s36, s36, 0x100
	s_addc_u32 s37, s37, 0
	s_add_u32 s86, s83, s30
	s_addc_u32 s87, s84, s31
	s_cmpk_eq_i32 s30, 0x1f00
	s_cselect_b32 s41, s23, s37
	s_cselect_b32 s40, s75, s36
	s_cselect_b32 s37, s77, s87
	s_cselect_b32 s36, s78, s86
	v_lshl_add_u64 v[4:5], v[180:181], 0, s[30:31]
	s_add_i32 m0, s42, 0xc000
	ds_read_b128 v[194:197], v188
	ds_read_b128 v[198:201], v188 offset:1024
	ds_read_b128 v[202:205], v188 offset:2048
	ds_read_b128 v[206:209], v188 offset:3072
	ds_read_b128 v[210:213], v188 offset:4096
	ds_read_b128 v[214:217], v188 offset:5120
	ds_read_b128 v[218:221], v188 offset:6144
	ds_read_b128 v[222:225], v188 offset:7168
	global_load_lds_dwordx4 v[4:5], off
	v_lshl_add_u64 v[4:5], v[182:183], 0, s[30:31]
	s_add_i32 m0, s42, 0xe000
	s_nop 0
	global_load_lds_dwordx4 v[4:5], off
	s_waitcnt vmcnt(8)
	s_waitcnt lgkmcnt(0)
	s_barrier
	s_setprio 3
	s_waitcnt lgkmcnt(0)
	v_mfma_f32_16x16x32_bf16 v[130:133], v[134:137], v[194:197], v[130:133]
	v_mfma_f32_16x16x32_bf16 v[126:129], v[142:145], v[194:197], v[126:129]
	v_mfma_f32_16x16x32_bf16 v[114:117], v[134:137], v[202:205], v[114:117]
	v_mfma_f32_16x16x32_bf16 v[110:113], v[142:145], v[202:205], v[110:113]
	v_mfma_f32_16x16x32_bf16 v[98:101], v[134:137], v[210:213], v[98:101]
	v_mfma_f32_16x16x32_bf16 v[94:97], v[142:145], v[210:213], v[94:97]
	v_mfma_f32_16x16x32_bf16 v[82:85], v[134:137], v[218:221], v[82:85]
	v_mfma_f32_16x16x32_bf16 v[78:81], v[142:145], v[218:221], v[78:81]
	v_mfma_f32_16x16x32_bf16 v[130:133], v[138:141], v[198:201], v[130:133]
	v_mfma_f32_16x16x32_bf16 v[126:129], v[146:149], v[198:201], v[126:129]
	v_mfma_f32_16x16x32_bf16 v[114:117], v[138:141], v[206:209], v[114:117]
	v_mfma_f32_16x16x32_bf16 v[110:113], v[146:149], v[206:209], v[110:113]
	v_mfma_f32_16x16x32_bf16 v[98:101], v[138:141], v[214:217], v[98:101]
	v_mfma_f32_16x16x32_bf16 v[94:97], v[146:149], v[214:217], v[94:97]
	v_mfma_f32_16x16x32_bf16 v[82:85], v[138:141], v[222:225], v[82:85]
	v_mfma_f32_16x16x32_bf16 v[78:81], v[146:149], v[222:225], v[78:81]
	s_setprio 0
	s_setprio 3
	v_mfma_f32_16x16x32_bf16 v[122:125], v[150:153], v[194:197], v[122:125]
	v_mfma_f32_16x16x32_bf16 v[118:121], v[158:161], v[194:197], v[118:121]
	v_mfma_f32_16x16x32_bf16 v[106:109], v[150:153], v[202:205], v[106:109]
	v_mfma_f32_16x16x32_bf16 v[102:105], v[158:161], v[202:205], v[102:105]
	v_mfma_f32_16x16x32_bf16 v[90:93], v[150:153], v[210:213], v[90:93]
	v_mfma_f32_16x16x32_bf16 v[86:89], v[158:161], v[210:213], v[86:89]
	v_mfma_f32_16x16x32_bf16 v[74:77], v[150:153], v[218:221], v[74:77]
	v_mfma_f32_16x16x32_bf16 v[70:73], v[158:161], v[218:221], v[70:73]
	v_mfma_f32_16x16x32_bf16 v[122:125], v[154:157], v[198:201], v[122:125]
	v_mfma_f32_16x16x32_bf16 v[118:121], v[190:193], v[198:201], v[118:121]
	v_mfma_f32_16x16x32_bf16 v[106:109], v[154:157], v[206:209], v[106:109]
	v_mfma_f32_16x16x32_bf16 v[102:105], v[190:193], v[206:209], v[102:105]
	v_mfma_f32_16x16x32_bf16 v[90:93], v[154:157], v[214:217], v[90:93]
	v_mfma_f32_16x16x32_bf16 v[86:89], v[190:193], v[214:217], v[86:89]
	v_mfma_f32_16x16x32_bf16 v[74:77], v[154:157], v[222:225], v[74:77]
	v_mfma_f32_16x16x32_bf16 v[70:73], v[190:193], v[222:225], v[70:73]
	s_setprio 0
	s_barrier
	s_add_i32 s86, s65, s33
	v_lshl_add_u64 v[226:227], s[36:37], 0, v[166:167]
	s_mov_b32 m0, s86
	ds_read_b128 v[194:197], v188 offset:16384
	ds_read_b128 v[198:201], v188 offset:17408
	ds_read_b128 v[202:205], v188 offset:18432
	ds_read_b128 v[206:209], v188 offset:19456
	ds_read_b128 v[210:213], v188 offset:20480
	ds_read_b128 v[214:217], v188 offset:21504
	ds_read_b128 v[218:221], v188 offset:22528
	ds_read_b128 v[222:225], v188 offset:23552
	global_load_lds_dwordx4 v[226:227], off
	s_add_i32 m0, s86, 0x2000
	s_add_u32 s86, s36, 0x100000
	v_lshl_add_u64 v[228:229], s[36:37], 0, v[170:171]
	s_addc_u32 s87, s37, 0
	s_add_i32 s88, s66, s33
	global_load_lds_dwordx4 v[228:229], off
	v_lshl_add_u64 v[4:5], s[86:87], 0, v[166:167]
	s_mov_b32 m0, s88
	v_lshl_add_u64 v[230:231], s[40:41], 0, v[164:165]
	global_load_lds_dwordx4 v[4:5], off
	v_lshl_add_u64 v[4:5], s[86:87], 0, v[170:171]
	s_add_i32 m0, s88, 0x2000
	v_lshl_add_u64 v[232:233], s[40:41], 0, v[168:169]
	global_load_lds_dwordx4 v[4:5], off
	s_waitcnt vmcnt(6)
	s_waitcnt lgkmcnt(0)
	s_barrier
; #define PG8_STAGE(bufoff, gbase, voff) do { _Pragma("unroll") for (int _i = 0; _i < 2; ++_i) \
;         __builtin_amdgcn_global_load_lds((const unsigned*)((const char*)(gbase) + (voff)[_i]), (PG8_LAS unsigned*)(lds + (bufoff) + ldsw + _i * 8192), 16, 0, 0); } while (0)
; #define PG8_LDA(dst, b, h) do { _Pragma("unroll") for (int m = 0; m < 4; ++m) _Pragma("unroll") for (int k = 0; k < 2; ++k) dst[m][k] = *(const PG8_LAS bf16x8*)(lds + PG8_SA(b, h) + aoff + m * 2048 + k * 1024); } while (0)
; #define PG8_LDB(dst, b, h) do { _Pragma("unroll") for (int n = 0; n < 2; ++n) _Pragma("unroll") for (int k = 0; k < 2; ++k) dst[n][k] = *(const PG8_LAS bf16x8*)(lds + PG8_SB(b, h) + boff + n * 2048 + k * 1024); } while (0)
; #define PG8_MMA(ai, bj, At, Bt) do { __builtin_amdgcn_s_setprio(3); _Pragma("unroll") for (int m = 0; m < 4; ++m) _Pragma("unroll") for (int n = 0; n < 2; ++n) _Pragma("unroll") for (int k = 0; k < 2; ++k) \
;         acc[ai][bj][m][n] = __builtin_amdgcn_mfma_f32_16x16x32_bf16(Bt[n][k], At[m][k], acc[ai][bj][m][n], 0, 0, 0); __builtin_amdgcn_s_setprio(0); } while (0)
; #define PG8_WAIT_V(n) asm volatile("s_waitcnt vmcnt(" #n ")" ::: "memory")
; #define PG8_WAIT_L(n) asm volatile("s_waitcnt lgkmcnt(" #n ")" ::: "memory")
; #define PG8_BAR __builtin_amdgcn_s_barrier()
; #define PG8_SCHED __builtin_amdgcn_sched_barrier(0)
; template <class Epi, class Sched, bool ALIGN_EPI = false, bool SP2 = false>
; __device__ __forceinline__ void gemm_phase(PG8_LAS unsigned char* lds, const Gemm g, const Sched& S, const Epi& E) {
;     ...
;             PG8_WAIT_V(8); PG8_WAIT_L(0); PG8_BAR; PG8_MMA(0, 0, At, B0); PG8_MMA(0, 1, At, B1); PG8_BAR; PG8_SCHED;
;             PG8_LDA(At, 0, 1); PG8_STAGE(PG8_SB(0, 0), b2, voffB); PG8_STAGE(PG8_SB(0, 1), b2 + hstepB, voffB); PG8_STAGE(PG8_SA(0, 0), a2, voffA);
;             PG8_WAIT_V(8); PG8_WAIT_L(0); PG8_BAR; PG8_MMA(1, 0, At, B0); PG8_MMA(1, 1, At, B1); PG8_BAR; PG8_SCHED;
;             PG8_LDB(B0, 1, 0); PG8_LDB(B1, 1, 1); PG8_SCHED; PG8_LDA(At, 1, 0); PG8_STAGE(PG8_SA(0, 1), a2 + hstepA, voffA);
;             PG8_WAIT_V(8); PG8_WAIT_L(0); PG8_BAR; PG8_MMA(0, 0, At, B0); PG8_MMA(0, 1, At, B1); PG8_BAR; PG8_SCHED;
	s_setprio 3
	s_waitcnt lgkmcnt(0)
	v_mfma_f32_16x16x32_bf16 v[66:69], v[134:137], v[194:197], v[66:69]
	v_mfma_f32_16x16x32_bf16 v[62:65], v[142:145], v[194:197], v[62:65]
	v_mfma_f32_16x16x32_bf16 v[50:53], v[134:137], v[202:205], v[50:53]
	v_mfma_f32_16x16x32_bf16 v[46:49], v[142:145], v[202:205], v[46:49]
	v_mfma_f32_16x16x32_bf16 v[34:37], v[134:137], v[210:213], v[34:37]
	v_mfma_f32_16x16x32_bf16 v[30:33], v[142:145], v[210:213], v[30:33]
	v_mfma_f32_16x16x32_bf16 v[18:21], v[134:137], v[218:221], v[18:21]
	v_mfma_f32_16x16x32_bf16 v[14:17], v[142:145], v[218:221], v[14:17]
	v_mfma_f32_16x16x32_bf16 v[66:69], v[138:141], v[198:201], v[66:69]
	v_mfma_f32_16x16x32_bf16 v[62:65], v[146:149], v[198:201], v[62:65]
	v_mfma_f32_16x16x32_bf16 v[50:53], v[138:141], v[206:209], v[50:53]
	v_mfma_f32_16x16x32_bf16 v[46:49], v[146:149], v[206:209], v[46:49]
	v_mfma_f32_16x16x32_bf16 v[34:37], v[138:141], v[214:217], v[34:37]
	v_mfma_f32_16x16x32_bf16 v[30:33], v[146:149], v[214:217], v[30:33]
	v_mfma_f32_16x16x32_bf16 v[18:21], v[138:141], v[222:225], v[18:21]
	v_mfma_f32_16x16x32_bf16 v[14:17], v[146:149], v[222:225], v[14:17]
	s_setprio 0
	s_setprio 3
	v_mfma_f32_16x16x32_bf16 v[58:61], v[150:153], v[194:197], v[58:61]
	v_mfma_f32_16x16x32_bf16 v[54:57], v[158:161], v[194:197], v[54:57]
	v_mfma_f32_16x16x32_bf16 v[42:45], v[150:153], v[202:205], v[42:45]
	v_mfma_f32_16x16x32_bf16 v[38:41], v[158:161], v[202:205], v[38:41]
	v_mfma_f32_16x16x32_bf16 v[26:29], v[150:153], v[210:213], v[26:29]
	v_mfma_f32_16x16x32_bf16 v[22:25], v[158:161], v[210:213], v[22:25]
	v_mfma_f32_16x16x32_bf16 v[10:13], v[150:153], v[218:221], v[10:13]
	v_mfma_f32_16x16x32_bf16 v[4:7], v[158:161], v[218:221], v[6:9]
	v_mfma_f32_16x16x32_bf16 v[58:61], v[154:157], v[198:201], v[58:61]
	v_mfma_f32_16x16x32_bf16 v[54:57], v[190:193], v[198:201], v[54:57]
	v_mfma_f32_16x16x32_bf16 v[42:45], v[154:157], v[206:209], v[42:45]
	v_mfma_f32_16x16x32_bf16 v[38:41], v[190:193], v[206:209], v[38:41]
	v_mfma_f32_16x16x32_bf16 v[26:29], v[154:157], v[214:217], v[26:29]
	v_mfma_f32_16x16x32_bf16 v[22:25], v[190:193], v[214:217], v[22:25]
	v_mfma_f32_16x16x32_bf16 v[10:13], v[154:157], v[222:225], v[10:13]
	v_mfma_f32_16x16x32_bf16 v[4:7], v[190:193], v[222:225], v[4:7]
	s_setprio 0
	s_barrier
	s_add_i32 s86, 0, 0x18000
	v_add_u32_e32 v3, s86, v186
	s_add_i32 s87, 0, 0x1c000
	ds_read_b128 v[134:137], v3
	ds_read_b128 v[138:141], v3 offset:1024
	ds_read_b128 v[142:145], v3 offset:2048
	ds_read_b128 v[146:149], v3 offset:3072
	v_add_u32_e32 v3, s87, v186
	ds_read_b128 v[150:153], v3
	ds_read_b128 v[154:157], v3 offset:1024
	ds_read_b128 v[158:161], v3 offset:2048
	ds_read_b128 v[190:193], v3 offset:3072
	s_add_u32 s40, s40, 0x100000
	s_addc_u32 s41, s41, 0
	s_mov_b32 m0, s44
	v_lshl_add_u64 v[8:9], s[40:41], 0, v[164:165]
	ds_read_b128 v[194:197], v188 offset:32768
	ds_read_b128 v[198:201], v188 offset:33792
	ds_read_b128 v[202:205], v188 offset:34816
	ds_read_b128 v[206:209], v188 offset:35840
	ds_read_b128 v[210:213], v188 offset:36864
	ds_read_b128 v[214:217], v188 offset:37888
	ds_read_b128 v[218:221], v188 offset:38912
	ds_read_b128 v[222:225], v188 offset:39936
	s_mov_b32 m0, s42
	s_nop 0
	global_load_lds_dwordx4 v[230:231], off
	s_mov_b32 m0, s43
	s_nop 0
	global_load_lds_dwordx4 v[232:233], off
	s_mov_b32 m0, s44
	s_nop 0
	global_load_lds_dwordx4 v[8:9], off
	v_lshl_add_u64 v[8:9], s[40:41], 0, v[168:169]
	s_mov_b32 m0, s45
	s_nop 0
	global_load_lds_dwordx4 v[8:9], off
	s_waitcnt vmcnt(8)
	s_waitcnt lgkmcnt(0)
	s_barrier
	s_setprio 3
	s_waitcnt lgkmcnt(0)
	v_mfma_f32_16x16x32_bf16 v[130:133], v[134:137], v[194:197], v[130:133]
	v_mfma_f32_16x16x32_bf16 v[126:129], v[142:145], v[194:197], v[126:129]
	v_mfma_f32_16x16x32_bf16 v[114:117], v[134:137], v[202:205], v[114:117]
	v_mfma_f32_16x16x32_bf16 v[110:113], v[142:145], v[202:205], v[110:113]
	v_mfma_f32_16x16x32_bf16 v[98:101], v[134:137], v[210:213], v[98:101]
	v_mfma_f32_16x16x32_bf16 v[94:97], v[142:145], v[210:213], v[94:97]
	v_mfma_f32_16x16x32_bf16 v[82:85], v[134:137], v[218:221], v[82:85]
	v_mfma_f32_16x16x32_bf16 v[78:81], v[142:145], v[218:221], v[78:81]
	v_mfma_f32_16x16x32_bf16 v[130:133], v[138:141], v[198:201], v[130:133]
	v_mfma_f32_16x16x32_bf16 v[126:129], v[146:149], v[198:201], v[126:129]
	v_mfma_f32_16x16x32_bf16 v[114:117], v[138:141], v[206:209], v[114:117]
	v_mfma_f32_16x16x32_bf16 v[110:113], v[146:149], v[206:209], v[110:113]
	v_mfma_f32_16x16x32_bf16 v[98:101], v[138:141], v[214:217], v[98:101]
	v_mfma_f32_16x16x32_bf16 v[94:97], v[146:149], v[214:217], v[94:97]
	v_mfma_f32_16x16x32_bf16 v[82:85], v[138:141], v[222:225], v[82:85]
	v_mfma_f32_16x16x32_bf16 v[78:81], v[146:149], v[222:225], v[78:81]
	s_setprio 0
	s_setprio 3
	v_mfma_f32_16x16x32_bf16 v[122:125], v[150:153], v[194:197], v[122:125]
	v_mfma_f32_16x16x32_bf16 v[118:121], v[158:161], v[194:197], v[118:121]
	v_mfma_f32_16x16x32_bf16 v[106:109], v[150:153], v[202:205], v[106:109]
	v_mfma_f32_16x16x32_bf16 v[102:105], v[158:161], v[202:205], v[102:105]
	v_mfma_f32_16x16x32_bf16 v[90:93], v[150:153], v[210:213], v[90:93]
	v_mfma_f32_16x16x32_bf16 v[86:89], v[158:161], v[210:213], v[86:89]
	v_mfma_f32_16x16x32_bf16 v[74:77], v[150:153], v[218:221], v[74:77]
	v_mfma_f32_16x16x32_bf16 v[70:73], v[158:161], v[218:221], v[70:73]
	v_mfma_f32_16x16x32_bf16 v[122:125], v[154:157], v[198:201], v[122:125]
	v_mfma_f32_16x16x32_bf16 v[118:121], v[190:193], v[198:201], v[118:121]
	v_mfma_f32_16x16x32_bf16 v[106:109], v[154:157], v[206:209], v[106:109]
	v_mfma_f32_16x16x32_bf16 v[102:105], v[190:193], v[206:209], v[102:105]
	v_mfma_f32_16x16x32_bf16 v[90:93], v[154:157], v[214:217], v[90:93]
	v_mfma_f32_16x16x32_bf16 v[86:89], v[190:193], v[214:217], v[86:89]
	v_mfma_f32_16x16x32_bf16 v[74:77], v[154:157], v[222:225], v[74:77]
	v_mfma_f32_16x16x32_bf16 v[70:73], v[190:193], v[222:225], v[70:73]
	s_setprio 0
	s_barrier
; #define PG8_STAGE(bufoff, gbase, voff) do { _Pragma("unroll") for (int _i = 0; _i < 2; ++_i) \
;         __builtin_amdgcn_global_load_lds((const unsigned*)((const char*)(gbase) + (voff)[_i]), (PG8_LAS unsigned*)(lds + (bufoff) + ldsw + _i * 8192), 16, 0, 0); } while (0)
; #define PG8_LDA(dst, b, h) do { _Pragma("unroll") for (int m = 0; m < 4; ++m) _Pragma("unroll") for (int k = 0; k < 2; ++k) dst[m][k] = *(const PG8_LAS bf16x8*)(lds + PG8_SA(b, h) + aoff + m * 2048 + k * 1024); } while (0)
; #define PG8_MMA(ai, bj, At, Bt) do { __builtin_amdgcn_s_setprio(3); _Pragma("unroll") for (int m = 0; m < 4; ++m) _Pragma("unroll") for (int n = 0; n < 2; ++n) _Pragma("unroll") for (int k = 0; k < 2; ++k) \
;         acc[ai][bj][m][n] = __builtin_amdgcn_mfma_f32_16x16x32_bf16(Bt[n][k], At[m][k], acc[ai][bj][m][n], 0, 0, 0); __builtin_amdgcn_s_setprio(0); } while (0)
; #define PG8_WAIT_V(n) asm volatile("s_waitcnt vmcnt(" #n ")" ::: "memory")
; #define PG8_WAIT_L(n) asm volatile("s_waitcnt lgkmcnt(" #n ")" ::: "memory")
; #define PG8_BAR __builtin_amdgcn_s_barrier()
; #define PG8_SCHED __builtin_amdgcn_sched_barrier(0)
; template <class Epi, class Sched, bool ALIGN_EPI = false, bool SP2 = false>
; __device__ __forceinline__ void gemm_phase(PG8_LAS unsigned char* lds, const Gemm g, const Sched& S, const Epi& E) {
;     ...
;             PG8_LDA(At, 1, 1); PG8_STAGE(PG8_SB(1, 0), b3, voffB); PG8_STAGE(PG8_SB(1, 1), b3 + hstepB, voffB); PG8_STAGE(PG8_SA(1, 0), a3, voffA);
;             PG8_WAIT_V(8); PG8_WAIT_L(0); PG8_BAR; PG8_MMA(1, 0, At, B0); PG8_MMA(1, 1, At, B1); PG8_BAR; PG8_SCHED;
	s_add_i32 s40, s86, s33
	v_lshl_add_u64 v[8:9], v[226:227], 0, s[10:11]
	s_mov_b32 m0, s40
	ds_read_b128 v[194:197], v188 offset:49152
	ds_read_b128 v[198:201], v188 offset:50176
	ds_read_b128 v[202:205], v188 offset:51200
	ds_read_b128 v[206:209], v188 offset:52224
	ds_read_b128 v[210:213], v188 offset:53248
	ds_read_b128 v[214:217], v188 offset:54272
	ds_read_b128 v[218:221], v188 offset:55296
	ds_read_b128 v[222:225], v188 offset:56320
	global_load_lds_dwordx4 v[8:9], off
	s_add_i32 m0, s40, 0x2000
	s_add_u32 s36, s36, 0x100080
	v_lshl_add_u64 v[8:9], v[228:229], 0, s[10:11]
	s_addc_u32 s37, s37, 0
	s_add_i32 s40, s87, s33
	global_load_lds_dwordx4 v[8:9], off
	v_lshl_add_u64 v[8:9], s[36:37], 0, v[166:167]
	s_mov_b32 m0, s40
	s_nop 0
	global_load_lds_dwordx4 v[8:9], off
	v_lshl_add_u64 v[8:9], s[36:37], 0, v[170:171]
	s_add_i32 m0, s40, 0x2000
	s_nop 0
	global_load_lds_dwordx4 v[8:9], off
	v_lshl_add_u64 v[8:9], v[230:231], 0, s[10:11]
	s_mov_b32 m0, s60
	s_nop 0
	global_load_lds_dwordx4 v[8:9], off
	v_lshl_add_u64 v[8:9], v[232:233], 0, s[10:11]
	s_mov_b32 m0, s61
	s_nop 0
	global_load_lds_dwordx4 v[8:9], off
	s_waitcnt vmcnt(8)
	s_waitcnt lgkmcnt(0)
	s_barrier
	s_setprio 3
	s_waitcnt lgkmcnt(0)
	v_mfma_f32_16x16x32_bf16 v[66:69], v[134:137], v[194:197], v[66:69]
	v_mfma_f32_16x16x32_bf16 v[62:65], v[142:145], v[194:197], v[62:65]
	v_mfma_f32_16x16x32_bf16 v[50:53], v[134:137], v[202:205], v[50:53]
	v_mfma_f32_16x16x32_bf16 v[46:49], v[142:145], v[202:205], v[46:49]
	v_mfma_f32_16x16x32_bf16 v[34:37], v[134:137], v[210:213], v[34:37]
	v_mfma_f32_16x16x32_bf16 v[30:33], v[142:145], v[210:213], v[30:33]
	v_mfma_f32_16x16x32_bf16 v[18:21], v[134:137], v[218:221], v[18:21]
	v_mfma_f32_16x16x32_bf16 v[14:17], v[142:145], v[218:221], v[14:17]
	v_mfma_f32_16x16x32_bf16 v[66:69], v[138:141], v[198:201], v[66:69]
	v_mfma_f32_16x16x32_bf16 v[62:65], v[146:149], v[198:201], v[62:65]
	v_mfma_f32_16x16x32_bf16 v[50:53], v[138:141], v[206:209], v[50:53]
	v_mfma_f32_16x16x32_bf16 v[46:49], v[146:149], v[206:209], v[46:49]
	v_mfma_f32_16x16x32_bf16 v[34:37], v[138:141], v[214:217], v[34:37]
	v_mfma_f32_16x16x32_bf16 v[30:33], v[146:149], v[214:217], v[30:33]
	v_mfma_f32_16x16x32_bf16 v[18:21], v[138:141], v[222:225], v[18:21]
	v_mfma_f32_16x16x32_bf16 v[14:17], v[146:149], v[222:225], v[14:17]
	s_setprio 0
	s_setprio 3
	v_mfma_f32_16x16x32_bf16 v[58:61], v[150:153], v[194:197], v[58:61]
	v_mfma_f32_16x16x32_bf16 v[54:57], v[158:161], v[194:197], v[54:57]
	v_mfma_f32_16x16x32_bf16 v[42:45], v[150:153], v[202:205], v[42:45]
	v_mfma_f32_16x16x32_bf16 v[38:41], v[158:161], v[202:205], v[38:41]
	v_mfma_f32_16x16x32_bf16 v[26:29], v[150:153], v[210:213], v[26:29]
	v_mfma_f32_16x16x32_bf16 v[22:25], v[158:161], v[210:213], v[22:25]
	v_mfma_f32_16x16x32_bf16 v[8:11], v[150:153], v[218:221], v[10:13]
	v_mfma_f32_16x16x32_bf16 v[4:7], v[158:161], v[218:221], v[4:7]
	v_mfma_f32_16x16x32_bf16 v[58:61], v[154:157], v[198:201], v[58:61]
	v_mfma_f32_16x16x32_bf16 v[54:57], v[190:193], v[198:201], v[54:57]
	v_mfma_f32_16x16x32_bf16 v[42:45], v[154:157], v[206:209], v[42:45]
	v_mfma_f32_16x16x32_bf16 v[38:41], v[190:193], v[206:209], v[38:41]
	v_mfma_f32_16x16x32_bf16 v[26:29], v[154:157], v[214:217], v[26:29]
	v_mfma_f32_16x16x32_bf16 v[22:25], v[190:193], v[214:217], v[22:25]
	v_mfma_f32_16x16x32_bf16 v[10:13], v[154:157], v[222:225], v[8:11]
	v_mfma_f32_16x16x32_bf16 v[6:9], v[190:193], v[222:225], v[4:7]
	s_setprio 0
	s_barrier
	s_add_i32 s85, s85, 2
	s_add_u32 s30, s30, 0x100
	s_addc_u32 s31, s31, 0
	s_cmp_gt_u32 s85, 61
	s_cbranch_scc1 .LBB0_811

; #define PG8_STAGE(bufoff, gbase, voff) do { _Pragma("unroll") for (int _i = 0; _i < 2; ++_i) \
;         __builtin_amdgcn_global_load_lds((const unsigned*)((const char*)(gbase) + (voff)[_i]), (PG8_LAS unsigned*)(lds + (bufoff) + ldsw + _i * 8192), 16, 0, 0); } while (0)
; #define PG8_LDA(dst, b, h) do { _Pragma("unroll") for (int m = 0; m < 4; ++m) _Pragma("unroll") for (int k = 0; k < 2; ++k) dst[m][k] = *(const PG8_LAS bf16x8*)(lds + PG8_SA(b, h) + aoff + m * 2048 + k * 1024); } while (0)
; #define PG8_LDB(dst, b, h) do { _Pragma("unroll") for (int n = 0; n < 2; ++n) _Pragma("unroll") for (int k = 0; k < 2; ++k) dst[n][k] = *(const PG8_LAS bf16x8*)(lds + PG8_SB(b, h) + boff + n * 2048 + k * 1024); } while (0)
; #define PG8_MMA(ai, bj, At, Bt) do { __builtin_amdgcn_s_setprio(3); _Pragma("unroll") for (int m = 0; m < 4; ++m) _Pragma("unroll") for (int n = 0; n < 2; ++n) _Pragma("unroll") for (int k = 0; k < 2; ++k) \
;         acc[ai][bj][m][n] = __builtin_amdgcn_mfma_f32_16x16x32_bf16(Bt[n][k], At[m][k], acc[ai][bj][m][n], 0, 0, 0); __builtin_amdgcn_s_setprio(0); } while (0)
; #define PG8_WAIT_V(n) asm volatile("s_waitcnt vmcnt(" #n ")" ::: "memory")
; #define PG8_WAIT_L(n) asm volatile("s_waitcnt lgkmcnt(" #n ")" ::: "memory")
; template <class Epi, class Sched, bool ALIGN_EPI = false, bool SP2 = false>
; __device__ __forceinline__ void gemm_phase(PG8_LAS unsigned char* lds, const Gemm g, const Sched& S, const Epi& E) {
;     ...
;         for (int t = 0; t < nt; t += 2) {
;             const bool last = (t == nt - 2);
;             const char* a1 = cA + (size_t)(t + 1) * kstep;
;             const char* a2 = last ? nA : cA + (size_t)(t + 2) * kstep; const char* b2 = last ? nB : cB + (size_t)(t + 2) * kstep;
;             const char* a3 = a2 + kstep; const char* b3 = b2 + kstep;
;             if (last && has_next) S.a_ready(nxt);
;             if constexpr (Epi::MIDK) { if (t == E.midk_step(nt)) E.midk(acc, cur, wr, wc, fr, fq); }
;             if constexpr (SP2) {
;             PG8_LDB(B0, 0, 0); PG8_LDB(B1, 0, 1); PG8_SCHED; PG8_LDA(At, 0, 0); PG8_STAGE(PG8_SA(1, 1), a1 + hstepA, voffA);
;             PG8_WAIT_V(8); PG8_WAIT_L(0); PG8_BAR; PG8_MMA(0, 0, At, B0); PG8_MMA(0, 1, At, B1); PG8_BAR; PG8_SCHED;
;             PG8_LDA(At, 0, 1); PG8_STAGE(PG8_SB(0, 0), b2, voffB); PG8_STAGE(PG8_SB(0, 1), b2 + hstepB, voffB); PG8_STAGE(PG8_SA(0, 0), a2, voffA);
.LBB0_908:
	ds_read_b128 v[158:161], v155
	ds_read_b128 v[164:167], v155 offset:1024
	ds_read_b128 v[168:171], v155 offset:2048
	ds_read_b128 v[172:175], v155 offset:3072
	ds_read_b128 v[176:179], v156
	ds_read_b128 v[180:183], v156 offset:1024
	ds_read_b128 v[184:187], v156 offset:2048
	ds_read_b128 v[188:191], v156 offset:3072
	s_add_u32 s26, s24, 0xfff00080
	s_addc_u32 s27, s25, -1
	s_cmp_eq_u32 s55, 60
	s_cselect_b32 s29, s17, s27
	s_cselect_b32 s28, s47, s26
	s_cselect_b32 s27, s15, s54
	s_cselect_b32 s26, s52, s53
	v_lshl_add_u64 v[146:147], s[24:25], 0, v[138:139]
	s_add_i32 m0, s23, 0xc000
	ds_read_b128 v[192:195], v157
	ds_read_b128 v[196:199], v157 offset:1024
	ds_read_b128 v[200:203], v157 offset:2048
	ds_read_b128 v[204:207], v157 offset:3072
	ds_read_b128 v[208:211], v157 offset:4096
	ds_read_b128 v[212:215], v157 offset:5120
	ds_read_b128 v[216:219], v157 offset:6144
	ds_read_b128 v[220:223], v157 offset:7168
	global_load_lds_dwordx4 v[146:147], off
	v_lshl_add_u64 v[146:147], s[24:25], 0, v[140:141]
	s_add_i32 m0, s23, 0xe000
	s_nop 0
	global_load_lds_dwordx4 v[146:147], off
	s_waitcnt vmcnt(8)
	s_waitcnt lgkmcnt(0)
	s_barrier
	s_setprio 3
	s_waitcnt lgkmcnt(0)
	v_mfma_f32_16x16x32_bf16 v[126:129], v[158:161], v[192:195], v[126:129]
	v_mfma_f32_16x16x32_bf16 v[122:125], v[168:171], v[192:195], v[122:125]
	v_mfma_f32_16x16x32_bf16 v[114:117], v[158:161], v[200:203], v[114:117]
	v_mfma_f32_16x16x32_bf16 v[106:109], v[168:171], v[200:203], v[106:109]
	v_mfma_f32_16x16x32_bf16 v[98:101], v[158:161], v[208:211], v[98:101]
	v_mfma_f32_16x16x32_bf16 v[90:93], v[168:171], v[208:211], v[90:93]
	v_mfma_f32_16x16x32_bf16 v[82:85], v[158:161], v[216:219], v[82:85]
	v_mfma_f32_16x16x32_bf16 v[74:77], v[168:171], v[216:219], v[74:77]
	v_mfma_f32_16x16x32_bf16 v[126:129], v[164:167], v[196:199], v[126:129]
	v_mfma_f32_16x16x32_bf16 v[122:125], v[172:175], v[196:199], v[122:125]
	v_mfma_f32_16x16x32_bf16 v[114:117], v[164:167], v[204:207], v[114:117]
	v_mfma_f32_16x16x32_bf16 v[106:109], v[172:175], v[204:207], v[106:109]
	v_mfma_f32_16x16x32_bf16 v[98:101], v[164:167], v[212:215], v[98:101]
	v_mfma_f32_16x16x32_bf16 v[90:93], v[172:175], v[212:215], v[90:93]
	v_mfma_f32_16x16x32_bf16 v[82:85], v[164:167], v[220:223], v[82:85]
	v_mfma_f32_16x16x32_bf16 v[74:77], v[172:175], v[220:223], v[74:77]
	s_setprio 0
	s_setprio 3
	v_mfma_f32_16x16x32_bf16 v[118:121], v[176:179], v[192:195], v[118:121]
	v_mfma_f32_16x16x32_bf16 v[110:113], v[184:187], v[192:195], v[110:113]
	v_mfma_f32_16x16x32_bf16 v[102:105], v[176:179], v[200:203], v[102:105]
	v_mfma_f32_16x16x32_bf16 v[94:97], v[184:187], v[200:203], v[94:97]
	v_mfma_f32_16x16x32_bf16 v[86:89], v[176:179], v[208:211], v[86:89]
	v_mfma_f32_16x16x32_bf16 v[78:81], v[184:187], v[208:211], v[78:81]
	v_mfma_f32_16x16x32_bf16 v[70:73], v[176:179], v[216:219], v[70:73]
	v_mfma_f32_16x16x32_bf16 v[66:69], v[184:187], v[216:219], v[66:69]
	v_mfma_f32_16x16x32_bf16 v[118:121], v[180:183], v[196:199], v[118:121]
	v_mfma_f32_16x16x32_bf16 v[110:113], v[188:191], v[196:199], v[110:113]
	v_mfma_f32_16x16x32_bf16 v[102:105], v[180:183], v[204:207], v[102:105]
	v_mfma_f32_16x16x32_bf16 v[94:97], v[188:191], v[204:207], v[94:97]
	v_mfma_f32_16x16x32_bf16 v[86:89], v[180:183], v[212:215], v[86:89]
	v_mfma_f32_16x16x32_bf16 v[78:81], v[188:191], v[212:215], v[78:81]
	v_mfma_f32_16x16x32_bf16 v[70:73], v[180:183], v[220:223], v[70:73]
	v_mfma_f32_16x16x32_bf16 v[66:69], v[188:191], v[220:223], v[66:69]
	s_setprio 0
	s_barrier
	s_add_i32 s56, s42, s30
	v_lshl_add_u64 v[146:147], s[26:27], 0, v[134:135]
	s_mov_b32 m0, s56
	ds_read_b128 v[192:195], v157 offset:16384
	ds_read_b128 v[196:199], v157 offset:17408
	ds_read_b128 v[200:203], v157 offset:18432
	ds_read_b128 v[204:207], v157 offset:19456
	ds_read_b128 v[208:211], v157 offset:20480
	ds_read_b128 v[212:215], v157 offset:21504
	ds_read_b128 v[216:219], v157 offset:22528
	ds_read_b128 v[220:223], v157 offset:23552
	global_load_lds_dwordx4 v[146:147], off
	s_add_i32 m0, s56, 0x2000
	s_add_u32 s56, s26, 0x100000
	v_lshl_add_u64 v[224:225], s[26:27], 0, v[130:131]
	s_addc_u32 s57, s27, 0
	s_add_i32 s58, s43, s30
	global_load_lds_dwordx4 v[224:225], off
	v_lshl_add_u64 v[226:227], s[56:57], 0, v[134:135]
	s_mov_b32 m0, s58
	v_lshl_add_u64 v[228:229], s[28:29], 0, v[132:133]
	global_load_lds_dwordx4 v[226:227], off
	v_lshl_add_u64 v[226:227], s[56:57], 0, v[130:131]
	s_add_i32 m0, s58, 0x2000
	s_nop 0
	global_load_lds_dwordx4 v[226:227], off
	v_lshl_add_u64 v[226:227], s[28:29], 0, v[136:137]
	s_waitcnt vmcnt(6)
	s_waitcnt lgkmcnt(0)
	s_barrier
; #define PG8_STAGE(bufoff, gbase, voff) do { _Pragma("unroll") for (int _i = 0; _i < 2; ++_i) \
;         __builtin_amdgcn_global_load_lds((const unsigned*)((const char*)(gbase) + (voff)[_i]), (PG8_LAS unsigned*)(lds + (bufoff) + ldsw + _i * 8192), 16, 0, 0); } while (0)
; #define PG8_LDA(dst, b, h) do { _Pragma("unroll") for (int m = 0; m < 4; ++m) _Pragma("unroll") for (int k = 0; k < 2; ++k) dst[m][k] = *(const PG8_LAS bf16x8*)(lds + PG8_SA(b, h) + aoff + m * 2048 + k * 1024); } while (0)
; #define PG8_LDB(dst, b, h) do { _Pragma("unroll") for (int n = 0; n < 2; ++n) _Pragma("unroll") for (int k = 0; k < 2; ++k) dst[n][k] = *(const PG8_LAS bf16x8*)(lds + PG8_SB(b, h) + boff + n * 2048 + k * 1024); } while (0)
; #define PG8_MMA(ai, bj, At, Bt) do { __builtin_amdgcn_s_setprio(3); _Pragma("unroll") for (int m = 0; m < 4; ++m) _Pragma("unroll") for (int n = 0; n < 2; ++n) _Pragma("unroll") for (int k = 0; k < 2; ++k) \
;         acc[ai][bj][m][n] = __builtin_amdgcn_mfma_f32_16x16x32_bf16(Bt[n][k], At[m][k], acc[ai][bj][m][n], 0, 0, 0); __builtin_amdgcn_s_setprio(0); } while (0)
; #define PG8_WAIT_V(n) asm volatile("s_waitcnt vmcnt(" #n ")" ::: "memory")
; #define PG8_WAIT_L(n) asm volatile("s_waitcnt lgkmcnt(" #n ")" ::: "memory")
; #define PG8_BAR __builtin_amdgcn_s_barrier()
; #define PG8_SCHED __builtin_amdgcn_sched_barrier(0)
; template <class Epi, class Sched, bool ALIGN_EPI = false, bool SP2 = false>
; __device__ __forceinline__ void gemm_phase(PG8_LAS unsigned char* lds, const Gemm g, const Sched& S, const Epi& E) {
;     ...
;             PG8_WAIT_V(8); PG8_WAIT_L(0); PG8_BAR; PG8_MMA(0, 0, At, B0); PG8_MMA(0, 1, At, B1); PG8_BAR; PG8_SCHED;
;             PG8_LDA(At, 0, 1); PG8_STAGE(PG8_SB(0, 0), b2, voffB); PG8_STAGE(PG8_SB(0, 1), b2 + hstepB, voffB); PG8_STAGE(PG8_SA(0, 0), a2, voffA);
;             PG8_WAIT_V(8); PG8_WAIT_L(0); PG8_BAR; PG8_MMA(1, 0, At, B0); PG8_MMA(1, 1, At, B1); PG8_BAR; PG8_SCHED;
;             PG8_LDB(B0, 1, 0); PG8_LDB(B1, 1, 1); PG8_SCHED; PG8_LDA(At, 1, 0); PG8_STAGE(PG8_SA(0, 1), a2 + hstepA, voffA);
;             PG8_WAIT_V(8); PG8_WAIT_L(0); PG8_BAR; PG8_MMA(0, 0, At, B0); PG8_MMA(0, 1, At, B1); PG8_BAR; PG8_SCHED;
	s_setprio 3
	s_waitcnt lgkmcnt(0)
	v_mfma_f32_16x16x32_bf16 v[62:65], v[158:161], v[192:195], v[62:65]
	v_mfma_f32_16x16x32_bf16 v[58:61], v[168:171], v[192:195], v[58:61]
	v_mfma_f32_16x16x32_bf16 v[50:53], v[158:161], v[200:203], v[50:53]
	v_mfma_f32_16x16x32_bf16 v[42:45], v[168:171], v[200:203], v[42:45]
	v_mfma_f32_16x16x32_bf16 v[34:37], v[158:161], v[208:211], v[34:37]
	v_mfma_f32_16x16x32_bf16 v[26:29], v[168:171], v[208:211], v[26:29]
	v_mfma_f32_16x16x32_bf16 v[14:17], v[158:161], v[216:219], v[14:17]
	v_mfma_f32_16x16x32_bf16 v[10:13], v[168:171], v[216:219], v[10:13]
	v_mfma_f32_16x16x32_bf16 v[62:65], v[164:167], v[196:199], v[62:65]
	v_mfma_f32_16x16x32_bf16 v[58:61], v[172:175], v[196:199], v[58:61]
	v_mfma_f32_16x16x32_bf16 v[50:53], v[164:167], v[204:207], v[50:53]
	v_mfma_f32_16x16x32_bf16 v[42:45], v[172:175], v[204:207], v[42:45]
	v_mfma_f32_16x16x32_bf16 v[34:37], v[164:167], v[212:215], v[34:37]
	v_mfma_f32_16x16x32_bf16 v[26:29], v[172:175], v[212:215], v[26:29]
	v_mfma_f32_16x16x32_bf16 v[14:17], v[164:167], v[220:223], v[14:17]
	v_mfma_f32_16x16x32_bf16 v[10:13], v[172:175], v[220:223], v[10:13]
	s_setprio 0
	s_setprio 3
	v_mfma_f32_16x16x32_bf16 v[54:57], v[176:179], v[192:195], v[54:57]
	v_mfma_f32_16x16x32_bf16 v[46:49], v[184:187], v[192:195], v[46:49]
	v_mfma_f32_16x16x32_bf16 v[38:41], v[176:179], v[200:203], v[38:41]
	v_mfma_f32_16x16x32_bf16 v[30:33], v[184:187], v[200:203], v[30:33]
	v_mfma_f32_16x16x32_bf16 v[22:25], v[176:179], v[208:211], v[22:25]
	v_mfma_f32_16x16x32_bf16 v[18:21], v[184:187], v[208:211], v[18:21]
	v_mfma_f32_16x16x32_bf16 v[6:9], v[176:179], v[216:219], v[6:9]
	v_mfma_f32_16x16x32_bf16 v[2:5], v[184:187], v[216:219], v[2:5]
	v_mfma_f32_16x16x32_bf16 v[54:57], v[180:183], v[196:199], v[54:57]
	v_mfma_f32_16x16x32_bf16 v[46:49], v[188:191], v[196:199], v[46:49]
	v_mfma_f32_16x16x32_bf16 v[38:41], v[180:183], v[204:207], v[38:41]
	v_mfma_f32_16x16x32_bf16 v[30:33], v[188:191], v[204:207], v[30:33]
	v_mfma_f32_16x16x32_bf16 v[22:25], v[180:183], v[212:215], v[22:25]
	v_mfma_f32_16x16x32_bf16 v[18:21], v[188:191], v[212:215], v[18:21]
	v_mfma_f32_16x16x32_bf16 v[6:9], v[180:183], v[220:223], v[6:9]
	v_mfma_f32_16x16x32_bf16 v[2:5], v[188:191], v[220:223], v[2:5]
	s_setprio 0
	s_barrier
	s_add_i32 s56, 0, 0x18000
	v_add_u32_e32 v148, s56, v151
	s_add_i32 s57, 0, 0x1c000
	ds_read_b128 v[158:161], v148
	ds_read_b128 v[164:167], v148 offset:1024
	ds_read_b128 v[168:171], v148 offset:2048
	ds_read_b128 v[172:175], v148 offset:3072
	v_add_u32_e32 v148, s57, v151
	ds_read_b128 v[176:179], v148
	ds_read_b128 v[180:183], v148 offset:1024
	ds_read_b128 v[184:187], v148 offset:2048
	ds_read_b128 v[188:191], v148 offset:3072
	s_add_u32 s28, s28, 0x100000
	s_addc_u32 s29, s29, 0
	s_mov_b32 m0, s36
	v_lshl_add_u64 v[230:231], s[28:29], 0, v[136:137]
	ds_read_b128 v[192:195], v157 offset:32768
	ds_read_b128 v[196:199], v157 offset:33792
	ds_read_b128 v[200:203], v157 offset:34816
	ds_read_b128 v[204:207], v157 offset:35840
	ds_read_b128 v[208:211], v157 offset:36864
	ds_read_b128 v[212:215], v157 offset:37888
	ds_read_b128 v[216:219], v157 offset:38912
	ds_read_b128 v[220:223], v157 offset:39936
	s_mov_b32 m0, s23
	s_nop 0
	global_load_lds_dwordx4 v[226:227], off
	s_mov_b32 m0, s33
	s_nop 0
	global_load_lds_dwordx4 v[228:229], off
	s_mov_b32 m0, s36
	s_nop 0
	global_load_lds_dwordx4 v[230:231], off
	v_lshl_add_u64 v[230:231], s[28:29], 0, v[132:133]
	s_mov_b32 m0, s37
	s_nop 0
	global_load_lds_dwordx4 v[230:231], off
	s_waitcnt vmcnt(8)
	s_waitcnt lgkmcnt(0)
	s_barrier
	s_setprio 3
	s_waitcnt lgkmcnt(0)
	v_mfma_f32_16x16x32_bf16 v[126:129], v[158:161], v[192:195], v[126:129]
	v_mfma_f32_16x16x32_bf16 v[122:125], v[168:171], v[192:195], v[122:125]
	v_mfma_f32_16x16x32_bf16 v[114:117], v[158:161], v[200:203], v[114:117]
	v_mfma_f32_16x16x32_bf16 v[106:109], v[168:171], v[200:203], v[106:109]
	v_mfma_f32_16x16x32_bf16 v[98:101], v[158:161], v[208:211], v[98:101]
	v_mfma_f32_16x16x32_bf16 v[90:93], v[168:171], v[208:211], v[90:93]
	v_mfma_f32_16x16x32_bf16 v[82:85], v[158:161], v[216:219], v[82:85]
	v_mfma_f32_16x16x32_bf16 v[74:77], v[168:171], v[216:219], v[74:77]
	v_mfma_f32_16x16x32_bf16 v[126:129], v[164:167], v[196:199], v[126:129]
	v_mfma_f32_16x16x32_bf16 v[122:125], v[172:175], v[196:199], v[122:125]
	v_mfma_f32_16x16x32_bf16 v[114:117], v[164:167], v[204:207], v[114:117]
	v_mfma_f32_16x16x32_bf16 v[106:109], v[172:175], v[204:207], v[106:109]
	v_mfma_f32_16x16x32_bf16 v[98:101], v[164:167], v[212:215], v[98:101]
	v_mfma_f32_16x16x32_bf16 v[90:93], v[172:175], v[212:215], v[90:93]
	v_mfma_f32_16x16x32_bf16 v[82:85], v[164:167], v[220:223], v[82:85]
	v_mfma_f32_16x16x32_bf16 v[74:77], v[172:175], v[220:223], v[74:77]
	s_setprio 0
	s_setprio 3
	v_mfma_f32_16x16x32_bf16 v[118:121], v[176:179], v[192:195], v[118:121]
	v_mfma_f32_16x16x32_bf16 v[110:113], v[184:187], v[192:195], v[110:113]
	v_mfma_f32_16x16x32_bf16 v[102:105], v[176:179], v[200:203], v[102:105]
	v_mfma_f32_16x16x32_bf16 v[94:97], v[184:187], v[200:203], v[94:97]
	v_mfma_f32_16x16x32_bf16 v[86:89], v[176:179], v[208:211], v[86:89]
	v_mfma_f32_16x16x32_bf16 v[78:81], v[184:187], v[208:211], v[78:81]
	v_mfma_f32_16x16x32_bf16 v[70:73], v[176:179], v[216:219], v[70:73]
	v_mfma_f32_16x16x32_bf16 v[66:69], v[184:187], v[216:219], v[66:69]
	v_mfma_f32_16x16x32_bf16 v[118:121], v[180:183], v[196:199], v[118:121]
	v_mfma_f32_16x16x32_bf16 v[110:113], v[188:191], v[196:199], v[110:113]
	v_mfma_f32_16x16x32_bf16 v[102:105], v[180:183], v[204:207], v[102:105]
	v_mfma_f32_16x16x32_bf16 v[94:97], v[188:191], v[204:207], v[94:97]
	v_mfma_f32_16x16x32_bf16 v[86:89], v[180:183], v[212:215], v[86:89]
	v_mfma_f32_16x16x32_bf16 v[78:81], v[188:191], v[212:215], v[78:81]
	v_mfma_f32_16x16x32_bf16 v[70:73], v[180:183], v[220:223], v[70:73]
	v_mfma_f32_16x16x32_bf16 v[66:69], v[188:191], v[220:223], v[66:69]
	s_setprio 0
	s_barrier
; #define PG8_STAGE(bufoff, gbase, voff) do { _Pragma("unroll") for (int _i = 0; _i < 2; ++_i) \
;         __builtin_amdgcn_global_load_lds((const unsigned*)((const char*)(gbase) + (voff)[_i]), (PG8_LAS unsigned*)(lds + (bufoff) + ldsw + _i * 8192), 16, 0, 0); } while (0)
; #define PG8_LDA(dst, b, h) do { _Pragma("unroll") for (int m = 0; m < 4; ++m) _Pragma("unroll") for (int k = 0; k < 2; ++k) dst[m][k] = *(const PG8_LAS bf16x8*)(lds + PG8_SA(b, h) + aoff + m * 2048 + k * 1024); } while (0)
; #define PG8_MMA(ai, bj, At, Bt) do { __builtin_amdgcn_s_setprio(3); _Pragma("unroll") for (int m = 0; m < 4; ++m) _Pragma("unroll") for (int n = 0; n < 2; ++n) _Pragma("unroll") for (int k = 0; k < 2; ++k) \
;         acc[ai][bj][m][n] = __builtin_amdgcn_mfma_f32_16x16x32_bf16(Bt[n][k], At[m][k], acc[ai][bj][m][n], 0, 0, 0); __builtin_amdgcn_s_setprio(0); } while (0)
; #define PG8_WAIT_V(n) asm volatile("s_waitcnt vmcnt(" #n ")" ::: "memory")
; #define PG8_WAIT_L(n) asm volatile("s_waitcnt lgkmcnt(" #n ")" ::: "memory")
; #define PG8_BAR __builtin_amdgcn_s_barrier()
; #define PG8_SCHED __builtin_amdgcn_sched_barrier(0)
; template <class Epi, class Sched, bool ALIGN_EPI = false, bool SP2 = false>
; __device__ __forceinline__ void gemm_phase(PG8_LAS unsigned char* lds, const Gemm g, const Sched& S, const Epi& E) {
;     ...
;             PG8_LDA(At, 1, 1); PG8_STAGE(PG8_SB(1, 0), b3, voffB); PG8_STAGE(PG8_SB(1, 1), b3 + hstepB, voffB); PG8_STAGE(PG8_SA(1, 0), a3, voffA);
;             PG8_WAIT_V(8); PG8_WAIT_L(0); PG8_BAR; PG8_MMA(1, 0, At, B0); PG8_MMA(1, 1, At, B1); PG8_BAR; PG8_SCHED;
;     ...
;         if constexpr (ALIGN_EPI) { if (wr == 0) PG8_BAR; }
;         if constexpr (!Epi::AFTER_DRAIN) { E(acc, cur, wr, wc, fr, fq); S.done(cur); }
	s_add_i32 s28, s56, s30
	v_lshl_add_u64 v[146:147], v[146:147], 0, s[12:13]
	s_mov_b32 m0, s28
	ds_read_b128 v[192:195], v157 offset:49152
	ds_read_b128 v[196:199], v157 offset:50176
	ds_read_b128 v[200:203], v157 offset:51200
	ds_read_b128 v[204:207], v157 offset:52224
	ds_read_b128 v[208:211], v157 offset:53248
	ds_read_b128 v[212:215], v157 offset:54272
	ds_read_b128 v[216:219], v157 offset:55296
	ds_read_b128 v[220:223], v157 offset:56320
	global_load_lds_dwordx4 v[146:147], off
	s_add_i32 m0, s28, 0x2000
	s_add_u32 s26, s26, 0x100080
	v_lshl_add_u64 v[146:147], v[224:225], 0, s[12:13]
	s_addc_u32 s27, s27, 0
	s_add_i32 s28, s57, s30
	global_load_lds_dwordx4 v[146:147], off
	v_lshl_add_u64 v[146:147], s[26:27], 0, v[134:135]
	s_mov_b32 m0, s28
	s_nop 0
	global_load_lds_dwordx4 v[146:147], off
	v_lshl_add_u64 v[146:147], s[26:27], 0, v[130:131]
	s_add_i32 m0, s28, 0x2000
	s_nop 0
	global_load_lds_dwordx4 v[146:147], off
	v_lshl_add_u64 v[146:147], v[226:227], 0, s[12:13]
	s_mov_b32 m0, s39
	s_nop 0
	global_load_lds_dwordx4 v[146:147], off
	v_lshl_add_u64 v[146:147], v[228:229], 0, s[12:13]
	s_mov_b32 m0, s40
	s_nop 0
	global_load_lds_dwordx4 v[146:147], off
	s_waitcnt vmcnt(8)
	s_waitcnt lgkmcnt(0)
	s_barrier
	s_setprio 3
	s_waitcnt lgkmcnt(0)
	v_mfma_f32_16x16x32_bf16 v[62:65], v[158:161], v[192:195], v[62:65]
	v_mfma_f32_16x16x32_bf16 v[58:61], v[168:171], v[192:195], v[58:61]
	v_mfma_f32_16x16x32_bf16 v[50:53], v[158:161], v[200:203], v[50:53]
	v_mfma_f32_16x16x32_bf16 v[42:45], v[168:171], v[200:203], v[42:45]
	v_mfma_f32_16x16x32_bf16 v[34:37], v[158:161], v[208:211], v[34:37]
	v_mfma_f32_16x16x32_bf16 v[26:29], v[168:171], v[208:211], v[26:29]
	v_mfma_f32_16x16x32_bf16 v[14:17], v[158:161], v[216:219], v[14:17]
	v_mfma_f32_16x16x32_bf16 v[10:13], v[168:171], v[216:219], v[10:13]
	v_mfma_f32_16x16x32_bf16 v[62:65], v[164:167], v[196:199], v[62:65]
	v_mfma_f32_16x16x32_bf16 v[58:61], v[172:175], v[196:199], v[58:61]
	v_mfma_f32_16x16x32_bf16 v[50:53], v[164:167], v[204:207], v[50:53]
	v_mfma_f32_16x16x32_bf16 v[42:45], v[172:175], v[204:207], v[42:45]
	v_mfma_f32_16x16x32_bf16 v[34:37], v[164:167], v[212:215], v[34:37]
	v_mfma_f32_16x16x32_bf16 v[26:29], v[172:175], v[212:215], v[26:29]
	v_mfma_f32_16x16x32_bf16 v[14:17], v[164:167], v[220:223], v[14:17]
	v_mfma_f32_16x16x32_bf16 v[10:13], v[172:175], v[220:223], v[10:13]
	s_setprio 0
	s_setprio 3
	v_mfma_f32_16x16x32_bf16 v[54:57], v[176:179], v[192:195], v[54:57]
	v_mfma_f32_16x16x32_bf16 v[46:49], v[184:187], v[192:195], v[46:49]
	v_mfma_f32_16x16x32_bf16 v[38:41], v[176:179], v[200:203], v[38:41]
	v_mfma_f32_16x16x32_bf16 v[30:33], v[184:187], v[200:203], v[30:33]
	v_mfma_f32_16x16x32_bf16 v[22:25], v[176:179], v[208:211], v[22:25]
	v_mfma_f32_16x16x32_bf16 v[18:21], v[184:187], v[208:211], v[18:21]
	v_mfma_f32_16x16x32_bf16 v[6:9], v[176:179], v[216:219], v[6:9]
	v_mfma_f32_16x16x32_bf16 v[2:5], v[184:187], v[216:219], v[2:5]
	v_mfma_f32_16x16x32_bf16 v[54:57], v[180:183], v[196:199], v[54:57]
	v_mfma_f32_16x16x32_bf16 v[46:49], v[188:191], v[196:199], v[46:49]
	v_mfma_f32_16x16x32_bf16 v[38:41], v[180:183], v[204:207], v[38:41]
	v_mfma_f32_16x16x32_bf16 v[30:33], v[188:191], v[204:207], v[30:33]
	v_mfma_f32_16x16x32_bf16 v[22:25], v[180:183], v[212:215], v[22:25]
	v_mfma_f32_16x16x32_bf16 v[18:21], v[188:191], v[212:215], v[18:21]
	v_mfma_f32_16x16x32_bf16 v[6:9], v[180:183], v[220:223], v[6:9]
	v_mfma_f32_16x16x32_bf16 v[2:5], v[188:191], v[220:223], v[2:5]
	s_setprio 0
	s_barrier
	s_add_i32 s55, s55, 2
	s_add_u32 s24, s24, 0x100
	s_addc_u32 s25, s25, 0
	s_add_u32 s53, s53, 0x100
	s_addc_u32 s54, s54, 0
	s_cmp_gt_u32 s55, 61
	s_cbranch_scc0 .LBB0_908
	s_and_b64 vcc, exec, s[0:1]
	s_cbranch_vccz .LBB0_911
	s_barrier

; #define PG8_STAGE(bufoff, gbase, voff) do { _Pragma("unroll") for (int _i = 0; _i < 2; ++_i) \
;         __builtin_amdgcn_global_load_lds((const unsigned*)((const char*)(gbase) + (voff)[_i]), (PG8_LAS unsigned*)(lds + (bufoff) + ldsw + _i * 8192), 16, 0, 0); } while (0)
; #define PG8_LDA(dst, b, h) do { _Pragma("unroll") for (int m = 0; m < 4; ++m) _Pragma("unroll") for (int k = 0; k < 2; ++k) dst[m][k] = *(const PG8_LAS bf16x8*)(lds + PG8_SA(b, h) + aoff + m * 2048 + k * 1024); } while (0)
; #define PG8_LDB(dst, b, h) do { _Pragma("unroll") for (int n = 0; n < 2; ++n) _Pragma("unroll") for (int k = 0; k < 2; ++k) dst[n][k] = *(const PG8_LAS bf16x8*)(lds + PG8_SB(b, h) + boff + n * 2048 + k * 1024); } while (0)
; #define PG8_MMA(ai, bj, At, Bt) do { __builtin_amdgcn_s_setprio(3); _Pragma("unroll") for (int m = 0; m < 4; ++m) _Pragma("unroll") for (int n = 0; n < 2; ++n) _Pragma("unroll") for (int k = 0; k < 2; ++k) \
;         acc[ai][bj][m][n] = __builtin_amdgcn_mfma_f32_16x16x32_bf16(Bt[n][k], At[m][k], acc[ai][bj][m][n], 0, 0, 0); __builtin_amdgcn_s_setprio(0); } while (0)
; #define PG8_WAIT_V(n) asm volatile("s_waitcnt vmcnt(" #n ")" ::: "memory")
; #define PG8_WAIT_L(n) asm volatile("s_waitcnt lgkmcnt(" #n ")" ::: "memory")
; template <class Epi, class Sched, bool ALIGN_EPI = false, bool SP2 = false>
; __device__ __forceinline__ void gemm_phase(PG8_LAS unsigned char* lds, const Gemm g, const Sched& S, const Epi& E) {
;     ...
;         for (int t = 0; t < nt; t += 2) {
;             const bool last = (t == nt - 2);
;             const char* a1 = cA + (size_t)(t + 1) * kstep;
;             const char* a2 = last ? nA : cA + (size_t)(t + 2) * kstep; const char* b2 = last ? nB : cB + (size_t)(t + 2) * kstep;
;             const char* a3 = a2 + kstep; const char* b3 = b2 + kstep;
;             if (last && has_next) S.a_ready(nxt);
;             if constexpr (Epi::MIDK) { if (t == E.midk_step(nt)) E.midk(acc, cur, wr, wc, fr, fq); }
;             if constexpr (SP2) {
;             PG8_LDB(B0, 0, 0); PG8_LDB(B1, 0, 1); PG8_SCHED; PG8_LDA(At, 0, 0); PG8_STAGE(PG8_SA(1, 1), a1 + hstepA, voffA);
;             PG8_WAIT_V(8); PG8_WAIT_L(0); PG8_BAR; PG8_MMA(0, 0, At, B0); PG8_MMA(0, 1, At, B1); PG8_BAR; PG8_SCHED;
;             PG8_LDA(At, 0, 1); PG8_STAGE(PG8_SB(0, 0), b2, voffB); PG8_STAGE(PG8_SB(0, 1), b2 + hstepB, voffB); PG8_STAGE(PG8_SA(0, 0), a2, voffA);
.LBB0_975:
	v_add_u32_e32 v144, s46, v206
	v_add_u32_e32 v160, s47, v206
	s_add_u32 s28, s2, s12
	ds_read_b128 v[132:135], v144
	ds_read_b128 v[136:139], v144 offset:1024
	ds_read_b128 v[140:143], v144 offset:2048
	ds_read_b128 v[144:147], v144 offset:3072
	ds_read_b128 v[148:151], v160
	ds_read_b128 v[152:155], v160 offset:1024
	ds_read_b128 v[156:159], v160 offset:2048
	ds_read_b128 v[160:163], v160 offset:3072
	s_addc_u32 s29, s3, s13
	s_add_u32 s28, s28, 0x21500100
	s_addc_u32 s29, s29, 0
	s_add_u32 s81, s44, s12
	s_addc_u32 s82, s45, s13
	s_cmpk_eq_i32 s12, 0x5500
	s_cselect_b32 s31, s1, s29
	s_cselect_b32 s30, s0, s28
	s_cselect_b32 s29, s11, s82
	s_cselect_b32 s28, s10, s81
	s_mov_b32 m0, s71
	v_lshl_add_u64 v[234:235], v[2:3], 0, s[12:13]
	ds_read_b128 v[164:167], v207
	ds_read_b128 v[168:171], v207 offset:1024
	ds_read_b128 v[210:213], v207 offset:2048
	ds_read_b128 v[214:217], v207 offset:3072
	ds_read_b128 v[218:221], v207 offset:4096
	ds_read_b128 v[222:225], v207 offset:5120
	ds_read_b128 v[226:229], v207 offset:6144
	ds_read_b128 v[230:233], v207 offset:7168
	global_load_lds_dwordx4 v[234:235], off
	v_lshl_add_u64 v[234:235], v[200:201], 0, s[12:13]
	s_mov_b32 m0, s72
	s_nop 0
	global_load_lds_dwordx4 v[234:235], off
	s_waitcnt vmcnt(8)
	s_waitcnt lgkmcnt(0)
	s_barrier
	s_setprio 3
	s_waitcnt lgkmcnt(0)
	v_mfma_f32_16x16x32_bf16 v[128:131], v[132:135], v[164:167], v[128:131]
	v_mfma_f32_16x16x32_bf16 v[124:127], v[140:143], v[164:167], v[124:127]
	v_mfma_f32_16x16x32_bf16 v[100:103], v[132:135], v[210:213], v[100:103]
	v_mfma_f32_16x16x32_bf16 v[96:99], v[140:143], v[210:213], v[96:99]
	v_mfma_f32_16x16x32_bf16 v[112:115], v[132:135], v[218:221], v[112:115]
	v_mfma_f32_16x16x32_bf16 v[108:111], v[140:143], v[218:221], v[108:111]
	v_mfma_f32_16x16x32_bf16 v[80:83], v[132:135], v[226:229], v[80:83]
	v_mfma_f32_16x16x32_bf16 v[76:79], v[140:143], v[226:229], v[76:79]
	v_mfma_f32_16x16x32_bf16 v[128:131], v[136:139], v[168:171], v[128:131]
	v_mfma_f32_16x16x32_bf16 v[124:127], v[144:147], v[168:171], v[124:127]
	v_mfma_f32_16x16x32_bf16 v[100:103], v[136:139], v[214:217], v[100:103]
	v_mfma_f32_16x16x32_bf16 v[96:99], v[144:147], v[214:217], v[96:99]
	v_mfma_f32_16x16x32_bf16 v[112:115], v[136:139], v[222:225], v[112:115]
	v_mfma_f32_16x16x32_bf16 v[108:111], v[144:147], v[222:225], v[108:111]
	v_mfma_f32_16x16x32_bf16 v[80:83], v[136:139], v[230:233], v[80:83]
	v_mfma_f32_16x16x32_bf16 v[76:79], v[144:147], v[230:233], v[76:79]
	s_setprio 0
	s_setprio 3
	v_mfma_f32_16x16x32_bf16 v[120:123], v[148:151], v[164:167], v[120:123]
	v_mfma_f32_16x16x32_bf16 v[116:119], v[156:159], v[164:167], v[116:119]
	v_mfma_f32_16x16x32_bf16 v[92:95], v[148:151], v[210:213], v[92:95]
	v_mfma_f32_16x16x32_bf16 v[88:91], v[156:159], v[210:213], v[88:91]
	v_mfma_f32_16x16x32_bf16 v[104:107], v[148:151], v[218:221], v[104:107]
	v_mfma_f32_16x16x32_bf16 v[84:87], v[156:159], v[218:221], v[84:87]
	v_mfma_f32_16x16x32_bf16 v[72:75], v[148:151], v[226:229], v[72:75]
	v_mfma_f32_16x16x32_bf16 v[68:71], v[156:159], v[226:229], v[68:71]
	v_mfma_f32_16x16x32_bf16 v[120:123], v[152:155], v[168:171], v[120:123]
	v_mfma_f32_16x16x32_bf16 v[116:119], v[160:163], v[168:171], v[116:119]
	v_mfma_f32_16x16x32_bf16 v[92:95], v[152:155], v[214:217], v[92:95]
	v_mfma_f32_16x16x32_bf16 v[88:91], v[160:163], v[214:217], v[88:91]
	v_mfma_f32_16x16x32_bf16 v[104:107], v[152:155], v[222:225], v[104:107]
	v_mfma_f32_16x16x32_bf16 v[84:87], v[160:163], v[222:225], v[84:87]
	v_mfma_f32_16x16x32_bf16 v[72:75], v[152:155], v[230:233], v[72:75]
	v_mfma_f32_16x16x32_bf16 v[68:71], v[160:163], v[230:233], v[68:71]
	s_setprio 0
	s_barrier
	s_mov_b32 m0, s73
	v_lshl_add_u64 v[234:235], s[28:29], 0, v[174:175]
	s_add_u32 s82, s28, 0x2b0000
	ds_read_b128 v[164:167], v207 offset:16384
	ds_read_b128 v[168:171], v207 offset:17408
	ds_read_b128 v[210:213], v207 offset:18432
	ds_read_b128 v[214:217], v207 offset:19456
	ds_read_b128 v[218:221], v207 offset:20480
	ds_read_b128 v[222:225], v207 offset:21504
	ds_read_b128 v[226:229], v207 offset:22528
	ds_read_b128 v[230:233], v207 offset:23552
	global_load_lds_dwordx4 v[234:235], off
	v_lshl_add_u64 v[236:237], s[28:29], 0, v[178:179]
	s_mov_b32 m0, s74
	s_addc_u32 s83, s29, 0
	global_load_lds_dwordx4 v[236:237], off
	v_lshl_add_u64 v[238:239], s[82:83], 0, v[174:175]
	s_mov_b32 m0, s75
	v_lshl_add_u64 v[240:241], s[30:31], 0, v[176:177]
	global_load_lds_dwordx4 v[238:239], off
	v_lshl_add_u64 v[238:239], s[82:83], 0, v[178:179]
	s_mov_b32 m0, s76
	s_nop 0
	global_load_lds_dwordx4 v[238:239], off
	v_lshl_add_u64 v[238:239], s[30:31], 0, v[172:173]
	s_waitcnt vmcnt(6)
	s_waitcnt lgkmcnt(0)
	s_barrier
; #define PG8_STAGE(bufoff, gbase, voff) do { _Pragma("unroll") for (int _i = 0; _i < 2; ++_i) \
;         __builtin_amdgcn_global_load_lds((const unsigned*)((const char*)(gbase) + (voff)[_i]), (PG8_LAS unsigned*)(lds + (bufoff) + ldsw + _i * 8192), 16, 0, 0); } while (0)
; #define PG8_LDA(dst, b, h) do { _Pragma("unroll") for (int m = 0; m < 4; ++m) _Pragma("unroll") for (int k = 0; k < 2; ++k) dst[m][k] = *(const PG8_LAS bf16x8*)(lds + PG8_SA(b, h) + aoff + m * 2048 + k * 1024); } while (0)
; #define PG8_LDB(dst, b, h) do { _Pragma("unroll") for (int n = 0; n < 2; ++n) _Pragma("unroll") for (int k = 0; k < 2; ++k) dst[n][k] = *(const PG8_LAS bf16x8*)(lds + PG8_SB(b, h) + boff + n * 2048 + k * 1024); } while (0)
; #define PG8_MMA(ai, bj, At, Bt) do { __builtin_amdgcn_s_setprio(3); _Pragma("unroll") for (int m = 0; m < 4; ++m) _Pragma("unroll") for (int n = 0; n < 2; ++n) _Pragma("unroll") for (int k = 0; k < 2; ++k) \
;         acc[ai][bj][m][n] = __builtin_amdgcn_mfma_f32_16x16x32_bf16(Bt[n][k], At[m][k], acc[ai][bj][m][n], 0, 0, 0); __builtin_amdgcn_s_setprio(0); } while (0)
; #define PG8_WAIT_V(n) asm volatile("s_waitcnt vmcnt(" #n ")" ::: "memory")
; #define PG8_WAIT_L(n) asm volatile("s_waitcnt lgkmcnt(" #n ")" ::: "memory")
; #define PG8_BAR __builtin_amdgcn_s_barrier()
; #define PG8_SCHED __builtin_amdgcn_sched_barrier(0)
; template <class Epi, class Sched, bool ALIGN_EPI = false, bool SP2 = false>
; __device__ __forceinline__ void gemm_phase(PG8_LAS unsigned char* lds, const Gemm g, const Sched& S, const Epi& E) {
;     ...
;             PG8_WAIT_V(8); PG8_WAIT_L(0); PG8_BAR; PG8_MMA(0, 0, At, B0); PG8_MMA(0, 1, At, B1); PG8_BAR; PG8_SCHED;
;             PG8_LDA(At, 0, 1); PG8_STAGE(PG8_SB(0, 0), b2, voffB); PG8_STAGE(PG8_SB(0, 1), b2 + hstepB, voffB); PG8_STAGE(PG8_SA(0, 0), a2, voffA);
;             PG8_WAIT_V(8); PG8_WAIT_L(0); PG8_BAR; PG8_MMA(1, 0, At, B0); PG8_MMA(1, 1, At, B1); PG8_BAR; PG8_SCHED;
;             PG8_LDB(B0, 1, 0); PG8_LDB(B1, 1, 1); PG8_SCHED; PG8_LDA(At, 1, 0); PG8_STAGE(PG8_SA(0, 1), a2 + hstepA, voffA);
;             PG8_WAIT_V(8); PG8_WAIT_L(0); PG8_BAR; PG8_MMA(0, 0, At, B0); PG8_MMA(0, 1, At, B1); PG8_BAR; PG8_SCHED;
	s_setprio 3
	s_waitcnt lgkmcnt(0)
	v_mfma_f32_16x16x32_bf16 v[64:67], v[132:135], v[164:167], v[64:67]
	v_mfma_f32_16x16x32_bf16 v[60:63], v[140:143], v[164:167], v[60:63]
	v_mfma_f32_16x16x32_bf16 v[48:51], v[132:135], v[210:213], v[48:51]
	v_mfma_f32_16x16x32_bf16 v[44:47], v[140:143], v[210:213], v[44:47]
	v_mfma_f32_16x16x32_bf16 v[32:35], v[132:135], v[218:221], v[32:35]
	v_mfma_f32_16x16x32_bf16 v[28:31], v[140:143], v[218:221], v[28:31]
	v_mfma_f32_16x16x32_bf16 v[16:19], v[132:135], v[226:229], v[16:19]
	v_mfma_f32_16x16x32_bf16 v[12:15], v[140:143], v[226:229], v[12:15]
	v_mfma_f32_16x16x32_bf16 v[64:67], v[136:139], v[168:171], v[64:67]
	v_mfma_f32_16x16x32_bf16 v[60:63], v[144:147], v[168:171], v[60:63]
	v_mfma_f32_16x16x32_bf16 v[48:51], v[136:139], v[214:217], v[48:51]
	v_mfma_f32_16x16x32_bf16 v[44:47], v[144:147], v[214:217], v[44:47]
	v_mfma_f32_16x16x32_bf16 v[32:35], v[136:139], v[222:225], v[32:35]
	v_mfma_f32_16x16x32_bf16 v[28:31], v[144:147], v[222:225], v[28:31]
	v_mfma_f32_16x16x32_bf16 v[16:19], v[136:139], v[230:233], v[16:19]
	v_mfma_f32_16x16x32_bf16 v[12:15], v[144:147], v[230:233], v[12:15]
	s_setprio 0
	s_setprio 3
	v_mfma_f32_16x16x32_bf16 v[56:59], v[148:151], v[164:167], v[56:59]
	v_mfma_f32_16x16x32_bf16 v[52:55], v[156:159], v[164:167], v[52:55]
	v_mfma_f32_16x16x32_bf16 v[40:43], v[148:151], v[210:213], v[40:43]
	v_mfma_f32_16x16x32_bf16 v[36:39], v[156:159], v[210:213], v[36:39]
	v_mfma_f32_16x16x32_bf16 v[24:27], v[148:151], v[218:221], v[24:27]
	v_mfma_f32_16x16x32_bf16 v[20:23], v[156:159], v[218:221], v[20:23]
	v_mfma_f32_16x16x32_bf16 v[8:11], v[148:151], v[226:229], v[8:11]
	v_mfma_f32_16x16x32_bf16 v[4:7], v[156:159], v[226:229], v[4:7]
	v_mfma_f32_16x16x32_bf16 v[56:59], v[152:155], v[168:171], v[56:59]
	v_mfma_f32_16x16x32_bf16 v[52:55], v[160:163], v[168:171], v[52:55]
	v_mfma_f32_16x16x32_bf16 v[40:43], v[152:155], v[214:217], v[40:43]
	v_mfma_f32_16x16x32_bf16 v[36:39], v[160:163], v[214:217], v[36:39]
	v_mfma_f32_16x16x32_bf16 v[24:27], v[152:155], v[222:225], v[24:27]
	v_mfma_f32_16x16x32_bf16 v[20:23], v[160:163], v[222:225], v[20:23]
	v_mfma_f32_16x16x32_bf16 v[8:11], v[152:155], v[230:233], v[8:11]
	v_mfma_f32_16x16x32_bf16 v[4:7], v[160:163], v[230:233], v[4:7]
	s_setprio 0
	s_barrier
	v_add_u32_e32 v144, s52, v206
	v_add_u32_e32 v160, s53, v206
	ds_read_b128 v[132:135], v144
	ds_read_b128 v[136:139], v144 offset:1024
	ds_read_b128 v[140:143], v144 offset:2048
	ds_read_b128 v[144:147], v144 offset:3072
	ds_read_b128 v[148:151], v160
	ds_read_b128 v[152:155], v160 offset:1024
	ds_read_b128 v[156:159], v160 offset:2048
	ds_read_b128 v[160:163], v160 offset:3072
	s_add_u32 s30, s30, 0x2b0000
	s_addc_u32 s31, s31, 0
	s_mov_b32 m0, s55
	v_lshl_add_u64 v[242:243], s[30:31], 0, v[172:173]
	ds_read_b128 v[164:167], v207 offset:32768
	ds_read_b128 v[168:171], v207 offset:33792
	ds_read_b128 v[210:213], v207 offset:34816
	ds_read_b128 v[214:217], v207 offset:35840
	ds_read_b128 v[218:221], v207 offset:36864
	ds_read_b128 v[222:225], v207 offset:37888
	ds_read_b128 v[226:229], v207 offset:38912
	ds_read_b128 v[230:233], v207 offset:39936
	s_mov_b32 m0, s42
	s_nop 0
	global_load_lds_dwordx4 v[238:239], off
	s_mov_b32 m0, s54
	s_nop 0
	global_load_lds_dwordx4 v[240:241], off
	s_mov_b32 m0, s55
	s_nop 0
	global_load_lds_dwordx4 v[242:243], off
	v_lshl_add_u64 v[242:243], s[30:31], 0, v[176:177]
	s_mov_b32 m0, s56
	s_nop 0
	global_load_lds_dwordx4 v[242:243], off
	s_waitcnt vmcnt(8)
	s_waitcnt lgkmcnt(0)
	s_barrier
	s_setprio 3
	s_waitcnt lgkmcnt(0)
	v_mfma_f32_16x16x32_bf16 v[128:131], v[132:135], v[164:167], v[128:131]
	v_mfma_f32_16x16x32_bf16 v[124:127], v[140:143], v[164:167], v[124:127]
	v_mfma_f32_16x16x32_bf16 v[100:103], v[132:135], v[210:213], v[100:103]
	v_mfma_f32_16x16x32_bf16 v[96:99], v[140:143], v[210:213], v[96:99]
	v_mfma_f32_16x16x32_bf16 v[112:115], v[132:135], v[218:221], v[112:115]
	v_mfma_f32_16x16x32_bf16 v[108:111], v[140:143], v[218:221], v[108:111]
	v_mfma_f32_16x16x32_bf16 v[80:83], v[132:135], v[226:229], v[80:83]
	v_mfma_f32_16x16x32_bf16 v[76:79], v[140:143], v[226:229], v[76:79]
	v_mfma_f32_16x16x32_bf16 v[128:131], v[136:139], v[168:171], v[128:131]
	v_mfma_f32_16x16x32_bf16 v[124:127], v[144:147], v[168:171], v[124:127]
	v_mfma_f32_16x16x32_bf16 v[100:103], v[136:139], v[214:217], v[100:103]
	v_mfma_f32_16x16x32_bf16 v[96:99], v[144:147], v[214:217], v[96:99]
	v_mfma_f32_16x16x32_bf16 v[112:115], v[136:139], v[222:225], v[112:115]
	v_mfma_f32_16x16x32_bf16 v[108:111], v[144:147], v[222:225], v[108:111]
	v_mfma_f32_16x16x32_bf16 v[80:83], v[136:139], v[230:233], v[80:83]
	v_mfma_f32_16x16x32_bf16 v[76:79], v[144:147], v[230:233], v[76:79]
	s_setprio 0
	s_setprio 3
	v_mfma_f32_16x16x32_bf16 v[120:123], v[148:151], v[164:167], v[120:123]
	v_mfma_f32_16x16x32_bf16 v[116:119], v[156:159], v[164:167], v[116:119]
	v_mfma_f32_16x16x32_bf16 v[92:95], v[148:151], v[210:213], v[92:95]
	v_mfma_f32_16x16x32_bf16 v[88:91], v[156:159], v[210:213], v[88:91]
	v_mfma_f32_16x16x32_bf16 v[104:107], v[148:151], v[218:221], v[104:107]
	v_mfma_f32_16x16x32_bf16 v[84:87], v[156:159], v[218:221], v[84:87]
	v_mfma_f32_16x16x32_bf16 v[72:75], v[148:151], v[226:229], v[72:75]
	v_mfma_f32_16x16x32_bf16 v[68:71], v[156:159], v[226:229], v[68:71]
	v_mfma_f32_16x16x32_bf16 v[120:123], v[152:155], v[168:171], v[120:123]
	v_mfma_f32_16x16x32_bf16 v[116:119], v[160:163], v[168:171], v[116:119]
	v_mfma_f32_16x16x32_bf16 v[92:95], v[152:155], v[214:217], v[92:95]
	v_mfma_f32_16x16x32_bf16 v[88:91], v[160:163], v[214:217], v[88:91]
	v_mfma_f32_16x16x32_bf16 v[104:107], v[152:155], v[222:225], v[104:107]
	v_mfma_f32_16x16x32_bf16 v[84:87], v[160:163], v[222:225], v[84:87]
	v_mfma_f32_16x16x32_bf16 v[72:75], v[152:155], v[230:233], v[72:75]
	v_mfma_f32_16x16x32_bf16 v[68:71], v[160:163], v[230:233], v[68:71]
	s_setprio 0
	s_barrier
; #define PG8_STAGE(bufoff, gbase, voff) do { _Pragma("unroll") for (int _i = 0; _i < 2; ++_i) \
;         __builtin_amdgcn_global_load_lds((const unsigned*)((const char*)(gbase) + (voff)[_i]), (PG8_LAS unsigned*)(lds + (bufoff) + ldsw + _i * 8192), 16, 0, 0); } while (0)
; #define PG8_LDA(dst, b, h) do { _Pragma("unroll") for (int m = 0; m < 4; ++m) _Pragma("unroll") for (int k = 0; k < 2; ++k) dst[m][k] = *(const PG8_LAS bf16x8*)(lds + PG8_SA(b, h) + aoff + m * 2048 + k * 1024); } while (0)
; #define PG8_MMA(ai, bj, At, Bt) do { __builtin_amdgcn_s_setprio(3); _Pragma("unroll") for (int m = 0; m < 4; ++m) _Pragma("unroll") for (int n = 0; n < 2; ++n) _Pragma("unroll") for (int k = 0; k < 2; ++k) \
;         acc[ai][bj][m][n] = __builtin_amdgcn_mfma_f32_16x16x32_bf16(Bt[n][k], At[m][k], acc[ai][bj][m][n], 0, 0, 0); __builtin_amdgcn_s_setprio(0); } while (0)
; #define PG8_WAIT_V(n) asm volatile("s_waitcnt vmcnt(" #n ")" ::: "memory")
; #define PG8_WAIT_L(n) asm volatile("s_waitcnt lgkmcnt(" #n ")" ::: "memory")
; #define PG8_BAR __builtin_amdgcn_s_barrier()
; #define PG8_SCHED __builtin_amdgcn_sched_barrier(0)
; template <class Epi, class Sched, bool ALIGN_EPI = false, bool SP2 = false>
; __device__ __forceinline__ void gemm_phase(PG8_LAS unsigned char* lds, const Gemm g, const Sched& S, const Epi& E) {
;     ...
;             PG8_LDA(At, 1, 1); PG8_STAGE(PG8_SB(1, 0), b3, voffB); PG8_STAGE(PG8_SB(1, 1), b3 + hstepB, voffB); PG8_STAGE(PG8_SA(1, 0), a3, voffA);
;             PG8_WAIT_V(8); PG8_WAIT_L(0); PG8_BAR; PG8_MMA(1, 0, At, B0); PG8_MMA(1, 1, At, B1); PG8_BAR; PG8_SCHED;
	s_mov_b32 m0, s77
	v_lshl_add_u64 v[234:235], v[234:235], 0, s[4:5]
	s_add_u32 s28, s28, 0x2b0080
	ds_read_b128 v[164:167], v207 offset:49152
	ds_read_b128 v[168:171], v207 offset:50176
	ds_read_b128 v[210:213], v207 offset:51200
	ds_read_b128 v[214:217], v207 offset:52224
	ds_read_b128 v[218:221], v207 offset:53248
	ds_read_b128 v[222:225], v207 offset:54272
	ds_read_b128 v[226:229], v207 offset:55296
	ds_read_b128 v[230:233], v207 offset:56320
	global_load_lds_dwordx4 v[234:235], off
	v_lshl_add_u64 v[234:235], v[236:237], 0, s[4:5]
	s_mov_b32 m0, s78
	s_addc_u32 s29, s29, 0
	global_load_lds_dwordx4 v[234:235], off
	v_lshl_add_u64 v[234:235], s[28:29], 0, v[174:175]
	s_mov_b32 m0, s79
	s_nop 0
	global_load_lds_dwordx4 v[234:235], off
	v_lshl_add_u64 v[234:235], s[28:29], 0, v[178:179]
	s_mov_b32 m0, s80
	s_nop 0
	global_load_lds_dwordx4 v[234:235], off
	v_lshl_add_u64 v[234:235], v[238:239], 0, s[4:5]
	s_mov_b32 m0, s57
	s_nop 0
	global_load_lds_dwordx4 v[234:235], off
	v_lshl_add_u64 v[234:235], v[240:241], 0, s[4:5]
	s_mov_b32 m0, s58
	s_nop 0
	global_load_lds_dwordx4 v[234:235], off
	s_waitcnt vmcnt(8)
	s_waitcnt lgkmcnt(0)
	s_barrier
	s_setprio 3
	s_waitcnt lgkmcnt(0)
	v_mfma_f32_16x16x32_bf16 v[64:67], v[132:135], v[164:167], v[64:67]
	v_mfma_f32_16x16x32_bf16 v[60:63], v[140:143], v[164:167], v[60:63]
	v_mfma_f32_16x16x32_bf16 v[48:51], v[132:135], v[210:213], v[48:51]
	v_mfma_f32_16x16x32_bf16 v[44:47], v[140:143], v[210:213], v[44:47]
	v_mfma_f32_16x16x32_bf16 v[32:35], v[132:135], v[218:221], v[32:35]
	v_mfma_f32_16x16x32_bf16 v[28:31], v[140:143], v[218:221], v[28:31]
	v_mfma_f32_16x16x32_bf16 v[16:19], v[132:135], v[226:229], v[16:19]
	v_mfma_f32_16x16x32_bf16 v[12:15], v[140:143], v[226:229], v[12:15]
	v_mfma_f32_16x16x32_bf16 v[64:67], v[136:139], v[168:171], v[64:67]
	v_mfma_f32_16x16x32_bf16 v[60:63], v[144:147], v[168:171], v[60:63]
	v_mfma_f32_16x16x32_bf16 v[48:51], v[136:139], v[214:217], v[48:51]
	v_mfma_f32_16x16x32_bf16 v[44:47], v[144:147], v[214:217], v[44:47]
	v_mfma_f32_16x16x32_bf16 v[32:35], v[136:139], v[222:225], v[32:35]
	v_mfma_f32_16x16x32_bf16 v[28:31], v[144:147], v[222:225], v[28:31]
	v_mfma_f32_16x16x32_bf16 v[16:19], v[136:139], v[230:233], v[16:19]
	v_mfma_f32_16x16x32_bf16 v[12:15], v[144:147], v[230:233], v[12:15]
	s_setprio 0
	s_setprio 3
	v_mfma_f32_16x16x32_bf16 v[56:59], v[148:151], v[164:167], v[56:59]
	v_mfma_f32_16x16x32_bf16 v[52:55], v[156:159], v[164:167], v[52:55]
	v_mfma_f32_16x16x32_bf16 v[40:43], v[148:151], v[210:213], v[40:43]
	v_mfma_f32_16x16x32_bf16 v[36:39], v[156:159], v[210:213], v[36:39]
	v_mfma_f32_16x16x32_bf16 v[24:27], v[148:151], v[218:221], v[24:27]
	v_mfma_f32_16x16x32_bf16 v[20:23], v[156:159], v[218:221], v[20:23]
	v_mfma_f32_16x16x32_bf16 v[8:11], v[148:151], v[226:229], v[8:11]
	v_mfma_f32_16x16x32_bf16 v[4:7], v[156:159], v[226:229], v[4:7]
	v_mfma_f32_16x16x32_bf16 v[56:59], v[152:155], v[168:171], v[56:59]
	v_mfma_f32_16x16x32_bf16 v[52:55], v[160:163], v[168:171], v[52:55]
	v_mfma_f32_16x16x32_bf16 v[40:43], v[152:155], v[214:217], v[40:43]
	v_mfma_f32_16x16x32_bf16 v[36:39], v[160:163], v[214:217], v[36:39]
	v_mfma_f32_16x16x32_bf16 v[24:27], v[152:155], v[222:225], v[24:27]
	v_mfma_f32_16x16x32_bf16 v[20:23], v[160:163], v[222:225], v[20:23]
	v_mfma_f32_16x16x32_bf16 v[8:11], v[152:155], v[230:233], v[8:11]
	v_mfma_f32_16x16x32_bf16 v[4:7], v[160:163], v[230:233], v[4:7]
	s_setprio 0
	s_barrier
	s_add_i32 s61, s61, 2
	s_add_u32 s12, s12, 0x100
	s_addc_u32 s13, s13, 0
	s_cmpk_gt_u32 s61, 0xa9
	s_cbranch_scc1 .LBB0_978

; #define PG8_STAGE(bufoff, gbase, voff) do { _Pragma("unroll") for (int _i = 0; _i < 2; ++_i) \
;         __builtin_amdgcn_global_load_lds((const unsigned*)((const char*)(gbase) + (voff)[_i]), (PG8_LAS unsigned*)(lds + (bufoff) + ldsw + _i * 8192), 16, 0, 0); } while (0)
; #define PG8_LDA(dst, b, h) do { _Pragma("unroll") for (int m = 0; m < 4; ++m) _Pragma("unroll") for (int k = 0; k < 2; ++k) dst[m][k] = *(const PG8_LAS bf16x8*)(lds + PG8_SA(b, h) + aoff + m * 2048 + k * 1024); } while (0)
; #define PG8_LDB(dst, b, h) do { _Pragma("unroll") for (int n = 0; n < 2; ++n) _Pragma("unroll") for (int k = 0; k < 2; ++k) dst[n][k] = *(const PG8_LAS bf16x8*)(lds + PG8_SB(b, h) + boff + n * 2048 + k * 1024); } while (0)
; #define PG8_MMA(ai, bj, At, Bt) do { __builtin_amdgcn_s_setprio(3); _Pragma("unroll") for (int m = 0; m < 4; ++m) _Pragma("unroll") for (int n = 0; n < 2; ++n) _Pragma("unroll") for (int k = 0; k < 2; ++k) \
;         acc[ai][bj][m][n] = __builtin_amdgcn_mfma_f32_16x16x32_bf16(Bt[n][k], At[m][k], acc[ai][bj][m][n], 0, 0, 0); __builtin_amdgcn_s_setprio(0); } while (0)
; #define PG8_WAIT_V(n) asm volatile("s_waitcnt vmcnt(" #n ")" ::: "memory")
; #define PG8_WAIT_L(n) asm volatile("s_waitcnt lgkmcnt(" #n ")" ::: "memory")
; template <class Epi, class Sched, bool ALIGN_EPI = false, bool SP2 = false>
; __device__ __forceinline__ void gemm_phase(PG8_LAS unsigned char* lds, const Gemm g, const Sched& S, const Epi& E) {
;     ...
;         for (int t = 0; t < nt; t += 2) {
;             const bool last = (t == nt - 2);
;             const char* a1 = cA + (size_t)(t + 1) * kstep;
;             const char* a2 = last ? nA : cA + (size_t)(t + 2) * kstep; const char* b2 = last ? nB : cB + (size_t)(t + 2) * kstep;
;             const char* a3 = a2 + kstep; const char* b3 = b2 + kstep;
;             if (last && has_next) S.a_ready(nxt);
;             if constexpr (Epi::MIDK) { if (t == E.midk_step(nt)) E.midk(acc, cur, wr, wc, fr, fq); }
;             if constexpr (SP2) {
;             PG8_LDB(B0, 0, 0); PG8_LDB(B1, 0, 1); PG8_SCHED; PG8_LDA(At, 0, 0); PG8_STAGE(PG8_SA(1, 1), a1 + hstepA, voffA);
;             PG8_WAIT_V(8); PG8_WAIT_L(0); PG8_BAR; PG8_MMA(0, 0, At, B0); PG8_MMA(0, 1, At, B1); PG8_BAR; PG8_SCHED;
;             PG8_LDA(At, 0, 1); PG8_STAGE(PG8_SB(0, 0), b2, voffB); PG8_STAGE(PG8_SB(0, 1), b2 + hstepB, voffB); PG8_STAGE(PG8_SA(0, 0), a2, voffA);
.LBB0_1018:
	v_add_u32_e32 v142, s46, v189
	v_add_u32_e32 v158, s47, v189
	s_add_u32 s40, s20, s22
	ds_read_b128 v[130:133], v142
	ds_read_b128 v[134:137], v142 offset:1024
	ds_read_b128 v[138:141], v142 offset:2048
	ds_read_b128 v[142:145], v142 offset:3072
	ds_read_b128 v[146:149], v158
	ds_read_b128 v[150:153], v158 offset:1024
	ds_read_b128 v[154:157], v158 offset:2048
	ds_read_b128 v[158:161], v158 offset:3072
	s_addc_u32 s41, s21, s23
	s_add_u32 s40, s40, 0x21500100
	s_addc_u32 s41, s41, 0
	s_add_u32 s87, s44, s22
	s_addc_u32 s88, s45, s23
	s_cmpk_eq_i32 s22, 0x5500
	s_cselect_b32 s43, s17, s41
	s_cselect_b32 s42, s16, s40
	s_cselect_b32 s41, s11, s88
	s_cselect_b32 s40, s10, s87
	s_mov_b32 m0, s77
	v_lshl_add_u64 v[186:187], v[0:1], 0, s[22:23]
	ds_read_b128 v[162:165], v180
	ds_read_b128 v[166:169], v180 offset:1024
	ds_read_b128 v[182:185], v180 offset:2048
	ds_read_b128 v[190:193], v180 offset:3072
	ds_read_b128 v[194:197], v180 offset:4096
	ds_read_b128 v[208:211], v180 offset:5120
	ds_read_b128 v[212:215], v180 offset:6144
	ds_read_b128 v[216:219], v180 offset:7168
	global_load_lds_dwordx4 v[186:187], off
	v_lshl_add_u64 v[186:187], v[170:171], 0, s[22:23]
	s_mov_b32 m0, s78
	s_nop 0
	global_load_lds_dwordx4 v[186:187], off
	s_waitcnt vmcnt(8)
	s_waitcnt lgkmcnt(0)
	s_barrier
	s_setprio 3
	s_waitcnt lgkmcnt(0)
	v_mfma_f32_16x16x32_bf16 v[126:129], v[130:133], v[162:165], v[126:129]
	v_mfma_f32_16x16x32_bf16 v[122:125], v[138:141], v[162:165], v[122:125]
	v_mfma_f32_16x16x32_bf16 v[98:101], v[130:133], v[182:185], v[98:101]
	v_mfma_f32_16x16x32_bf16 v[94:97], v[138:141], v[182:185], v[94:97]
	v_mfma_f32_16x16x32_bf16 v[110:113], v[130:133], v[194:197], v[110:113]
	v_mfma_f32_16x16x32_bf16 v[106:109], v[138:141], v[194:197], v[106:109]
	v_mfma_f32_16x16x32_bf16 v[78:81], v[130:133], v[212:215], v[78:81]
	v_mfma_f32_16x16x32_bf16 v[74:77], v[138:141], v[212:215], v[74:77]
	v_mfma_f32_16x16x32_bf16 v[126:129], v[134:137], v[166:169], v[126:129]
	v_mfma_f32_16x16x32_bf16 v[122:125], v[142:145], v[166:169], v[122:125]
	v_mfma_f32_16x16x32_bf16 v[98:101], v[134:137], v[190:193], v[98:101]
	v_mfma_f32_16x16x32_bf16 v[94:97], v[142:145], v[190:193], v[94:97]
	v_mfma_f32_16x16x32_bf16 v[110:113], v[134:137], v[208:211], v[110:113]
	v_mfma_f32_16x16x32_bf16 v[106:109], v[142:145], v[208:211], v[106:109]
	v_mfma_f32_16x16x32_bf16 v[78:81], v[134:137], v[216:219], v[78:81]
	v_mfma_f32_16x16x32_bf16 v[74:77], v[142:145], v[216:219], v[74:77]
	s_setprio 0
	s_setprio 3
	v_mfma_f32_16x16x32_bf16 v[118:121], v[146:149], v[162:165], v[118:121]
	v_mfma_f32_16x16x32_bf16 v[114:117], v[154:157], v[162:165], v[114:117]
	v_mfma_f32_16x16x32_bf16 v[90:93], v[146:149], v[182:185], v[90:93]
	v_mfma_f32_16x16x32_bf16 v[86:89], v[154:157], v[182:185], v[86:89]
	v_mfma_f32_16x16x32_bf16 v[102:105], v[146:149], v[194:197], v[102:105]
	v_mfma_f32_16x16x32_bf16 v[82:85], v[154:157], v[194:197], v[82:85]
	v_mfma_f32_16x16x32_bf16 v[70:73], v[146:149], v[212:215], v[70:73]
	v_mfma_f32_16x16x32_bf16 v[66:69], v[154:157], v[212:215], v[66:69]
	v_mfma_f32_16x16x32_bf16 v[118:121], v[150:153], v[166:169], v[118:121]
	v_mfma_f32_16x16x32_bf16 v[114:117], v[158:161], v[166:169], v[114:117]
	v_mfma_f32_16x16x32_bf16 v[90:93], v[150:153], v[190:193], v[90:93]
	v_mfma_f32_16x16x32_bf16 v[86:89], v[158:161], v[190:193], v[86:89]
	v_mfma_f32_16x16x32_bf16 v[102:105], v[150:153], v[208:211], v[102:105]
	v_mfma_f32_16x16x32_bf16 v[82:85], v[158:161], v[208:211], v[82:85]
	v_mfma_f32_16x16x32_bf16 v[70:73], v[150:153], v[216:219], v[70:73]
	v_mfma_f32_16x16x32_bf16 v[66:69], v[158:161], v[216:219], v[66:69]
	s_setprio 0
	s_barrier
	s_mov_b32 m0, s79
	v_lshl_add_u64 v[186:187], s[40:41], 0, v[174:175]
	s_add_u32 s88, s40, 0x2b0000
	ds_read_b128 v[162:165], v180 offset:16384
	ds_read_b128 v[166:169], v180 offset:17408
	ds_read_b128 v[182:185], v180 offset:18432
	ds_read_b128 v[190:193], v180 offset:19456
	ds_read_b128 v[194:197], v180 offset:20480
	ds_read_b128 v[208:211], v180 offset:21504
	ds_read_b128 v[212:215], v180 offset:22528
	ds_read_b128 v[216:219], v180 offset:23552
	global_load_lds_dwordx4 v[186:187], off
	v_lshl_add_u64 v[198:199], s[40:41], 0, v[178:179]
	s_mov_b32 m0, s80
	s_addc_u32 s89, s41, 0
	global_load_lds_dwordx4 v[198:199], off
	v_lshl_add_u64 v[204:205], s[88:89], 0, v[174:175]
	s_mov_b32 m0, s81
	v_lshl_add_u64 v[220:221], s[42:43], 0, v[176:177]
	global_load_lds_dwordx4 v[204:205], off
	v_lshl_add_u64 v[204:205], s[88:89], 0, v[178:179]
	s_mov_b32 m0, s82
	s_nop 0
	global_load_lds_dwordx4 v[204:205], off
	v_lshl_add_u64 v[204:205], s[42:43], 0, v[172:173]
	s_waitcnt vmcnt(6)
	s_waitcnt lgkmcnt(0)
	s_barrier
; #define PG8_STAGE(bufoff, gbase, voff) do { _Pragma("unroll") for (int _i = 0; _i < 2; ++_i) \
;         __builtin_amdgcn_global_load_lds((const unsigned*)((const char*)(gbase) + (voff)[_i]), (PG8_LAS unsigned*)(lds + (bufoff) + ldsw + _i * 8192), 16, 0, 0); } while (0)
; #define PG8_LDA(dst, b, h) do { _Pragma("unroll") for (int m = 0; m < 4; ++m) _Pragma("unroll") for (int k = 0; k < 2; ++k) dst[m][k] = *(const PG8_LAS bf16x8*)(lds + PG8_SA(b, h) + aoff + m * 2048 + k * 1024); } while (0)
; #define PG8_LDB(dst, b, h) do { _Pragma("unroll") for (int n = 0; n < 2; ++n) _Pragma("unroll") for (int k = 0; k < 2; ++k) dst[n][k] = *(const PG8_LAS bf16x8*)(lds + PG8_SB(b, h) + boff + n * 2048 + k * 1024); } while (0)
; #define PG8_MMA(ai, bj, At, Bt) do { __builtin_amdgcn_s_setprio(3); _Pragma("unroll") for (int m = 0; m < 4; ++m) _Pragma("unroll") for (int n = 0; n < 2; ++n) _Pragma("unroll") for (int k = 0; k < 2; ++k) \
;         acc[ai][bj][m][n] = __builtin_amdgcn_mfma_f32_16x16x32_bf16(Bt[n][k], At[m][k], acc[ai][bj][m][n], 0, 0, 0); __builtin_amdgcn_s_setprio(0); } while (0)
; #define PG8_WAIT_V(n) asm volatile("s_waitcnt vmcnt(" #n ")" ::: "memory")
; #define PG8_WAIT_L(n) asm volatile("s_waitcnt lgkmcnt(" #n ")" ::: "memory")
; #define PG8_BAR __builtin_amdgcn_s_barrier()
; #define PG8_SCHED __builtin_amdgcn_sched_barrier(0)
; template <class Epi, class Sched, bool ALIGN_EPI = false, bool SP2 = false>
; __device__ __forceinline__ void gemm_phase(PG8_LAS unsigned char* lds, const Gemm g, const Sched& S, const Epi& E) {
;     ...
;             PG8_WAIT_V(8); PG8_WAIT_L(0); PG8_BAR; PG8_MMA(0, 0, At, B0); PG8_MMA(0, 1, At, B1); PG8_BAR; PG8_SCHED;
;             PG8_LDA(At, 0, 1); PG8_STAGE(PG8_SB(0, 0), b2, voffB); PG8_STAGE(PG8_SB(0, 1), b2 + hstepB, voffB); PG8_STAGE(PG8_SA(0, 0), a2, voffA);
;             PG8_WAIT_V(8); PG8_WAIT_L(0); PG8_BAR; PG8_MMA(1, 0, At, B0); PG8_MMA(1, 1, At, B1); PG8_BAR; PG8_SCHED;
;             PG8_LDB(B0, 1, 0); PG8_LDB(B1, 1, 1); PG8_SCHED; PG8_LDA(At, 1, 0); PG8_STAGE(PG8_SA(0, 1), a2 + hstepA, voffA);
;             PG8_WAIT_V(8); PG8_WAIT_L(0); PG8_BAR; PG8_MMA(0, 0, At, B0); PG8_MMA(0, 1, At, B1); PG8_BAR; PG8_SCHED;
	s_setprio 3
	s_waitcnt lgkmcnt(0)
	v_mfma_f32_16x16x32_bf16 v[62:65], v[130:133], v[162:165], v[62:65]
	v_mfma_f32_16x16x32_bf16 v[58:61], v[138:141], v[162:165], v[58:61]
	v_mfma_f32_16x16x32_bf16 v[46:49], v[130:133], v[182:185], v[46:49]
	v_mfma_f32_16x16x32_bf16 v[42:45], v[138:141], v[182:185], v[42:45]
	v_mfma_f32_16x16x32_bf16 v[30:33], v[130:133], v[194:197], v[30:33]
	v_mfma_f32_16x16x32_bf16 v[26:29], v[138:141], v[194:197], v[26:29]
	v_mfma_f32_16x16x32_bf16 v[14:17], v[130:133], v[212:215], v[14:17]
	v_mfma_f32_16x16x32_bf16 v[10:13], v[138:141], v[212:215], v[10:13]
	v_mfma_f32_16x16x32_bf16 v[62:65], v[134:137], v[166:169], v[62:65]
	v_mfma_f32_16x16x32_bf16 v[58:61], v[142:145], v[166:169], v[58:61]
	v_mfma_f32_16x16x32_bf16 v[46:49], v[134:137], v[190:193], v[46:49]
	v_mfma_f32_16x16x32_bf16 v[42:45], v[142:145], v[190:193], v[42:45]
	v_mfma_f32_16x16x32_bf16 v[30:33], v[134:137], v[208:211], v[30:33]
	v_mfma_f32_16x16x32_bf16 v[26:29], v[142:145], v[208:211], v[26:29]
	v_mfma_f32_16x16x32_bf16 v[14:17], v[134:137], v[216:219], v[14:17]
	v_mfma_f32_16x16x32_bf16 v[10:13], v[142:145], v[216:219], v[10:13]
	s_setprio 0
	s_setprio 3
	v_mfma_f32_16x16x32_bf16 v[54:57], v[146:149], v[162:165], v[54:57]
	v_mfma_f32_16x16x32_bf16 v[50:53], v[154:157], v[162:165], v[50:53]
	v_mfma_f32_16x16x32_bf16 v[38:41], v[146:149], v[182:185], v[38:41]
	v_mfma_f32_16x16x32_bf16 v[34:37], v[154:157], v[182:185], v[34:37]
	v_mfma_f32_16x16x32_bf16 v[22:25], v[146:149], v[194:197], v[22:25]
	v_mfma_f32_16x16x32_bf16 v[18:21], v[154:157], v[194:197], v[18:21]
	v_mfma_f32_16x16x32_bf16 v[6:9], v[146:149], v[212:215], v[6:9]
	v_mfma_f32_16x16x32_bf16 v[2:5], v[154:157], v[212:215], v[2:5]
	v_mfma_f32_16x16x32_bf16 v[54:57], v[150:153], v[166:169], v[54:57]
	v_mfma_f32_16x16x32_bf16 v[50:53], v[158:161], v[166:169], v[50:53]
	v_mfma_f32_16x16x32_bf16 v[38:41], v[150:153], v[190:193], v[38:41]
	v_mfma_f32_16x16x32_bf16 v[34:37], v[158:161], v[190:193], v[34:37]
	v_mfma_f32_16x16x32_bf16 v[22:25], v[150:153], v[208:211], v[22:25]
	v_mfma_f32_16x16x32_bf16 v[18:21], v[158:161], v[208:211], v[18:21]
	v_mfma_f32_16x16x32_bf16 v[6:9], v[150:153], v[216:219], v[6:9]
	v_mfma_f32_16x16x32_bf16 v[2:5], v[158:161], v[216:219], v[2:5]
	s_setprio 0
	s_barrier
	v_add_u32_e32 v142, s52, v189
	v_add_u32_e32 v158, s53, v189
	ds_read_b128 v[130:133], v142
	ds_read_b128 v[134:137], v142 offset:1024
	ds_read_b128 v[138:141], v142 offset:2048
	ds_read_b128 v[142:145], v142 offset:3072
	ds_read_b128 v[146:149], v158
	ds_read_b128 v[150:153], v158 offset:1024
	ds_read_b128 v[154:157], v158 offset:2048
	ds_read_b128 v[158:161], v158 offset:3072
	s_add_u32 s42, s42, 0x2b0000
	s_addc_u32 s43, s43, 0
	s_mov_b32 m0, s61
	v_lshl_add_u64 v[222:223], s[42:43], 0, v[172:173]
	ds_read_b128 v[162:165], v180 offset:32768
	ds_read_b128 v[166:169], v180 offset:33792
	ds_read_b128 v[182:185], v180 offset:34816
	ds_read_b128 v[190:193], v180 offset:35840
	ds_read_b128 v[194:197], v180 offset:36864
	ds_read_b128 v[208:211], v180 offset:37888
	ds_read_b128 v[212:215], v180 offset:38912
	ds_read_b128 v[216:219], v180 offset:39936
	s_mov_b32 m0, s58
	s_nop 0
	global_load_lds_dwordx4 v[204:205], off
	s_mov_b32 m0, s60
	s_nop 0
	global_load_lds_dwordx4 v[220:221], off
	s_mov_b32 m0, s61
	s_nop 0
	global_load_lds_dwordx4 v[222:223], off
	v_lshl_add_u64 v[222:223], s[42:43], 0, v[176:177]
	s_mov_b32 m0, s62
	s_nop 0
	global_load_lds_dwordx4 v[222:223], off
	s_waitcnt vmcnt(8)
	s_waitcnt lgkmcnt(0)
	s_barrier
	s_setprio 3
	s_waitcnt lgkmcnt(0)
	v_mfma_f32_16x16x32_bf16 v[126:129], v[130:133], v[162:165], v[126:129]
	v_mfma_f32_16x16x32_bf16 v[122:125], v[138:141], v[162:165], v[122:125]
	v_mfma_f32_16x16x32_bf16 v[98:101], v[130:133], v[182:185], v[98:101]
	v_mfma_f32_16x16x32_bf16 v[94:97], v[138:141], v[182:185], v[94:97]
	v_mfma_f32_16x16x32_bf16 v[110:113], v[130:133], v[194:197], v[110:113]
	v_mfma_f32_16x16x32_bf16 v[106:109], v[138:141], v[194:197], v[106:109]
	v_mfma_f32_16x16x32_bf16 v[78:81], v[130:133], v[212:215], v[78:81]
	v_mfma_f32_16x16x32_bf16 v[74:77], v[138:141], v[212:215], v[74:77]
	v_mfma_f32_16x16x32_bf16 v[126:129], v[134:137], v[166:169], v[126:129]
	v_mfma_f32_16x16x32_bf16 v[122:125], v[142:145], v[166:169], v[122:125]
	v_mfma_f32_16x16x32_bf16 v[98:101], v[134:137], v[190:193], v[98:101]
	v_mfma_f32_16x16x32_bf16 v[94:97], v[142:145], v[190:193], v[94:97]
	v_mfma_f32_16x16x32_bf16 v[110:113], v[134:137], v[208:211], v[110:113]
	v_mfma_f32_16x16x32_bf16 v[106:109], v[142:145], v[208:211], v[106:109]
	v_mfma_f32_16x16x32_bf16 v[78:81], v[134:137], v[216:219], v[78:81]
	v_mfma_f32_16x16x32_bf16 v[74:77], v[142:145], v[216:219], v[74:77]
	s_setprio 0
	s_setprio 3
	v_mfma_f32_16x16x32_bf16 v[118:121], v[146:149], v[162:165], v[118:121]
	v_mfma_f32_16x16x32_bf16 v[114:117], v[154:157], v[162:165], v[114:117]
	v_mfma_f32_16x16x32_bf16 v[90:93], v[146:149], v[182:185], v[90:93]
	v_mfma_f32_16x16x32_bf16 v[86:89], v[154:157], v[182:185], v[86:89]
	v_mfma_f32_16x16x32_bf16 v[102:105], v[146:149], v[194:197], v[102:105]
	v_mfma_f32_16x16x32_bf16 v[82:85], v[154:157], v[194:197], v[82:85]
	v_mfma_f32_16x16x32_bf16 v[70:73], v[146:149], v[212:215], v[70:73]
	v_mfma_f32_16x16x32_bf16 v[66:69], v[154:157], v[212:215], v[66:69]
	v_mfma_f32_16x16x32_bf16 v[118:121], v[150:153], v[166:169], v[118:121]
	v_mfma_f32_16x16x32_bf16 v[114:117], v[158:161], v[166:169], v[114:117]
	v_mfma_f32_16x16x32_bf16 v[90:93], v[150:153], v[190:193], v[90:93]
	v_mfma_f32_16x16x32_bf16 v[86:89], v[158:161], v[190:193], v[86:89]
	v_mfma_f32_16x16x32_bf16 v[102:105], v[150:153], v[208:211], v[102:105]
	v_mfma_f32_16x16x32_bf16 v[82:85], v[158:161], v[208:211], v[82:85]
	v_mfma_f32_16x16x32_bf16 v[70:73], v[150:153], v[216:219], v[70:73]
	v_mfma_f32_16x16x32_bf16 v[66:69], v[158:161], v[216:219], v[66:69]
	s_setprio 0
	s_barrier
; #define PG8_STAGE(bufoff, gbase, voff) do { _Pragma("unroll") for (int _i = 0; _i < 2; ++_i) \
;         __builtin_amdgcn_global_load_lds((const unsigned*)((const char*)(gbase) + (voff)[_i]), (PG8_LAS unsigned*)(lds + (bufoff) + ldsw + _i * 8192), 16, 0, 0); } while (0)
; #define PG8_LDA(dst, b, h) do { _Pragma("unroll") for (int m = 0; m < 4; ++m) _Pragma("unroll") for (int k = 0; k < 2; ++k) dst[m][k] = *(const PG8_LAS bf16x8*)(lds + PG8_SA(b, h) + aoff + m * 2048 + k * 1024); } while (0)
; #define PG8_MMA(ai, bj, At, Bt) do { __builtin_amdgcn_s_setprio(3); _Pragma("unroll") for (int m = 0; m < 4; ++m) _Pragma("unroll") for (int n = 0; n < 2; ++n) _Pragma("unroll") for (int k = 0; k < 2; ++k) \
;         acc[ai][bj][m][n] = __builtin_amdgcn_mfma_f32_16x16x32_bf16(Bt[n][k], At[m][k], acc[ai][bj][m][n], 0, 0, 0); __builtin_amdgcn_s_setprio(0); } while (0)
; #define PG8_WAIT_V(n) asm volatile("s_waitcnt vmcnt(" #n ")" ::: "memory")
; #define PG8_WAIT_L(n) asm volatile("s_waitcnt lgkmcnt(" #n ")" ::: "memory")
; #define PG8_BAR __builtin_amdgcn_s_barrier()
; #define PG8_SCHED __builtin_amdgcn_sched_barrier(0)
; template <class Epi, class Sched, bool ALIGN_EPI = false, bool SP2 = false>
; __device__ __forceinline__ void gemm_phase(PG8_LAS unsigned char* lds, const Gemm g, const Sched& S, const Epi& E) {
;     ...
;             PG8_LDA(At, 1, 1); PG8_STAGE(PG8_SB(1, 0), b3, voffB); PG8_STAGE(PG8_SB(1, 1), b3 + hstepB, voffB); PG8_STAGE(PG8_SA(1, 0), a3, voffA);
;             PG8_WAIT_V(8); PG8_WAIT_L(0); PG8_BAR; PG8_MMA(1, 0, At, B0); PG8_MMA(1, 1, At, B1); PG8_BAR; PG8_SCHED;
	s_mov_b32 m0, s83
	v_lshl_add_u64 v[186:187], v[186:187], 0, s[18:19]
	s_add_u32 s40, s40, 0x2b0080
	ds_read_b128 v[162:165], v180 offset:49152
	ds_read_b128 v[166:169], v180 offset:50176
	ds_read_b128 v[182:185], v180 offset:51200
	ds_read_b128 v[190:193], v180 offset:52224
	ds_read_b128 v[194:197], v180 offset:53248
	ds_read_b128 v[208:211], v180 offset:54272
	ds_read_b128 v[212:215], v180 offset:55296
	ds_read_b128 v[216:219], v180 offset:56320
	global_load_lds_dwordx4 v[186:187], off
	v_lshl_add_u64 v[186:187], v[198:199], 0, s[18:19]
	s_mov_b32 m0, s84
	s_addc_u32 s41, s41, 0
	global_load_lds_dwordx4 v[186:187], off
	v_lshl_add_u64 v[186:187], s[40:41], 0, v[174:175]
	s_mov_b32 m0, s85
	s_nop 0
	global_load_lds_dwordx4 v[186:187], off
	v_lshl_add_u64 v[186:187], s[40:41], 0, v[178:179]
	s_mov_b32 m0, s86
	s_nop 0
	global_load_lds_dwordx4 v[186:187], off
	v_lshl_add_u64 v[186:187], v[204:205], 0, s[18:19]
	s_mov_b32 m0, s63
	s_nop 0
	global_load_lds_dwordx4 v[186:187], off
	v_lshl_add_u64 v[186:187], v[220:221], 0, s[18:19]
	s_mov_b32 m0, s64
	s_nop 0
	global_load_lds_dwordx4 v[186:187], off
	s_waitcnt vmcnt(8)
	s_waitcnt lgkmcnt(0)
	s_barrier
	s_setprio 3
	s_waitcnt lgkmcnt(0)
	v_mfma_f32_16x16x32_bf16 v[62:65], v[130:133], v[162:165], v[62:65]
	v_mfma_f32_16x16x32_bf16 v[58:61], v[138:141], v[162:165], v[58:61]
	v_mfma_f32_16x16x32_bf16 v[46:49], v[130:133], v[182:185], v[46:49]
	v_mfma_f32_16x16x32_bf16 v[42:45], v[138:141], v[182:185], v[42:45]
	v_mfma_f32_16x16x32_bf16 v[30:33], v[130:133], v[194:197], v[30:33]
	v_mfma_f32_16x16x32_bf16 v[26:29], v[138:141], v[194:197], v[26:29]
	v_mfma_f32_16x16x32_bf16 v[14:17], v[130:133], v[212:215], v[14:17]
	v_mfma_f32_16x16x32_bf16 v[10:13], v[138:141], v[212:215], v[10:13]
	v_mfma_f32_16x16x32_bf16 v[62:65], v[134:137], v[166:169], v[62:65]
	v_mfma_f32_16x16x32_bf16 v[58:61], v[142:145], v[166:169], v[58:61]
	v_mfma_f32_16x16x32_bf16 v[46:49], v[134:137], v[190:193], v[46:49]
	v_mfma_f32_16x16x32_bf16 v[42:45], v[142:145], v[190:193], v[42:45]
	v_mfma_f32_16x16x32_bf16 v[30:33], v[134:137], v[208:211], v[30:33]
	v_mfma_f32_16x16x32_bf16 v[26:29], v[142:145], v[208:211], v[26:29]
	v_mfma_f32_16x16x32_bf16 v[14:17], v[134:137], v[216:219], v[14:17]
	v_mfma_f32_16x16x32_bf16 v[10:13], v[142:145], v[216:219], v[10:13]
	s_setprio 0
	s_setprio 3
	v_mfma_f32_16x16x32_bf16 v[54:57], v[146:149], v[162:165], v[54:57]
	v_mfma_f32_16x16x32_bf16 v[50:53], v[154:157], v[162:165], v[50:53]
	v_mfma_f32_16x16x32_bf16 v[38:41], v[146:149], v[182:185], v[38:41]
	v_mfma_f32_16x16x32_bf16 v[34:37], v[154:157], v[182:185], v[34:37]
	v_mfma_f32_16x16x32_bf16 v[22:25], v[146:149], v[194:197], v[22:25]
	v_mfma_f32_16x16x32_bf16 v[18:21], v[154:157], v[194:197], v[18:21]
	v_mfma_f32_16x16x32_bf16 v[6:9], v[146:149], v[212:215], v[6:9]
	v_mfma_f32_16x16x32_bf16 v[2:5], v[154:157], v[212:215], v[2:5]
	v_mfma_f32_16x16x32_bf16 v[54:57], v[150:153], v[166:169], v[54:57]
	v_mfma_f32_16x16x32_bf16 v[50:53], v[158:161], v[166:169], v[50:53]
	v_mfma_f32_16x16x32_bf16 v[38:41], v[150:153], v[190:193], v[38:41]
	v_mfma_f32_16x16x32_bf16 v[34:37], v[158:161], v[190:193], v[34:37]
	v_mfma_f32_16x16x32_bf16 v[22:25], v[150:153], v[208:211], v[22:25]
	v_mfma_f32_16x16x32_bf16 v[18:21], v[158:161], v[208:211], v[18:21]
	v_mfma_f32_16x16x32_bf16 v[6:9], v[150:153], v[216:219], v[6:9]
	v_mfma_f32_16x16x32_bf16 v[2:5], v[158:161], v[216:219], v[2:5]
	s_setprio 0
	s_barrier
	s_add_i32 s67, s67, 2
	s_add_u32 s22, s22, 0x100
	s_addc_u32 s23, s23, 0
	s_cmpk_gt_u32 s67, 0xa9
	s_cbranch_scc1 .LBB0_1021
